# GEMM loops: s_setprio 1 issued before the phase barrier, load prep moved behind the barrier, in-proj pointer increments at the loop head
# baseline (speedup 1.0000x reference)
; #define PG8_STAGE(bufoff, gbase, voff) do { _Pragma("unroll") for (int _i = 0; _i < 2; ++_i) \
;         __builtin_amdgcn_global_load_lds((const unsigned*)((const char*)(gbase) + (voff)[_i]), (PG8_LAS unsigned*)(lds + (bufoff) + ldsw + _i * 8192), 16, 0, 0); } while (0)
; #define PG8_LDA(dst, b, h) do { _Pragma("unroll") for (int m = 0; m < 4; ++m) _Pragma("unroll") for (int k = 0; k < 2; ++k) dst[m][k] = *(const PG8_LAS bf16x8*)(lds + PG8_SA(b, h) + aoff + m * 2048 + k * 1024); } while (0)
; #define PG8_LDB(dst, b, h) do { _Pragma("unroll") for (int n = 0; n < 2; ++n) _Pragma("unroll") for (int k = 0; k < 2; ++k) dst[n][k] = *(const PG8_LAS bf16x8*)(lds + PG8_SB(b, h) + boff + n * 2048 + k * 1024); } while (0)
; #define PG8_MMA(ai, bj, At, Bt) do { __builtin_amdgcn_s_setprio(1); _Pragma("unroll") for (int m = 0; m < 4; ++m) _Pragma("unroll") for (int n = 0; n < 2; ++n) _Pragma("unroll") for (int k = 0; k < 2; ++k) \
;         acc[ai][bj][m][n] = __builtin_amdgcn_mfma_f32_16x16x32_bf16(Bt[n][k], At[m][k], acc[ai][bj][m][n], 0, 0, 0); __builtin_amdgcn_s_setprio(0); } while (0)
; #define PG8_WAIT_V(n) asm volatile("s_waitcnt vmcnt(" #n ")" ::: "memory")
; #define PG8_WAIT_L(n) asm volatile("s_waitcnt lgkmcnt(" #n ")" ::: "memory")
; #define PG8_BAR __builtin_amdgcn_s_barrier()
; #define PG8_SCHED __builtin_amdgcn_sched_barrier(0)
; template <class Epi, class Sched>
; __device__ __forceinline__ void gemm_phase(PG8_LAS unsigned char* lds, const Gemm g, const Sched& S, const Epi& E) {
;     ...
;             PG8_LDB(B0, 0, 0); PG8_SCHED; PG8_LDA(At, 0, 0); PG8_STAGE(PG8_SA(1, 1), a1 + hstep, voffA);
;             PG8_WAIT_L(8); PG8_BAR; PG8_WAIT_L(0); PG8_MMA(0, 0, At, B0); PG8_BAR; PG8_SCHED;
;             PG8_LDB(B1, 0, 1); PG8_STAGE(PG8_SB(0, 0), b2, voffB);
;             PG8_BAR; PG8_WAIT_L(0); PG8_MMA(0, 1, At, B1); PG8_BAR;
;             PG8_LDA(At, 0, 1); PG8_STAGE(PG8_SA(0, 0), a2, voffA);
;             PG8_BAR; PG8_WAIT_L(0); PG8_MMA(1, 0, At, B0); PG8_BAR; PG8_SCHED;
;             PG8_STAGE(PG8_SB(0, 1), b2 + hstep, voffB);
;             PG8_WAIT_V(6); PG8_BAR; PG8_MMA(1, 1, At, B1); PG8_BAR;
.LBB0_75:
	s_add_u32 s10, vcc_lo, 0xfffc0080
	s_addc_u32 s11, vcc_hi, -1
	s_add_i32 s89, 0, 0x10000
	v_add_u32_e32 v156, s89, v141
	ds_read_b128 v[144:147], v156
	ds_read_b128 v[148:151], v156 offset:1024
	ds_read_b128 v[152:155], v156 offset:2048
	ds_read_b128 v[156:159], v156 offset:3072
	s_cmp_eq_u32 s88, 12
	s_cselect_b32 s41, s39, s11
	s_cselect_b32 s40, s84, s10
	s_cselect_b32 s11, s37, s87
	s_cselect_b32 s10, s85, s86
	v_lshl_add_u64 v[202:203], vcc, 0, v[136:137]
	s_add_i32 m0, s21, 0xc000
	ds_read_b128 v[160:163], v143
	ds_read_b128 v[174:177], v143 offset:1024
	ds_read_b128 v[178:181], v143 offset:2048
	ds_read_b128 v[182:185], v143 offset:3072
	ds_read_b128 v[186:189], v143 offset:4096
	ds_read_b128 v[190:193], v143 offset:5120
	ds_read_b128 v[194:197], v143 offset:6144
	ds_read_b128 v[198:201], v143 offset:7168
	global_load_lds_dwordx4 v[202:203], off
	v_lshl_add_u64 v[202:203], vcc, 0, v[138:139]
	s_add_i32 m0, s21, 0xe000
	s_nop 0
	global_load_lds_dwordx4 v[202:203], off
	s_waitcnt lgkmcnt(8)
	s_setprio 1
	s_barrier
	s_waitcnt lgkmcnt(0)
	v_mfma_f32_16x16x32_bf16 v[126:129], v[144:147], v[160:163], v[126:129]
	v_mfma_f32_16x16x32_bf16 v[122:125], v[152:155], v[160:163], v[122:125]
	v_mfma_f32_16x16x32_bf16 v[118:121], v[144:147], v[178:181], v[118:121]
	v_mfma_f32_16x16x32_bf16 v[114:117], v[152:155], v[178:181], v[114:117]
	v_mfma_f32_16x16x32_bf16 v[102:105], v[144:147], v[186:189], v[102:105]
	v_mfma_f32_16x16x32_bf16 v[98:101], v[152:155], v[186:189], v[98:101]
	v_mfma_f32_16x16x32_bf16 v[86:89], v[144:147], v[194:197], v[86:89]
	v_mfma_f32_16x16x32_bf16 v[82:85], v[152:155], v[194:197], v[82:85]
	v_mfma_f32_16x16x32_bf16 v[126:129], v[148:151], v[174:177], v[126:129]
	v_mfma_f32_16x16x32_bf16 v[122:125], v[156:159], v[174:177], v[122:125]
	v_mfma_f32_16x16x32_bf16 v[118:121], v[148:151], v[182:185], v[118:121]
	v_mfma_f32_16x16x32_bf16 v[114:117], v[156:159], v[182:185], v[114:117]
	v_mfma_f32_16x16x32_bf16 v[102:105], v[148:151], v[190:193], v[102:105]
	v_mfma_f32_16x16x32_bf16 v[98:101], v[156:159], v[190:193], v[98:101]
	v_mfma_f32_16x16x32_bf16 v[86:89], v[148:151], v[198:201], v[86:89]
	v_mfma_f32_16x16x32_bf16 v[82:85], v[156:159], v[198:201], v[82:85]
	s_setprio 0
	s_barrier
	s_add_i32 s92, 0, 0x14000
	s_add_i32 s89, s89, s76
	v_add_u32_e32 v173, s92, v141
	v_lshl_add_u64 v[202:203], s[10:11], 0, v[0:1]
	s_mov_b32 m0, s89
	ds_read_b128 v[216:219], v173
	ds_read_b128 v[220:223], v173 offset:1024
	ds_read_b128 v[224:227], v173 offset:2048
	ds_read_b128 v[228:231], v173 offset:3072
	global_load_lds_dwordx4 v[202:203], off
	v_lshl_add_u64 v[232:233], s[10:11], 0, v[134:135]
	s_add_i32 m0, s89, 0x2000
	s_nop 0
	global_load_lds_dwordx4 v[232:233], off
	s_setprio 1
	s_barrier
	s_waitcnt lgkmcnt(0)
	v_mfma_f32_16x16x32_bf16 v[110:113], v[216:219], v[160:163], v[110:113]
	v_mfma_f32_16x16x32_bf16 v[106:109], v[224:227], v[160:163], v[106:109]
	v_mfma_f32_16x16x32_bf16 v[94:97], v[216:219], v[178:181], v[94:97]
	v_mfma_f32_16x16x32_bf16 v[90:93], v[224:227], v[178:181], v[90:93]
	v_mfma_f32_16x16x32_bf16 v[78:81], v[216:219], v[186:189], v[78:81]
	v_mfma_f32_16x16x32_bf16 v[74:77], v[224:227], v[186:189], v[74:77]
	v_mfma_f32_16x16x32_bf16 v[70:73], v[216:219], v[194:197], v[70:73]
	v_mfma_f32_16x16x32_bf16 v[66:69], v[224:227], v[194:197], v[66:69]
	v_mfma_f32_16x16x32_bf16 v[110:113], v[220:223], v[174:177], v[110:113]
	v_mfma_f32_16x16x32_bf16 v[106:109], v[228:231], v[174:177], v[106:109]
	v_mfma_f32_16x16x32_bf16 v[94:97], v[220:223], v[182:185], v[94:97]
	v_mfma_f32_16x16x32_bf16 v[90:93], v[228:231], v[182:185], v[90:93]
	v_mfma_f32_16x16x32_bf16 v[78:81], v[220:223], v[190:193], v[78:81]
	v_mfma_f32_16x16x32_bf16 v[74:77], v[228:231], v[190:193], v[74:77]
	v_mfma_f32_16x16x32_bf16 v[70:73], v[220:223], v[198:201], v[70:73]
	v_mfma_f32_16x16x32_bf16 v[66:69], v[228:231], v[198:201], v[66:69]
	s_setprio 0
	s_barrier
	s_mov_b32 m0, s21
	v_lshl_add_u64 v[234:235], s[40:41], 0, v[130:131]
	ds_read_b128 v[160:163], v143 offset:16384
	ds_read_b128 v[174:177], v143 offset:17408
	ds_read_b128 v[178:181], v143 offset:18432
	ds_read_b128 v[182:185], v143 offset:19456
	ds_read_b128 v[186:189], v143 offset:20480
	ds_read_b128 v[190:193], v143 offset:21504
	ds_read_b128 v[194:197], v143 offset:22528
	ds_read_b128 v[198:201], v143 offset:23552
	global_load_lds_dwordx4 v[234:235], off
	v_lshl_add_u64 v[236:237], s[40:41], 0, v[132:133]
	s_mov_b32 m0, s77
	s_nop 0
	global_load_lds_dwordx4 v[236:237], off
	s_setprio 1
	s_barrier
	s_waitcnt lgkmcnt(0)
	v_mfma_f32_16x16x32_bf16 v[62:65], v[144:147], v[160:163], v[62:65]
	v_mfma_f32_16x16x32_bf16 v[58:61], v[152:155], v[160:163], v[58:61]
	v_mfma_f32_16x16x32_bf16 v[54:57], v[144:147], v[178:181], v[54:57]
	v_mfma_f32_16x16x32_bf16 v[50:53], v[152:155], v[178:181], v[50:53]
	v_mfma_f32_16x16x32_bf16 v[38:41], v[144:147], v[186:189], v[38:41]
	v_mfma_f32_16x16x32_bf16 v[34:37], v[152:155], v[186:189], v[34:37]
	v_mfma_f32_16x16x32_bf16 v[22:25], v[144:147], v[194:197], v[22:25]
	v_mfma_f32_16x16x32_bf16 v[18:21], v[152:155], v[194:197], v[18:21]
	v_mfma_f32_16x16x32_bf16 v[62:65], v[148:151], v[174:177], v[62:65]
	v_mfma_f32_16x16x32_bf16 v[58:61], v[156:159], v[174:177], v[58:61]
	v_mfma_f32_16x16x32_bf16 v[54:57], v[148:151], v[182:185], v[54:57]
	v_mfma_f32_16x16x32_bf16 v[50:53], v[156:159], v[182:185], v[50:53]
	v_mfma_f32_16x16x32_bf16 v[38:41], v[148:151], v[190:193], v[38:41]
	v_mfma_f32_16x16x32_bf16 v[34:37], v[156:159], v[190:193], v[34:37]
	v_mfma_f32_16x16x32_bf16 v[22:25], v[148:151], v[198:201], v[22:25]
	v_mfma_f32_16x16x32_bf16 v[18:21], v[156:159], v[198:201], v[18:21]
	s_setprio 0
	s_barrier
; #define PG8_STAGE(bufoff, gbase, voff) do { _Pragma("unroll") for (int _i = 0; _i < 2; ++_i) \
;         __builtin_amdgcn_global_load_lds((const unsigned*)((const char*)(gbase) + (voff)[_i]), (PG8_LAS unsigned*)(lds + (bufoff) + ldsw + _i * 8192), 16, 0, 0); } while (0)
; #define PG8_LDA(dst, b, h) do { _Pragma("unroll") for (int m = 0; m < 4; ++m) _Pragma("unroll") for (int k = 0; k < 2; ++k) dst[m][k] = *(const PG8_LAS bf16x8*)(lds + PG8_SA(b, h) + aoff + m * 2048 + k * 1024); } while (0)
; #define PG8_LDB(dst, b, h) do { _Pragma("unroll") for (int n = 0; n < 2; ++n) _Pragma("unroll") for (int k = 0; k < 2; ++k) dst[n][k] = *(const PG8_LAS bf16x8*)(lds + PG8_SB(b, h) + boff + n * 2048 + k * 1024); } while (0)
; #define PG8_MMA(ai, bj, At, Bt) do { __builtin_amdgcn_s_setprio(1); _Pragma("unroll") for (int m = 0; m < 4; ++m) _Pragma("unroll") for (int n = 0; n < 2; ++n) _Pragma("unroll") for (int k = 0; k < 2; ++k) \
;         acc[ai][bj][m][n] = __builtin_amdgcn_mfma_f32_16x16x32_bf16(Bt[n][k], At[m][k], acc[ai][bj][m][n], 0, 0, 0); __builtin_amdgcn_s_setprio(0); } while (0)
; #define PG8_WAIT_V(n) asm volatile("s_waitcnt vmcnt(" #n ")" ::: "memory")
; #define PG8_WAIT_L(n) asm volatile("s_waitcnt lgkmcnt(" #n ")" ::: "memory")
; #define PG8_BAR __builtin_amdgcn_s_barrier()
; #define PG8_SCHED __builtin_amdgcn_sched_barrier(0)
; template <class Epi, class Sched>
; __device__ __forceinline__ void gemm_phase(PG8_LAS unsigned char* lds, const Gemm g, const Sched& S, const Epi& E) {
;     ...
;             PG8_STAGE(PG8_SB(0, 1), b2 + hstep, voffB);
;             PG8_WAIT_V(6); PG8_BAR; PG8_MMA(1, 1, At, B1); PG8_BAR;
;             PG8_LDB(B0, 1, 0); PG8_SCHED; PG8_LDA(At, 1, 0); PG8_STAGE(PG8_SA(0, 1), a2 + hstep, voffA);
;             PG8_WAIT_L(8); PG8_BAR; PG8_WAIT_L(0); PG8_MMA(0, 0, At, B0); PG8_BAR; PG8_SCHED;
;             PG8_LDB(B1, 1, 1); PG8_STAGE(PG8_SB(1, 0), b3, voffB);
;             PG8_BAR; PG8_WAIT_L(0); PG8_MMA(0, 1, At, B1); PG8_BAR;
;             PG8_LDA(At, 1, 1); PG8_STAGE(PG8_SA(1, 0), a3, voffA);
;             PG8_BAR; PG8_WAIT_L(0); PG8_MMA(1, 0, At, B0); PG8_BAR; PG8_SCHED;
	s_add_u32 s90, s10, 0x40000
	s_addc_u32 s91, s11, 0
	s_add_i32 s89, s92, s76
	v_lshl_add_u64 v[144:145], s[90:91], 0, v[0:1]
	s_mov_b32 m0, s89
	s_nop 0
	global_load_lds_dwordx4 v[144:145], off
	v_lshl_add_u64 v[144:145], s[90:91], 0, v[134:135]
	s_add_i32 m0, s89, 0x2000
	s_nop 0
	global_load_lds_dwordx4 v[144:145], off
	s_waitcnt vmcnt(6)
	s_setprio 1
	s_barrier
	v_mfma_f32_16x16x32_bf16 v[46:49], v[216:219], v[160:163], v[46:49]
	v_mfma_f32_16x16x32_bf16 v[42:45], v[224:227], v[160:163], v[42:45]
	v_mfma_f32_16x16x32_bf16 v[30:33], v[216:219], v[178:181], v[30:33]
	v_mfma_f32_16x16x32_bf16 v[26:29], v[224:227], v[178:181], v[26:29]
	v_mfma_f32_16x16x32_bf16 v[14:17], v[216:219], v[186:189], v[14:17]
	v_mfma_f32_16x16x32_bf16 v[10:13], v[224:227], v[186:189], v[10:13]
	v_mfma_f32_16x16x32_bf16 v[6:9], v[216:219], v[194:197], v[6:9]
	v_mfma_f32_16x16x32_bf16 v[2:5], v[224:227], v[194:197], v[2:5]
	v_mfma_f32_16x16x32_bf16 v[46:49], v[220:223], v[174:177], v[46:49]
	v_mfma_f32_16x16x32_bf16 v[42:45], v[228:231], v[174:177], v[42:45]
	v_mfma_f32_16x16x32_bf16 v[30:33], v[220:223], v[182:185], v[30:33]
	v_mfma_f32_16x16x32_bf16 v[26:29], v[228:231], v[182:185], v[26:29]
	v_mfma_f32_16x16x32_bf16 v[14:17], v[220:223], v[190:193], v[14:17]
	v_mfma_f32_16x16x32_bf16 v[10:13], v[228:231], v[190:193], v[10:13]
	v_mfma_f32_16x16x32_bf16 v[6:9], v[220:223], v[198:201], v[6:9]
	v_mfma_f32_16x16x32_bf16 v[2:5], v[228:231], v[198:201], v[2:5]
	s_setprio 0
	s_barrier
	s_add_i32 s89, 0, 0x18000
	v_add_u32_e32 v156, s89, v141
	ds_read_b128 v[144:147], v156
	ds_read_b128 v[148:151], v156 offset:1024
	ds_read_b128 v[152:155], v156 offset:2048
	ds_read_b128 v[156:159], v156 offset:3072
	s_add_u32 s40, s40, 0x40000
	s_addc_u32 s41, s41, 0
	s_mov_b32 m0, s78
	v_lshl_add_u64 v[216:217], s[40:41], 0, v[130:131]
	ds_read_b128 v[160:163], v143 offset:32768
	ds_read_b128 v[174:177], v143 offset:33792
	ds_read_b128 v[178:181], v143 offset:34816
	ds_read_b128 v[182:185], v143 offset:35840
	ds_read_b128 v[186:189], v143 offset:36864
	ds_read_b128 v[190:193], v143 offset:37888
	ds_read_b128 v[194:197], v143 offset:38912
	ds_read_b128 v[198:201], v143 offset:39936
	global_load_lds_dwordx4 v[216:217], off
	v_lshl_add_u64 v[216:217], s[40:41], 0, v[132:133]
	s_mov_b32 m0, s79
	s_nop 0
	global_load_lds_dwordx4 v[216:217], off
	s_waitcnt lgkmcnt(8)
	s_setprio 1
	s_barrier
	s_waitcnt lgkmcnt(0)
	v_mfma_f32_16x16x32_bf16 v[126:129], v[144:147], v[160:163], v[126:129]
	v_mfma_f32_16x16x32_bf16 v[122:125], v[152:155], v[160:163], v[122:125]
	v_mfma_f32_16x16x32_bf16 v[118:121], v[144:147], v[178:181], v[118:121]
	v_mfma_f32_16x16x32_bf16 v[114:117], v[152:155], v[178:181], v[114:117]
	v_mfma_f32_16x16x32_bf16 v[102:105], v[144:147], v[186:189], v[102:105]
	v_mfma_f32_16x16x32_bf16 v[98:101], v[152:155], v[186:189], v[98:101]
	v_mfma_f32_16x16x32_bf16 v[86:89], v[144:147], v[194:197], v[86:89]
	v_mfma_f32_16x16x32_bf16 v[82:85], v[152:155], v[194:197], v[82:85]
	v_mfma_f32_16x16x32_bf16 v[126:129], v[148:151], v[174:177], v[126:129]
	v_mfma_f32_16x16x32_bf16 v[122:125], v[156:159], v[174:177], v[122:125]
	v_mfma_f32_16x16x32_bf16 v[118:121], v[148:151], v[182:185], v[118:121]
	v_mfma_f32_16x16x32_bf16 v[114:117], v[156:159], v[182:185], v[114:117]
	v_mfma_f32_16x16x32_bf16 v[102:105], v[148:151], v[190:193], v[102:105]
	v_mfma_f32_16x16x32_bf16 v[98:101], v[156:159], v[190:193], v[98:101]
	v_mfma_f32_16x16x32_bf16 v[86:89], v[148:151], v[198:201], v[86:89]
	v_mfma_f32_16x16x32_bf16 v[82:85], v[156:159], v[198:201], v[82:85]
	s_setprio 0
	s_barrier
	s_add_i32 s40, 0, 0x1c000
	s_add_i32 s41, s89, s76
	v_add_u32_e32 v173, s40, v141
	v_lshl_add_u64 v[202:203], v[202:203], 0, s[8:9]
	s_mov_b32 m0, s41
	ds_read_b128 v[216:219], v173
	ds_read_b128 v[220:223], v173 offset:1024
	ds_read_b128 v[224:227], v173 offset:2048
	ds_read_b128 v[228:231], v173 offset:3072
	global_load_lds_dwordx4 v[202:203], off
	v_lshl_add_u64 v[202:203], v[232:233], 0, s[8:9]
	s_add_i32 m0, s41, 0x2000
	s_nop 0
	global_load_lds_dwordx4 v[202:203], off
	s_setprio 1
	s_barrier
	s_waitcnt lgkmcnt(0)
	v_mfma_f32_16x16x32_bf16 v[110:113], v[216:219], v[160:163], v[110:113]
	v_mfma_f32_16x16x32_bf16 v[106:109], v[224:227], v[160:163], v[106:109]
	v_mfma_f32_16x16x32_bf16 v[94:97], v[216:219], v[178:181], v[94:97]
	v_mfma_f32_16x16x32_bf16 v[90:93], v[224:227], v[178:181], v[90:93]
	v_mfma_f32_16x16x32_bf16 v[78:81], v[216:219], v[186:189], v[78:81]
	v_mfma_f32_16x16x32_bf16 v[74:77], v[224:227], v[186:189], v[74:77]
	v_mfma_f32_16x16x32_bf16 v[70:73], v[216:219], v[194:197], v[70:73]
	v_mfma_f32_16x16x32_bf16 v[66:69], v[224:227], v[194:197], v[66:69]
	v_mfma_f32_16x16x32_bf16 v[110:113], v[220:223], v[174:177], v[110:113]
	v_mfma_f32_16x16x32_bf16 v[106:109], v[228:231], v[174:177], v[106:109]
	v_mfma_f32_16x16x32_bf16 v[94:97], v[220:223], v[182:185], v[94:97]
	v_mfma_f32_16x16x32_bf16 v[90:93], v[228:231], v[182:185], v[90:93]
	v_mfma_f32_16x16x32_bf16 v[78:81], v[220:223], v[190:193], v[78:81]
	v_mfma_f32_16x16x32_bf16 v[74:77], v[228:231], v[190:193], v[74:77]
	v_mfma_f32_16x16x32_bf16 v[70:73], v[220:223], v[198:201], v[70:73]
	v_mfma_f32_16x16x32_bf16 v[66:69], v[228:231], v[198:201], v[66:69]
	s_setprio 0
	s_barrier
	s_mov_b32 m0, s80
	v_lshl_add_u64 v[202:203], v[234:235], 0, s[8:9]
	ds_read_b128 v[160:163], v143 offset:49152
	ds_read_b128 v[174:177], v143 offset:50176
	ds_read_b128 v[178:181], v143 offset:51200
	ds_read_b128 v[182:185], v143 offset:52224
	ds_read_b128 v[186:189], v143 offset:53248
	ds_read_b128 v[190:193], v143 offset:54272
	ds_read_b128 v[194:197], v143 offset:55296
	ds_read_b128 v[198:201], v143 offset:56320
	global_load_lds_dwordx4 v[202:203], off
	v_lshl_add_u64 v[202:203], v[236:237], 0, s[8:9]
	s_mov_b32 m0, s81
	s_nop 0
	global_load_lds_dwordx4 v[202:203], off
	s_setprio 1
	s_barrier
; #define PG8_STAGE(bufoff, gbase, voff) do { _Pragma("unroll") for (int _i = 0; _i < 2; ++_i) \
;         __builtin_amdgcn_global_load_lds((const unsigned*)((const char*)(gbase) + (voff)[_i]), (PG8_LAS unsigned*)(lds + (bufoff) + ldsw + _i * 8192), 16, 0, 0); } while (0)
; #define PG8_LDA(dst, b, h) do { _Pragma("unroll") for (int m = 0; m < 4; ++m) _Pragma("unroll") for (int k = 0; k < 2; ++k) dst[m][k] = *(const PG8_LAS bf16x8*)(lds + PG8_SA(b, h) + aoff + m * 2048 + k * 1024); } while (0)
; #define PG8_MMA(ai, bj, At, Bt) do { __builtin_amdgcn_s_setprio(1); _Pragma("unroll") for (int m = 0; m < 4; ++m) _Pragma("unroll") for (int n = 0; n < 2; ++n) _Pragma("unroll") for (int k = 0; k < 2; ++k) \
;         acc[ai][bj][m][n] = __builtin_amdgcn_mfma_f32_16x16x32_bf16(Bt[n][k], At[m][k], acc[ai][bj][m][n], 0, 0, 0); __builtin_amdgcn_s_setprio(0); } while (0)
; #define PG8_WAIT_V(n) asm volatile("s_waitcnt vmcnt(" #n ")" ::: "memory")
; #define PG8_WAIT_L(n) asm volatile("s_waitcnt lgkmcnt(" #n ")" ::: "memory")
; #define PG8_BAR __builtin_amdgcn_s_barrier()
; #define PG8_SCHED __builtin_amdgcn_sched_barrier(0)
; template <class Epi, class Sched>
; __device__ __forceinline__ void gemm_phase(PG8_LAS unsigned char* lds, const Gemm g, const Sched& S, const Epi& E) {
;     ...
;             PG8_BAR; PG8_WAIT_L(0); PG8_MMA(0, 1, At, B1); PG8_BAR;
;             PG8_LDA(At, 1, 1); PG8_STAGE(PG8_SA(1, 0), a3, voffA);
;             PG8_BAR; PG8_WAIT_L(0); PG8_MMA(1, 0, At, B0); PG8_BAR; PG8_SCHED;
;             PG8_STAGE(PG8_SB(1, 1), b3 + hstep, voffB);
;             PG8_WAIT_V(6); PG8_BAR; PG8_MMA(1, 1, At, B1); PG8_BAR;
	s_waitcnt lgkmcnt(0)
	v_mfma_f32_16x16x32_bf16 v[62:65], v[144:147], v[160:163], v[62:65]
	v_mfma_f32_16x16x32_bf16 v[58:61], v[152:155], v[160:163], v[58:61]
	v_mfma_f32_16x16x32_bf16 v[54:57], v[144:147], v[178:181], v[54:57]
	v_mfma_f32_16x16x32_bf16 v[50:53], v[152:155], v[178:181], v[50:53]
	v_mfma_f32_16x16x32_bf16 v[38:41], v[144:147], v[186:189], v[38:41]
	v_mfma_f32_16x16x32_bf16 v[34:37], v[152:155], v[186:189], v[34:37]
	v_mfma_f32_16x16x32_bf16 v[22:25], v[144:147], v[194:197], v[22:25]
	v_mfma_f32_16x16x32_bf16 v[18:21], v[152:155], v[194:197], v[18:21]
	v_mfma_f32_16x16x32_bf16 v[62:65], v[148:151], v[174:177], v[62:65]
	v_mfma_f32_16x16x32_bf16 v[58:61], v[156:159], v[174:177], v[58:61]
	v_mfma_f32_16x16x32_bf16 v[54:57], v[148:151], v[182:185], v[54:57]
	v_mfma_f32_16x16x32_bf16 v[50:53], v[156:159], v[182:185], v[50:53]
	v_mfma_f32_16x16x32_bf16 v[38:41], v[148:151], v[190:193], v[38:41]
	v_mfma_f32_16x16x32_bf16 v[34:37], v[156:159], v[190:193], v[34:37]
	v_mfma_f32_16x16x32_bf16 v[22:25], v[148:151], v[198:201], v[22:25]
	v_mfma_f32_16x16x32_bf16 v[18:21], v[156:159], v[198:201], v[18:21]
	s_setprio 0
	s_barrier
	s_add_u32 s10, s10, 0x40080
	s_addc_u32 s11, s11, 0
	s_add_i32 s40, s40, s76
	v_lshl_add_u64 v[144:145], s[10:11], 0, v[0:1]
	s_mov_b32 m0, s40
	s_nop 0
	global_load_lds_dwordx4 v[144:145], off
	v_lshl_add_u64 v[144:145], s[10:11], 0, v[134:135]
	s_add_i32 m0, s40, 0x2000
	s_nop 0
	global_load_lds_dwordx4 v[144:145], off
	s_waitcnt vmcnt(6)
	s_setprio 1
	s_barrier
	v_mfma_f32_16x16x32_bf16 v[46:49], v[216:219], v[160:163], v[46:49]
	v_mfma_f32_16x16x32_bf16 v[42:45], v[224:227], v[160:163], v[42:45]
	v_mfma_f32_16x16x32_bf16 v[30:33], v[216:219], v[178:181], v[30:33]
	v_mfma_f32_16x16x32_bf16 v[26:29], v[224:227], v[178:181], v[26:29]
	v_mfma_f32_16x16x32_bf16 v[14:17], v[216:219], v[186:189], v[14:17]
	v_mfma_f32_16x16x32_bf16 v[10:13], v[224:227], v[186:189], v[10:13]
	v_mfma_f32_16x16x32_bf16 v[6:9], v[216:219], v[194:197], v[6:9]
	v_mfma_f32_16x16x32_bf16 v[2:5], v[224:227], v[194:197], v[2:5]
	v_mfma_f32_16x16x32_bf16 v[46:49], v[220:223], v[174:177], v[46:49]
	v_mfma_f32_16x16x32_bf16 v[42:45], v[228:231], v[174:177], v[42:45]
	v_mfma_f32_16x16x32_bf16 v[30:33], v[220:223], v[182:185], v[30:33]
	v_mfma_f32_16x16x32_bf16 v[26:29], v[228:231], v[182:185], v[26:29]
	v_mfma_f32_16x16x32_bf16 v[14:17], v[220:223], v[190:193], v[14:17]
	v_mfma_f32_16x16x32_bf16 v[10:13], v[228:231], v[190:193], v[10:13]
	v_mfma_f32_16x16x32_bf16 v[6:9], v[220:223], v[198:201], v[6:9]
	v_mfma_f32_16x16x32_bf16 v[2:5], v[228:231], v[198:201], v[2:5]
	s_setprio 0
	s_add_i32 s88, s88, 2
	s_add_u32 vcc_lo, vcc_lo, 0x100
	s_addc_u32 vcc_hi, vcc_hi, 0
	s_add_u32 s86, s86, 0x100
	s_addc_u32 s87, s87, 0
	s_cmp_gt_u32 s88, 13
	s_barrier
	s_cbranch_scc0 .LBB0_75
; #define PG8_WAIT_V(n) asm volatile("s_waitcnt vmcnt(" #n ")" ::: "memory")
; #define PG8_BAR __builtin_amdgcn_s_barrier()
; __device__ __forceinline__ unsigned pk2(float lo, float hi) { v2f v = {lo, hi}; return __builtin_bit_cast(unsigned, __builtin_convertvector(v, v2bf)); }
; template <class Epi, class Sched>
; __device__ __forceinline__ void gemm_phase(PG8_LAS unsigned char* lds, const Gemm g, const Sched& S, const Epi& E) {
;     ...
;     PG8_WAIT_V(0);
;     if (wr == 0) PG8_BAR;
;     PG8_BAR;
;     __device__ __forceinline__ void operator()(const f32x4 (&acc)[2][2][4][2], const Unit& u, int wr, int wc, int fr, int fq) const {
;         const int row0 = u.pm * 256 + wr * 64 + fr; int col0 = u.pn * 256 + wc * 32 + 8 * fq; int ld = ldz; bf16* base = Z;
;         if (SEG) { int c0, w; seg_of(u.pn * 256, c0, w); base = Z + (size_t)T * c0; ld = w; col0 -= c0; }
; #pragma unroll
;         for (int ai = 0; ai < 2; ++ai)
; #pragma unroll
;             for (int m = 0; m < 4; ++m) { bf16* rowp = base + (size_t)(row0 + ai * 128 + m * 16) * ld + col0;
; #pragma unroll
;                 for (int bj = 0; bj < 2; ++bj) { const f32x4 v0 = acc[ai][bj][m][0], v1 = acc[ai][bj][m][1];
;                     v4u w; w.x = pk2(v0[0], v0[1]); w.y = pk2(v0[2], v0[3]); w.z = pk2(v1[0], v1[1]); w.w = pk2(v1[2], v1[3]);
;                     *(v4u*)(rowp + bj * 128) = w; } }
;     }
	v_lshl_add_u32 v144, s20, 8, v140
	v_lshl_or_b32 v146, s83, 8, v142
	v_ashrrev_i32_e32 v147, 31, v146
	v_ashrrev_i32_e32 v145, 31, v144
	v_lshl_add_u64 v[146:147], v[146:147], 1, s[6:7]
	v_lshlrev_b64 v[148:149], 11, v[144:145]
	v_lshl_add_u64 v[148:149], v[146:147], 0, v[148:149]
	s_mov_b64 s[10:11], 0x40000
	v_cvt_pk_bf16_f32 v70, v70, v71
	v_cvt_pk_bf16_f32 v71, v72, v73
	v_cvt_pk_bf16_f32 v72, v66, v67
	v_lshl_add_u64 v[66:67], v[148:149], 0, s[10:11]
	v_cvt_pk_bf16_f32 v62, v62, v63
	v_cvt_pk_bf16_f32 v63, v64, v65
	v_cvt_pk_bf16_f32 v64, v58, v59
	v_add_co_u32_e32 v58, vcc, s67, v148
	v_cvt_pk_bf16_f32 v46, v46, v47
	v_cvt_pk_bf16_f32 v47, v48, v49
	v_cvt_pk_bf16_f32 v48, v42, v43
	v_cvt_pk_bf16_f32 v49, v44, v45
	s_mov_b64 s[10:11], 0x48000
	v_addc_co_u32_e32 v59, vcc, 0, v149, vcc
	global_store_dwordx4 v[66:67], v[46:49], off offset:256
	v_cvt_pk_bf16_f32 v30, v30, v31
	v_cvt_pk_bf16_f32 v31, v32, v33
	v_lshl_add_u64 v[46:47], v[148:149], 0, s[10:11]
	s_mov_b32 s10, 0x48000
	v_add_co_u32_e32 v48, vcc, s10, v148
	v_cvt_pk_bf16_f32 v32, v26, v27
	v_cvt_pk_bf16_f32 v33, v28, v29
	s_mov_b64 s[10:11], 0x50000
	v_cvt_pk_bf16_f32 v110, v110, v111
	v_cvt_pk_bf16_f32 v111, v112, v113
	v_cvt_pk_bf16_f32 v112, v106, v107
	v_or_b32_e32 v106, 16, v144
	v_addc_co_u32_e32 v49, vcc, 0, v149, vcc
	global_store_dwordx4 v[46:47], v[30:33], off offset:256
	v_ashrrev_i32_e32 v107, 31, v106
	v_cvt_pk_bf16_f32 v94, v94, v95
	v_lshl_add_u64 v[30:31], v[148:149], 0, s[10:11]
	s_mov_b32 s10, 0x50000
	v_cvt_pk_bf16_f32 v95, v96, v97
	v_cvt_pk_bf16_f32 v96, v90, v91
	v_or_b32_e32 v90, 32, v144
	v_add_co_u32_e32 v32, vcc, s10, v148
	v_cvt_pk_bf16_f32 v14, v14, v15
	v_cvt_pk_bf16_f32 v15, v16, v17
	v_cvt_pk_bf16_f32 v16, v10, v11
	v_cvt_pk_bf16_f32 v17, v12, v13
	s_mov_b64 s[10:11], 0x58000
	v_cvt_pk_bf16_f32 v113, v108, v109
	v_lshlrev_b64 v[106:107], 11, v[106:107]
	v_ashrrev_i32_e32 v91, 31, v90
	v_cvt_pk_bf16_f32 v78, v78, v79
	v_cvt_pk_bf16_f32 v79, v80, v81
	v_cvt_pk_bf16_f32 v80, v74, v75
	v_or_b32_e32 v74, 48, v144
	v_addc_co_u32_e32 v33, vcc, 0, v149, vcc
	global_store_dwordx4 v[30:31], v[14:17], off offset:256
	global_store_dwordx4 v[148:149], v[110:113], off offset:256
	v_cvt_pk_bf16_f32 v97, v92, v93
	v_lshl_add_u64 v[14:15], v[148:149], 0, s[10:11]
	s_mov_b32 s10, 0x58000
	v_lshl_add_u64 v[110:111], v[146:147], 0, v[106:107]
	v_lshlrev_b64 v[90:91], 11, v[90:91]
	v_ashrrev_i32_e32 v75, 31, v74
	v_add_co_u32_e32 v16, vcc, s10, v148
	global_store_dwordx4 v[110:111], v[94:97], off offset:256
	v_cvt_pk_bf16_f32 v81, v76, v77
	v_lshlrev_b64 v[74:75], 11, v[74:75]
	v_lshl_add_u64 v[94:95], v[146:147], 0, v[90:91]
	v_addc_co_u32_e32 v17, vcc, 0, v149, vcc
	v_cvt_pk_bf16_f32 v126, v126, v127
	v_cvt_pk_bf16_f32 v127, v128, v129
	v_cvt_pk_bf16_f32 v128, v122, v123
	v_cvt_pk_bf16_f32 v129, v124, v125
	v_cvt_pk_bf16_f32 v106, v118, v119
	v_cvt_pk_bf16_f32 v107, v120, v121
	v_cvt_pk_bf16_f32 v108, v114, v115
	v_cvt_pk_bf16_f32 v109, v116, v117
	v_cvt_pk_bf16_f32 v90, v102, v103
	v_cvt_pk_bf16_f32 v91, v104, v105
	v_cvt_pk_bf16_f32 v92, v98, v99
	v_cvt_pk_bf16_f32 v93, v100, v101
	global_store_dwordx4 v[94:95], v[78:81], off offset:256
	v_cvt_pk_bf16_f32 v76, v82, v83
	v_cvt_pk_bf16_f32 v77, v84, v85
	v_lshl_add_u64 v[78:79], v[146:147], 0, v[74:75]
	v_cvt_pk_bf16_f32 v74, v86, v87
	v_cvt_pk_bf16_f32 v75, v88, v89
	v_cvt_pk_bf16_f32 v73, v68, v69
	v_cvt_pk_bf16_f32 v65, v60, v61
	v_cvt_pk_bf16_f32 v42, v54, v55
	v_cvt_pk_bf16_f32 v43, v56, v57
	v_cvt_pk_bf16_f32 v44, v50, v51
	v_cvt_pk_bf16_f32 v45, v52, v53
	v_cvt_pk_bf16_f32 v26, v38, v39
	v_cvt_pk_bf16_f32 v27, v40, v41
	v_cvt_pk_bf16_f32 v28, v34, v35
	v_cvt_pk_bf16_f32 v29, v36, v37
	v_cvt_pk_bf16_f32 v10, v22, v23
	v_cvt_pk_bf16_f32 v11, v24, v25
	v_cvt_pk_bf16_f32 v12, v18, v19
	v_cvt_pk_bf16_f32 v13, v20, v21
	v_cvt_pk_bf16_f32 v6, v6, v7
	v_cvt_pk_bf16_f32 v7, v8, v9
	v_cvt_pk_bf16_f32 v8, v2, v3
	v_cvt_pk_bf16_f32 v9, v4, v5
	s_and_b64 vcc, exec, s[18:19]
	s_mov_b32 s83, s36
	s_mov_b32 s20, s38
	s_mov_b64 s[10:11], s[50:51]
	s_mov_b64 s[40:41], s[52:53]
	global_store_dwordx4 v[148:149], v[126:129], off
	global_store_dwordx4 v[110:111], v[106:109], off
	global_store_dwordx4 v[94:95], v[90:93], off
	global_store_dwordx4 v[78:79], v[74:77], off
	global_store_dwordx4 v[78:79], v[70:73], off offset:256
	global_store_dwordx4 v[58:59], v[62:65], off
	global_store_dwordx4 v[48:49], v[42:45], off
	global_store_dwordx4 v[32:33], v[26:29], off
	global_store_dwordx4 v[16:17], v[10:13], off
	global_store_dwordx4 v[14:15], v[6:9], off offset:256
	s_cbranch_vccz .LBB0_68
	s_waitcnt vmcnt(0)
	s_cmpk_gt_u32 s70, 0xff
	s_cbranch_scc1 .LBB0_58
	s_barrier
	s_branch .LBB0_58

; #define PG8_STAGE(bufoff, gbase, voff) do { _Pragma("unroll") for (int _i = 0; _i < 2; ++_i) \
;         __builtin_amdgcn_global_load_lds((const unsigned*)((const char*)(gbase) + (voff)[_i]), (PG8_LAS unsigned*)(lds + (bufoff) + ldsw + _i * 8192), 16, 0, 0); } while (0)
; #define PG8_LDA(dst, b, h) do { _Pragma("unroll") for (int m = 0; m < 4; ++m) _Pragma("unroll") for (int k = 0; k < 2; ++k) dst[m][k] = *(const PG8_LAS bf16x8*)(lds + PG8_SA(b, h) + aoff + m * 2048 + k * 1024); } while (0)
; #define PG8_LDB(dst, b, h) do { _Pragma("unroll") for (int n = 0; n < 2; ++n) _Pragma("unroll") for (int k = 0; k < 2; ++k) dst[n][k] = *(const PG8_LAS bf16x8*)(lds + PG8_SB(b, h) + boff + n * 2048 + k * 1024); } while (0)
; #define PG8_WAIT_L(n) asm volatile("s_waitcnt lgkmcnt(" #n ")" ::: "memory")
; #define PG8_BAR __builtin_amdgcn_s_barrier()
; #define PG8_SCHED __builtin_amdgcn_sched_barrier(0)
;     __device__ __forceinline__ bool next(int i, Unit& u) const { if (!S.next(i >> 2, u)) return false; u.seg = i & 3; return true; }
; template <class Epi, class Sched>
; __device__ __forceinline__ void gemm_phase(PG8_LAS unsigned char* lds, const Gemm g, const Sched& S, const Epi& E) {
;     ...
;         const bool has_next = S.next(ui + 1, nxt);
;         const char* nA = has_next ? (const char*)g.A + (size_t)nxt.pm * tstep + (size_t)nxt.seg * SEGB : cA; const char* nB = has_next ? (const char*)g.Bt + (size_t)nxt.pn * tstep + (size_t)nxt.seg * SEGB : cB;
;         for (int t = 0; t < nt; t += 2) {
;             const bool last = (t == nt - 2);
;             const char* a1 = cA + (size_t)(t + 1) * kstep;
;             const char* a2 = last ? nA : cA + (size_t)(t + 2) * kstep; const char* b2 = last ? nB : cB + (size_t)(t + 2) * kstep;
;             const char* a3 = a2 + kstep; const char* b3 = b2 + kstep;
;             if (last && has_next) S.a_ready(nxt);
;             PG8_LDB(B0, 0, 0); PG8_SCHED; PG8_LDA(At, 0, 0); PG8_STAGE(PG8_SA(1, 1), a1 + hstep, voffA);
;             PG8_WAIT_L(8); PG8_BAR; PG8_WAIT_L(0); PG8_MMA(0, 0, At, B0); PG8_BAR; PG8_SCHED;
;             PG8_LDB(B1, 0, 1); PG8_STAGE(PG8_SB(0, 0), b2, voffB);
;             PG8_BAR; PG8_WAIT_L(0); PG8_MMA(0, 1, At, B1); PG8_BAR;
;             PG8_LDA(At, 0, 1); PG8_STAGE(PG8_SA(0, 0), a2, voffA);
;             PG8_BAR; PG8_WAIT_L(0); PG8_MMA(1, 0, At, B0); PG8_BAR; PG8_SCHED;
.LBB0_87:
	s_ashr_i32 s19, s18, 31
	v_cmp_lt_i64_e32 vcc, s[20:21], v[166:167]
	s_lshl_b64 s[20:21], s[18:19], 19
	s_add_u32 s20, s56, s20
	s_addc_u32 s21, s57, s21
	s_and_b64 s[38:39], vcc, exec
	s_cselect_b32 s19, s21, s41
	s_cselect_b32 s79, s20, s40
	s_ashr_i32 s7, s6, 31
	s_lshl_b64 s[38:39], s[6:7], 19
	s_add_u32 s38, s52, s38
	s_addc_u32 s39, s53, s39
	s_and_b64 s[50:51], vcc, exec
	s_cselect_b32 s7, s39, s11
	s_cselect_b32 s80, s38, s10
	s_add_u32 s40, s40, 0x40080
	s_addc_u32 s41, s41, 0
	s_add_u32 s81, s10, 0x100
	s_addc_u32 s82, s11, 0
	s_mov_b32 s83, -2
	s_add_u32 s10, s40, 0xfffc0080
	s_addc_u32 s11, s41, -1
	s_add_i32 s84, 0, 0x10000
	v_add_u32_e32 v156, s84, v141
	ds_read_b128 v[144:147], v156
	ds_read_b128 v[148:151], v156 offset:1024
	ds_read_b128 v[152:155], v156 offset:2048
	ds_read_b128 v[156:159], v156 offset:3072
	s_cmp_eq_u32 s83, 12
	s_cselect_b32 s51, s19, s11
	s_cselect_b32 s50, s79, s10
	s_cselect_b32 s11, s7, s82
	s_cselect_b32 s10, s80, s81
	v_lshl_add_u64 v[202:203], s[40:41], 0, v[136:137]
	s_add_i32 m0, s71, 0xc000
	ds_read_b128 v[160:163], v143
	ds_read_b128 v[174:177], v143 offset:1024
	ds_read_b128 v[178:181], v143 offset:2048
	ds_read_b128 v[182:185], v143 offset:3072
	ds_read_b128 v[186:189], v143 offset:4096
	ds_read_b128 v[190:193], v143 offset:5120
	ds_read_b128 v[194:197], v143 offset:6144
	ds_read_b128 v[198:201], v143 offset:7168
	global_load_lds_dwordx4 v[202:203], off
	v_lshl_add_u64 v[202:203], s[40:41], 0, v[138:139]
	s_add_i32 m0, s71, 0xe000
	s_nop 0
	global_load_lds_dwordx4 v[202:203], off
	s_waitcnt lgkmcnt(8)
	s_setprio 1
	s_barrier
	s_waitcnt lgkmcnt(0)
	v_mfma_f32_16x16x32_bf16 v[126:129], v[144:147], v[160:163], 0
	v_mfma_f32_16x16x32_bf16 v[122:125], v[152:155], v[160:163], 0
	v_mfma_f32_16x16x32_bf16 v[118:121], v[144:147], v[178:181], 0
	v_mfma_f32_16x16x32_bf16 v[114:117], v[152:155], v[178:181], 0
	v_mfma_f32_16x16x32_bf16 v[102:105], v[144:147], v[186:189], 0
	v_mfma_f32_16x16x32_bf16 v[98:101], v[152:155], v[186:189], 0
	v_mfma_f32_16x16x32_bf16 v[86:89], v[144:147], v[194:197], 0
	v_mfma_f32_16x16x32_bf16 v[82:85], v[152:155], v[194:197], 0
	v_mfma_f32_16x16x32_bf16 v[126:129], v[148:151], v[174:177], v[126:129]
	v_mfma_f32_16x16x32_bf16 v[122:125], v[156:159], v[174:177], v[122:125]
	v_mfma_f32_16x16x32_bf16 v[118:121], v[148:151], v[182:185], v[118:121]
	v_mfma_f32_16x16x32_bf16 v[114:117], v[156:159], v[182:185], v[114:117]
	v_mfma_f32_16x16x32_bf16 v[102:105], v[148:151], v[190:193], v[102:105]
	v_mfma_f32_16x16x32_bf16 v[98:101], v[156:159], v[190:193], v[98:101]
	v_mfma_f32_16x16x32_bf16 v[86:89], v[148:151], v[198:201], v[86:89]
	v_mfma_f32_16x16x32_bf16 v[82:85], v[156:159], v[198:201], v[82:85]
	s_setprio 0
	s_barrier
	s_add_i32 s86, 0, 0x14000
	s_add_i32 s84, s84, s70
	v_add_u32_e32 v173, s86, v141
	v_lshl_add_u64 v[202:203], s[10:11], 0, v[0:1]
	s_mov_b32 m0, s84
	ds_read_b128 v[216:219], v173
	ds_read_b128 v[220:223], v173 offset:1024
	ds_read_b128 v[224:227], v173 offset:2048
	ds_read_b128 v[228:231], v173 offset:3072
	global_load_lds_dwordx4 v[202:203], off
	v_lshl_add_u64 v[232:233], s[10:11], 0, v[130:131]
	s_add_i32 m0, s84, 0x2000
	s_nop 0
	global_load_lds_dwordx4 v[232:233], off
	s_setprio 1
	s_barrier
	s_waitcnt lgkmcnt(0)
	v_mfma_f32_16x16x32_bf16 v[110:113], v[216:219], v[160:163], 0
	v_mfma_f32_16x16x32_bf16 v[106:109], v[224:227], v[160:163], 0
	v_mfma_f32_16x16x32_bf16 v[94:97], v[216:219], v[178:181], 0
	v_mfma_f32_16x16x32_bf16 v[90:93], v[224:227], v[178:181], 0
	v_mfma_f32_16x16x32_bf16 v[78:81], v[216:219], v[186:189], 0
	v_mfma_f32_16x16x32_bf16 v[74:77], v[224:227], v[186:189], 0
	v_mfma_f32_16x16x32_bf16 v[70:73], v[216:219], v[194:197], 0
	v_mfma_f32_16x16x32_bf16 v[66:69], v[224:227], v[194:197], 0
	v_mfma_f32_16x16x32_bf16 v[110:113], v[220:223], v[174:177], v[110:113]
	v_mfma_f32_16x16x32_bf16 v[106:109], v[228:231], v[174:177], v[106:109]
	v_mfma_f32_16x16x32_bf16 v[94:97], v[220:223], v[182:185], v[94:97]
	v_mfma_f32_16x16x32_bf16 v[90:93], v[228:231], v[182:185], v[90:93]
	v_mfma_f32_16x16x32_bf16 v[78:81], v[220:223], v[190:193], v[78:81]
	v_mfma_f32_16x16x32_bf16 v[74:77], v[228:231], v[190:193], v[74:77]
	v_mfma_f32_16x16x32_bf16 v[70:73], v[220:223], v[198:201], v[70:73]
	v_mfma_f32_16x16x32_bf16 v[66:69], v[228:231], v[198:201], v[66:69]
	s_setprio 0
	s_barrier
	s_mov_b32 m0, s71
	v_lshl_add_u64 v[234:235], s[50:51], 0, v[134:135]
	ds_read_b128 v[160:163], v143 offset:16384
	ds_read_b128 v[174:177], v143 offset:17408
	ds_read_b128 v[178:181], v143 offset:18432
	ds_read_b128 v[182:185], v143 offset:19456
	ds_read_b128 v[186:189], v143 offset:20480
	ds_read_b128 v[190:193], v143 offset:21504
	ds_read_b128 v[194:197], v143 offset:22528
	ds_read_b128 v[198:201], v143 offset:23552
	global_load_lds_dwordx4 v[234:235], off
	v_lshl_add_u64 v[236:237], s[50:51], 0, v[132:133]
	s_mov_b32 m0, s72
	s_nop 0
	global_load_lds_dwordx4 v[236:237], off
	s_setprio 1
	s_barrier
	s_waitcnt lgkmcnt(0)
	v_mfma_f32_16x16x32_bf16 v[62:65], v[144:147], v[160:163], 0
	v_mfma_f32_16x16x32_bf16 v[58:61], v[152:155], v[160:163], 0
	v_mfma_f32_16x16x32_bf16 v[54:57], v[144:147], v[178:181], 0
	v_mfma_f32_16x16x32_bf16 v[50:53], v[152:155], v[178:181], 0
	v_mfma_f32_16x16x32_bf16 v[38:41], v[144:147], v[186:189], 0
	v_mfma_f32_16x16x32_bf16 v[34:37], v[152:155], v[186:189], 0
	v_mfma_f32_16x16x32_bf16 v[22:25], v[144:147], v[194:197], 0
	v_mfma_f32_16x16x32_bf16 v[18:21], v[152:155], v[194:197], 0
	v_mfma_f32_16x16x32_bf16 v[62:65], v[148:151], v[174:177], v[62:65]
	v_mfma_f32_16x16x32_bf16 v[58:61], v[156:159], v[174:177], v[58:61]
	v_mfma_f32_16x16x32_bf16 v[54:57], v[148:151], v[182:185], v[54:57]
	v_mfma_f32_16x16x32_bf16 v[50:53], v[156:159], v[182:185], v[50:53]
	v_mfma_f32_16x16x32_bf16 v[38:41], v[148:151], v[190:193], v[38:41]
	v_mfma_f32_16x16x32_bf16 v[34:37], v[156:159], v[190:193], v[34:37]
	v_mfma_f32_16x16x32_bf16 v[22:25], v[148:151], v[198:201], v[22:25]
	v_mfma_f32_16x16x32_bf16 v[18:21], v[156:159], v[198:201], v[18:21]
	s_setprio 0
	s_barrier
; #define PG8_STAGE(bufoff, gbase, voff) do { _Pragma("unroll") for (int _i = 0; _i < 2; ++_i) \
;         __builtin_amdgcn_global_load_lds((const unsigned*)((const char*)(gbase) + (voff)[_i]), (PG8_LAS unsigned*)(lds + (bufoff) + ldsw + _i * 8192), 16, 0, 0); } while (0)
; #define PG8_LDA(dst, b, h) do { _Pragma("unroll") for (int m = 0; m < 4; ++m) _Pragma("unroll") for (int k = 0; k < 2; ++k) dst[m][k] = *(const PG8_LAS bf16x8*)(lds + PG8_SA(b, h) + aoff + m * 2048 + k * 1024); } while (0)
; #define PG8_LDB(dst, b, h) do { _Pragma("unroll") for (int n = 0; n < 2; ++n) _Pragma("unroll") for (int k = 0; k < 2; ++k) dst[n][k] = *(const PG8_LAS bf16x8*)(lds + PG8_SB(b, h) + boff + n * 2048 + k * 1024); } while (0)
; #define PG8_MMA(ai, bj, At, Bt) do { __builtin_amdgcn_s_setprio(1); _Pragma("unroll") for (int m = 0; m < 4; ++m) _Pragma("unroll") for (int n = 0; n < 2; ++n) _Pragma("unroll") for (int k = 0; k < 2; ++k) \
;         acc[ai][bj][m][n] = __builtin_amdgcn_mfma_f32_16x16x32_bf16(Bt[n][k], At[m][k], acc[ai][bj][m][n], 0, 0, 0); __builtin_amdgcn_s_setprio(0); } while (0)
; #define PG8_WAIT_V(n) asm volatile("s_waitcnt vmcnt(" #n ")" ::: "memory")
; #define PG8_WAIT_L(n) asm volatile("s_waitcnt lgkmcnt(" #n ")" ::: "memory")
; #define PG8_BAR __builtin_amdgcn_s_barrier()
; #define PG8_SCHED __builtin_amdgcn_sched_barrier(0)
; template <class Epi, class Sched>
; __device__ __forceinline__ void gemm_phase(PG8_LAS unsigned char* lds, const Gemm g, const Sched& S, const Epi& E) {
;     ...
;             PG8_STAGE(PG8_SB(0, 1), b2 + hstep, voffB);
;             PG8_WAIT_V(6); PG8_BAR; PG8_MMA(1, 1, At, B1); PG8_BAR;
;             PG8_LDB(B0, 1, 0); PG8_SCHED; PG8_LDA(At, 1, 0); PG8_STAGE(PG8_SA(0, 1), a2 + hstep, voffA);
;             PG8_WAIT_L(8); PG8_BAR; PG8_WAIT_L(0); PG8_MMA(0, 0, At, B0); PG8_BAR; PG8_SCHED;
;             PG8_LDB(B1, 1, 1); PG8_STAGE(PG8_SB(1, 0), b3, voffB);
;             PG8_BAR; PG8_WAIT_L(0); PG8_MMA(0, 1, At, B1); PG8_BAR;
;             PG8_LDA(At, 1, 1); PG8_STAGE(PG8_SA(1, 0), a3, voffA);
;             PG8_BAR; PG8_WAIT_L(0); PG8_MMA(1, 0, At, B0); PG8_BAR; PG8_SCHED;
	s_add_u32 s84, s10, 0x40000
	s_addc_u32 s85, s11, 0
	s_add_i32 s86, s86, s70
	v_lshl_add_u64 v[144:145], s[84:85], 0, v[0:1]
	s_mov_b32 m0, s86
	s_nop 0
	global_load_lds_dwordx4 v[144:145], off
	v_lshl_add_u64 v[144:145], s[84:85], 0, v[130:131]
	s_add_i32 m0, s86, 0x2000
	s_nop 0
	global_load_lds_dwordx4 v[144:145], off
	s_waitcnt vmcnt(6)
	s_setprio 1
	s_barrier
	v_mfma_f32_16x16x32_bf16 v[46:49], v[216:219], v[160:163], 0
	v_mfma_f32_16x16x32_bf16 v[42:45], v[224:227], v[160:163], 0
	v_mfma_f32_16x16x32_bf16 v[30:33], v[216:219], v[178:181], 0
	v_mfma_f32_16x16x32_bf16 v[26:29], v[224:227], v[178:181], 0
	v_mfma_f32_16x16x32_bf16 v[14:17], v[216:219], v[186:189], 0
	v_mfma_f32_16x16x32_bf16 v[10:13], v[224:227], v[186:189], 0
	v_mfma_f32_16x16x32_bf16 v[6:9], v[216:219], v[194:197], 0
	v_mfma_f32_16x16x32_bf16 v[2:5], v[224:227], v[194:197], 0
	v_mfma_f32_16x16x32_bf16 v[46:49], v[220:223], v[174:177], v[46:49]
	v_mfma_f32_16x16x32_bf16 v[42:45], v[228:231], v[174:177], v[42:45]
	v_mfma_f32_16x16x32_bf16 v[30:33], v[220:223], v[182:185], v[30:33]
	v_mfma_f32_16x16x32_bf16 v[26:29], v[228:231], v[182:185], v[26:29]
	v_mfma_f32_16x16x32_bf16 v[14:17], v[220:223], v[190:193], v[14:17]
	v_mfma_f32_16x16x32_bf16 v[10:13], v[228:231], v[190:193], v[10:13]
	v_mfma_f32_16x16x32_bf16 v[6:9], v[220:223], v[198:201], v[6:9]
	v_mfma_f32_16x16x32_bf16 v[2:5], v[228:231], v[198:201], v[2:5]
	s_setprio 0
	s_barrier
	s_add_i32 s84, 0, 0x18000
	v_add_u32_e32 v156, s84, v141
	ds_read_b128 v[144:147], v156
	ds_read_b128 v[148:151], v156 offset:1024
	ds_read_b128 v[152:155], v156 offset:2048
	ds_read_b128 v[156:159], v156 offset:3072
	s_add_u32 s50, s50, 0x40000
	s_addc_u32 s51, s51, 0
	s_mov_b32 m0, s73
	v_lshl_add_u64 v[216:217], s[50:51], 0, v[134:135]
	ds_read_b128 v[160:163], v143 offset:32768
	ds_read_b128 v[174:177], v143 offset:33792
	ds_read_b128 v[178:181], v143 offset:34816
	ds_read_b128 v[182:185], v143 offset:35840
	ds_read_b128 v[186:189], v143 offset:36864
	ds_read_b128 v[190:193], v143 offset:37888
	ds_read_b128 v[194:197], v143 offset:38912
	ds_read_b128 v[198:201], v143 offset:39936
	global_load_lds_dwordx4 v[216:217], off
	v_lshl_add_u64 v[216:217], s[50:51], 0, v[132:133]
	s_mov_b32 m0, s74
	s_nop 0
	global_load_lds_dwordx4 v[216:217], off
	s_waitcnt lgkmcnt(8)
	s_setprio 1
	s_barrier
	s_waitcnt lgkmcnt(0)
	v_mfma_f32_16x16x32_bf16 v[126:129], v[144:147], v[160:163], v[126:129]
	v_mfma_f32_16x16x32_bf16 v[122:125], v[152:155], v[160:163], v[122:125]
	v_mfma_f32_16x16x32_bf16 v[118:121], v[144:147], v[178:181], v[118:121]
	v_mfma_f32_16x16x32_bf16 v[114:117], v[152:155], v[178:181], v[114:117]
	v_mfma_f32_16x16x32_bf16 v[102:105], v[144:147], v[186:189], v[102:105]
	v_mfma_f32_16x16x32_bf16 v[98:101], v[152:155], v[186:189], v[98:101]
	v_mfma_f32_16x16x32_bf16 v[86:89], v[144:147], v[194:197], v[86:89]
	v_mfma_f32_16x16x32_bf16 v[82:85], v[152:155], v[194:197], v[82:85]
	v_mfma_f32_16x16x32_bf16 v[126:129], v[148:151], v[174:177], v[126:129]
	v_mfma_f32_16x16x32_bf16 v[122:125], v[156:159], v[174:177], v[122:125]
	v_mfma_f32_16x16x32_bf16 v[118:121], v[148:151], v[182:185], v[118:121]
	v_mfma_f32_16x16x32_bf16 v[114:117], v[156:159], v[182:185], v[114:117]
	v_mfma_f32_16x16x32_bf16 v[102:105], v[148:151], v[190:193], v[102:105]
	v_mfma_f32_16x16x32_bf16 v[98:101], v[156:159], v[190:193], v[98:101]
	v_mfma_f32_16x16x32_bf16 v[86:89], v[148:151], v[198:201], v[86:89]
	v_mfma_f32_16x16x32_bf16 v[82:85], v[156:159], v[198:201], v[82:85]
	s_setprio 0
	s_barrier
	s_add_i32 s50, 0, 0x1c000
	s_add_i32 s51, s84, s70
	v_add_u32_e32 v173, s50, v141
	v_lshl_add_u64 v[202:203], v[202:203], 0, s[8:9]
	s_mov_b32 m0, s51
	ds_read_b128 v[216:219], v173
	ds_read_b128 v[220:223], v173 offset:1024
	ds_read_b128 v[224:227], v173 offset:2048
	ds_read_b128 v[228:231], v173 offset:3072
	global_load_lds_dwordx4 v[202:203], off
	v_lshl_add_u64 v[202:203], v[232:233], 0, s[8:9]
	s_add_i32 m0, s51, 0x2000
	s_nop 0
	global_load_lds_dwordx4 v[202:203], off
	s_setprio 1
	s_barrier
	s_waitcnt lgkmcnt(0)
	v_mfma_f32_16x16x32_bf16 v[110:113], v[216:219], v[160:163], v[110:113]
	v_mfma_f32_16x16x32_bf16 v[106:109], v[224:227], v[160:163], v[106:109]
	v_mfma_f32_16x16x32_bf16 v[94:97], v[216:219], v[178:181], v[94:97]
	v_mfma_f32_16x16x32_bf16 v[90:93], v[224:227], v[178:181], v[90:93]
	v_mfma_f32_16x16x32_bf16 v[78:81], v[216:219], v[186:189], v[78:81]
	v_mfma_f32_16x16x32_bf16 v[74:77], v[224:227], v[186:189], v[74:77]
	v_mfma_f32_16x16x32_bf16 v[70:73], v[216:219], v[194:197], v[70:73]
	v_mfma_f32_16x16x32_bf16 v[66:69], v[224:227], v[194:197], v[66:69]
	v_mfma_f32_16x16x32_bf16 v[110:113], v[220:223], v[174:177], v[110:113]
	v_mfma_f32_16x16x32_bf16 v[106:109], v[228:231], v[174:177], v[106:109]
	v_mfma_f32_16x16x32_bf16 v[94:97], v[220:223], v[182:185], v[94:97]
	v_mfma_f32_16x16x32_bf16 v[90:93], v[228:231], v[182:185], v[90:93]
	v_mfma_f32_16x16x32_bf16 v[78:81], v[220:223], v[190:193], v[78:81]
	v_mfma_f32_16x16x32_bf16 v[74:77], v[228:231], v[190:193], v[74:77]
	v_mfma_f32_16x16x32_bf16 v[70:73], v[220:223], v[198:201], v[70:73]
	v_mfma_f32_16x16x32_bf16 v[66:69], v[228:231], v[198:201], v[66:69]
	s_setprio 0
	s_barrier
	s_mov_b32 m0, s75
	v_lshl_add_u64 v[202:203], v[234:235], 0, s[8:9]
	ds_read_b128 v[160:163], v143 offset:49152
	ds_read_b128 v[174:177], v143 offset:50176
	ds_read_b128 v[178:181], v143 offset:51200
	ds_read_b128 v[182:185], v143 offset:52224
	ds_read_b128 v[186:189], v143 offset:53248
	ds_read_b128 v[190:193], v143 offset:54272
	ds_read_b128 v[194:197], v143 offset:55296
	ds_read_b128 v[198:201], v143 offset:56320
	global_load_lds_dwordx4 v[202:203], off
	v_lshl_add_u64 v[202:203], v[236:237], 0, s[8:9]
	s_mov_b32 m0, s76
	s_nop 0
	global_load_lds_dwordx4 v[202:203], off
	s_setprio 1
	s_barrier
; #define PG8_STAGE(bufoff, gbase, voff) do { _Pragma("unroll") for (int _i = 0; _i < 2; ++_i) \
;         __builtin_amdgcn_global_load_lds((const unsigned*)((const char*)(gbase) + (voff)[_i]), (PG8_LAS unsigned*)(lds + (bufoff) + ldsw + _i * 8192), 16, 0, 0); } while (0)
; #define PG8_LDA(dst, b, h) do { _Pragma("unroll") for (int m = 0; m < 4; ++m) _Pragma("unroll") for (int k = 0; k < 2; ++k) dst[m][k] = *(const PG8_LAS bf16x8*)(lds + PG8_SA(b, h) + aoff + m * 2048 + k * 1024); } while (0)
; #define PG8_LDB(dst, b, h) do { _Pragma("unroll") for (int n = 0; n < 2; ++n) _Pragma("unroll") for (int k = 0; k < 2; ++k) dst[n][k] = *(const PG8_LAS bf16x8*)(lds + PG8_SB(b, h) + boff + n * 2048 + k * 1024); } while (0)
; #define PG8_MMA(ai, bj, At, Bt) do { __builtin_amdgcn_s_setprio(1); _Pragma("unroll") for (int m = 0; m < 4; ++m) _Pragma("unroll") for (int n = 0; n < 2; ++n) _Pragma("unroll") for (int k = 0; k < 2; ++k) \
;         acc[ai][bj][m][n] = __builtin_amdgcn_mfma_f32_16x16x32_bf16(Bt[n][k], At[m][k], acc[ai][bj][m][n], 0, 0, 0); __builtin_amdgcn_s_setprio(0); } while (0)
; #define PG8_WAIT_V(n) asm volatile("s_waitcnt vmcnt(" #n ")" ::: "memory")
; template <class Epi, class Sched>
; __device__ __forceinline__ void gemm_phase(PG8_LAS unsigned char* lds, const Gemm g, const Sched& S, const Epi& E) {
;     ...
;         for (int t = 0; t < nt; t += 2) {
;             const bool last = (t == nt - 2);
;             const char* a1 = cA + (size_t)(t + 1) * kstep;
;             const char* a2 = last ? nA : cA + (size_t)(t + 2) * kstep; const char* b2 = last ? nB : cB + (size_t)(t + 2) * kstep;
;             const char* a3 = a2 + kstep; const char* b3 = b2 + kstep;
;             if (last && has_next) S.a_ready(nxt);
;             PG8_LDB(B0, 0, 0); PG8_SCHED; PG8_LDA(At, 0, 0); PG8_STAGE(PG8_SA(1, 1), a1 + hstep, voffA);
;             PG8_WAIT_L(8); PG8_BAR; PG8_WAIT_L(0); PG8_MMA(0, 0, At, B0); PG8_BAR; PG8_SCHED;
;             PG8_LDB(B1, 0, 1); PG8_STAGE(PG8_SB(0, 0), b2, voffB);
;             PG8_BAR; PG8_WAIT_L(0); PG8_MMA(0, 1, At, B1); PG8_BAR;
;             PG8_LDA(At, 0, 1); PG8_STAGE(PG8_SA(0, 0), a2, voffA);
;             PG8_BAR; PG8_WAIT_L(0); PG8_MMA(1, 0, At, B0); PG8_BAR; PG8_SCHED;
;             PG8_STAGE(PG8_SB(0, 1), b2 + hstep, voffB);
;             PG8_WAIT_V(6); PG8_BAR; PG8_MMA(1, 1, At, B1); PG8_BAR;
	s_waitcnt lgkmcnt(0)
	v_mfma_f32_16x16x32_bf16 v[62:65], v[144:147], v[160:163], v[62:65]
	v_mfma_f32_16x16x32_bf16 v[58:61], v[152:155], v[160:163], v[58:61]
	v_mfma_f32_16x16x32_bf16 v[54:57], v[144:147], v[178:181], v[54:57]
	v_mfma_f32_16x16x32_bf16 v[50:53], v[152:155], v[178:181], v[50:53]
	v_mfma_f32_16x16x32_bf16 v[38:41], v[144:147], v[186:189], v[38:41]
	v_mfma_f32_16x16x32_bf16 v[34:37], v[152:155], v[186:189], v[34:37]
	v_mfma_f32_16x16x32_bf16 v[22:25], v[144:147], v[194:197], v[22:25]
	v_mfma_f32_16x16x32_bf16 v[18:21], v[152:155], v[194:197], v[18:21]
	v_mfma_f32_16x16x32_bf16 v[62:65], v[148:151], v[174:177], v[62:65]
	v_mfma_f32_16x16x32_bf16 v[58:61], v[156:159], v[174:177], v[58:61]
	v_mfma_f32_16x16x32_bf16 v[54:57], v[148:151], v[182:185], v[54:57]
	v_mfma_f32_16x16x32_bf16 v[50:53], v[156:159], v[182:185], v[50:53]
	v_mfma_f32_16x16x32_bf16 v[38:41], v[148:151], v[190:193], v[38:41]
	v_mfma_f32_16x16x32_bf16 v[34:37], v[156:159], v[190:193], v[34:37]
	v_mfma_f32_16x16x32_bf16 v[22:25], v[148:151], v[198:201], v[22:25]
	v_mfma_f32_16x16x32_bf16 v[18:21], v[156:159], v[198:201], v[18:21]
	s_setprio 0
	s_barrier
	s_add_u32 s10, s10, 0x40080
	s_addc_u32 s11, s11, 0
	s_add_i32 s50, s50, s70
	v_lshl_add_u64 v[144:145], s[10:11], 0, v[0:1]
	s_mov_b32 m0, s50
	s_nop 0
	global_load_lds_dwordx4 v[144:145], off
	v_lshl_add_u64 v[144:145], s[10:11], 0, v[130:131]
	s_add_i32 m0, s50, 0x2000
	s_nop 0
	global_load_lds_dwordx4 v[144:145], off
	s_waitcnt vmcnt(6)
	s_setprio 1
	s_barrier
	v_mfma_f32_16x16x32_bf16 v[46:49], v[216:219], v[160:163], v[46:49]
	v_mfma_f32_16x16x32_bf16 v[42:45], v[224:227], v[160:163], v[42:45]
	v_mfma_f32_16x16x32_bf16 v[30:33], v[216:219], v[178:181], v[30:33]
	v_mfma_f32_16x16x32_bf16 v[26:29], v[224:227], v[178:181], v[26:29]
	v_mfma_f32_16x16x32_bf16 v[14:17], v[216:219], v[186:189], v[14:17]
	v_mfma_f32_16x16x32_bf16 v[10:13], v[224:227], v[186:189], v[10:13]
	v_mfma_f32_16x16x32_bf16 v[6:9], v[216:219], v[194:197], v[6:9]
	v_mfma_f32_16x16x32_bf16 v[2:5], v[224:227], v[194:197], v[2:5]
	v_mfma_f32_16x16x32_bf16 v[46:49], v[220:223], v[174:177], v[46:49]
	v_mfma_f32_16x16x32_bf16 v[42:45], v[228:231], v[174:177], v[42:45]
	v_mfma_f32_16x16x32_bf16 v[30:33], v[220:223], v[182:185], v[30:33]
	v_mfma_f32_16x16x32_bf16 v[26:29], v[228:231], v[182:185], v[26:29]
	v_mfma_f32_16x16x32_bf16 v[14:17], v[220:223], v[190:193], v[14:17]
	v_mfma_f32_16x16x32_bf16 v[10:13], v[228:231], v[190:193], v[10:13]
	v_mfma_f32_16x16x32_bf16 v[6:9], v[220:223], v[198:201], v[6:9]
	v_mfma_f32_16x16x32_bf16 v[2:5], v[228:231], v[198:201], v[2:5]
	s_setprio 0
	s_add_i32 s83, s83, 2
	s_cmp_gt_u32 s83, 13
	s_barrier
.LBB0_88:
	s_add_u32 s40, s40, 0x100
	s_addc_u32 s41, s41, 0
	s_add_u32 s81, s81, 0x100
	s_addc_u32 s82, s82, 0
	s_add_u32 s10, s40, 0xfffc0080
	s_addc_u32 s11, s41, -1
	s_add_i32 s84, 0, 0x10000
	v_add_u32_e32 v156, s84, v141
	ds_read_b128 v[144:147], v156
	ds_read_b128 v[148:151], v156 offset:1024
	ds_read_b128 v[152:155], v156 offset:2048
	ds_read_b128 v[156:159], v156 offset:3072
	s_cmp_eq_u32 s83, 12
	s_cselect_b32 s51, s19, s11
	s_cselect_b32 s50, s79, s10
	s_cselect_b32 s11, s7, s82
	s_cselect_b32 s10, s80, s81
	v_lshl_add_u64 v[202:203], s[40:41], 0, v[136:137]
	s_add_i32 m0, s71, 0xc000
	ds_read_b128 v[160:163], v143
	ds_read_b128 v[174:177], v143 offset:1024
	ds_read_b128 v[178:181], v143 offset:2048
	ds_read_b128 v[182:185], v143 offset:3072
	ds_read_b128 v[186:189], v143 offset:4096
	ds_read_b128 v[190:193], v143 offset:5120
	ds_read_b128 v[194:197], v143 offset:6144
	ds_read_b128 v[198:201], v143 offset:7168
	global_load_lds_dwordx4 v[202:203], off
	v_lshl_add_u64 v[202:203], s[40:41], 0, v[138:139]
	s_add_i32 m0, s71, 0xe000
	s_nop 0
	global_load_lds_dwordx4 v[202:203], off
	s_waitcnt lgkmcnt(8)
	s_setprio 1
	s_barrier
	s_waitcnt lgkmcnt(0)
	v_mfma_f32_16x16x32_bf16 v[126:129], v[144:147], v[160:163], v[126:129]
	v_mfma_f32_16x16x32_bf16 v[122:125], v[152:155], v[160:163], v[122:125]
	v_mfma_f32_16x16x32_bf16 v[118:121], v[144:147], v[178:181], v[118:121]
	v_mfma_f32_16x16x32_bf16 v[114:117], v[152:155], v[178:181], v[114:117]
	v_mfma_f32_16x16x32_bf16 v[102:105], v[144:147], v[186:189], v[102:105]
	v_mfma_f32_16x16x32_bf16 v[98:101], v[152:155], v[186:189], v[98:101]
	v_mfma_f32_16x16x32_bf16 v[86:89], v[144:147], v[194:197], v[86:89]
	v_mfma_f32_16x16x32_bf16 v[82:85], v[152:155], v[194:197], v[82:85]
	v_mfma_f32_16x16x32_bf16 v[126:129], v[148:151], v[174:177], v[126:129]
	v_mfma_f32_16x16x32_bf16 v[122:125], v[156:159], v[174:177], v[122:125]
	v_mfma_f32_16x16x32_bf16 v[118:121], v[148:151], v[182:185], v[118:121]
	v_mfma_f32_16x16x32_bf16 v[114:117], v[156:159], v[182:185], v[114:117]
	v_mfma_f32_16x16x32_bf16 v[102:105], v[148:151], v[190:193], v[102:105]
	v_mfma_f32_16x16x32_bf16 v[98:101], v[156:159], v[190:193], v[98:101]
	v_mfma_f32_16x16x32_bf16 v[86:89], v[148:151], v[198:201], v[86:89]
	v_mfma_f32_16x16x32_bf16 v[82:85], v[156:159], v[198:201], v[82:85]
	s_setprio 0
	s_barrier
	s_add_i32 s86, 0, 0x14000
	s_add_i32 s84, s84, s70
	v_add_u32_e32 v173, s86, v141
	v_lshl_add_u64 v[202:203], s[10:11], 0, v[0:1]
	s_mov_b32 m0, s84
	ds_read_b128 v[216:219], v173
	ds_read_b128 v[220:223], v173 offset:1024
	ds_read_b128 v[224:227], v173 offset:2048
	ds_read_b128 v[228:231], v173 offset:3072
	global_load_lds_dwordx4 v[202:203], off
	v_lshl_add_u64 v[232:233], s[10:11], 0, v[130:131]
	s_add_i32 m0, s84, 0x2000
	s_nop 0
	global_load_lds_dwordx4 v[232:233], off
	s_setprio 1
	s_barrier
; #define PG8_STAGE(bufoff, gbase, voff) do { _Pragma("unroll") for (int _i = 0; _i < 2; ++_i) \
;         __builtin_amdgcn_global_load_lds((const unsigned*)((const char*)(gbase) + (voff)[_i]), (PG8_LAS unsigned*)(lds + (bufoff) + ldsw + _i * 8192), 16, 0, 0); } while (0)
; #define PG8_LDA(dst, b, h) do { _Pragma("unroll") for (int m = 0; m < 4; ++m) _Pragma("unroll") for (int k = 0; k < 2; ++k) dst[m][k] = *(const PG8_LAS bf16x8*)(lds + PG8_SA(b, h) + aoff + m * 2048 + k * 1024); } while (0)
; #define PG8_LDB(dst, b, h) do { _Pragma("unroll") for (int n = 0; n < 2; ++n) _Pragma("unroll") for (int k = 0; k < 2; ++k) dst[n][k] = *(const PG8_LAS bf16x8*)(lds + PG8_SB(b, h) + boff + n * 2048 + k * 1024); } while (0)
; #define PG8_MMA(ai, bj, At, Bt) do { __builtin_amdgcn_s_setprio(1); _Pragma("unroll") for (int m = 0; m < 4; ++m) _Pragma("unroll") for (int n = 0; n < 2; ++n) _Pragma("unroll") for (int k = 0; k < 2; ++k) \
;         acc[ai][bj][m][n] = __builtin_amdgcn_mfma_f32_16x16x32_bf16(Bt[n][k], At[m][k], acc[ai][bj][m][n], 0, 0, 0); __builtin_amdgcn_s_setprio(0); } while (0)
; #define PG8_WAIT_V(n) asm volatile("s_waitcnt vmcnt(" #n ")" ::: "memory")
; #define PG8_WAIT_L(n) asm volatile("s_waitcnt lgkmcnt(" #n ")" ::: "memory")
; #define PG8_BAR __builtin_amdgcn_s_barrier()
; #define PG8_SCHED __builtin_amdgcn_sched_barrier(0)
; template <class Epi, class Sched>
; __device__ __forceinline__ void gemm_phase(PG8_LAS unsigned char* lds, const Gemm g, const Sched& S, const Epi& E) {
;     ...
;             PG8_WAIT_L(8); PG8_BAR; PG8_WAIT_L(0); PG8_MMA(0, 0, At, B0); PG8_BAR; PG8_SCHED;
;             PG8_LDB(B1, 0, 1); PG8_STAGE(PG8_SB(0, 0), b2, voffB);
;             PG8_BAR; PG8_WAIT_L(0); PG8_MMA(0, 1, At, B1); PG8_BAR;
;             PG8_LDA(At, 0, 1); PG8_STAGE(PG8_SA(0, 0), a2, voffA);
;             PG8_BAR; PG8_WAIT_L(0); PG8_MMA(1, 0, At, B0); PG8_BAR; PG8_SCHED;
;             PG8_STAGE(PG8_SB(0, 1), b2 + hstep, voffB);
;             PG8_WAIT_V(6); PG8_BAR; PG8_MMA(1, 1, At, B1); PG8_BAR;
;             PG8_LDB(B0, 1, 0); PG8_SCHED; PG8_LDA(At, 1, 0); PG8_STAGE(PG8_SA(0, 1), a2 + hstep, voffA);
;             PG8_WAIT_L(8); PG8_BAR; PG8_WAIT_L(0); PG8_MMA(0, 0, At, B0); PG8_BAR; PG8_SCHED;
	s_waitcnt lgkmcnt(0)
	v_mfma_f32_16x16x32_bf16 v[110:113], v[216:219], v[160:163], v[110:113]
	v_mfma_f32_16x16x32_bf16 v[106:109], v[224:227], v[160:163], v[106:109]
	v_mfma_f32_16x16x32_bf16 v[94:97], v[216:219], v[178:181], v[94:97]
	v_mfma_f32_16x16x32_bf16 v[90:93], v[224:227], v[178:181], v[90:93]
	v_mfma_f32_16x16x32_bf16 v[78:81], v[216:219], v[186:189], v[78:81]
	v_mfma_f32_16x16x32_bf16 v[74:77], v[224:227], v[186:189], v[74:77]
	v_mfma_f32_16x16x32_bf16 v[70:73], v[216:219], v[194:197], v[70:73]
	v_mfma_f32_16x16x32_bf16 v[66:69], v[224:227], v[194:197], v[66:69]
	v_mfma_f32_16x16x32_bf16 v[110:113], v[220:223], v[174:177], v[110:113]
	v_mfma_f32_16x16x32_bf16 v[106:109], v[228:231], v[174:177], v[106:109]
	v_mfma_f32_16x16x32_bf16 v[94:97], v[220:223], v[182:185], v[94:97]
	v_mfma_f32_16x16x32_bf16 v[90:93], v[228:231], v[182:185], v[90:93]
	v_mfma_f32_16x16x32_bf16 v[78:81], v[220:223], v[190:193], v[78:81]
	v_mfma_f32_16x16x32_bf16 v[74:77], v[228:231], v[190:193], v[74:77]
	v_mfma_f32_16x16x32_bf16 v[70:73], v[220:223], v[198:201], v[70:73]
	v_mfma_f32_16x16x32_bf16 v[66:69], v[228:231], v[198:201], v[66:69]
	s_setprio 0
	s_barrier
	s_mov_b32 m0, s71
	v_lshl_add_u64 v[234:235], s[50:51], 0, v[134:135]
	ds_read_b128 v[160:163], v143 offset:16384
	ds_read_b128 v[174:177], v143 offset:17408
	ds_read_b128 v[178:181], v143 offset:18432
	ds_read_b128 v[182:185], v143 offset:19456
	ds_read_b128 v[186:189], v143 offset:20480
	ds_read_b128 v[190:193], v143 offset:21504
	ds_read_b128 v[194:197], v143 offset:22528
	ds_read_b128 v[198:201], v143 offset:23552
	global_load_lds_dwordx4 v[234:235], off
	v_lshl_add_u64 v[236:237], s[50:51], 0, v[132:133]
	s_mov_b32 m0, s72
	s_nop 0
	global_load_lds_dwordx4 v[236:237], off
	s_setprio 1
	s_barrier
	s_waitcnt lgkmcnt(0)
	v_mfma_f32_16x16x32_bf16 v[62:65], v[144:147], v[160:163], v[62:65]
	v_mfma_f32_16x16x32_bf16 v[58:61], v[152:155], v[160:163], v[58:61]
	v_mfma_f32_16x16x32_bf16 v[54:57], v[144:147], v[178:181], v[54:57]
	v_mfma_f32_16x16x32_bf16 v[50:53], v[152:155], v[178:181], v[50:53]
	v_mfma_f32_16x16x32_bf16 v[38:41], v[144:147], v[186:189], v[38:41]
	v_mfma_f32_16x16x32_bf16 v[34:37], v[152:155], v[186:189], v[34:37]
	v_mfma_f32_16x16x32_bf16 v[22:25], v[144:147], v[194:197], v[22:25]
	v_mfma_f32_16x16x32_bf16 v[18:21], v[152:155], v[194:197], v[18:21]
	v_mfma_f32_16x16x32_bf16 v[62:65], v[148:151], v[174:177], v[62:65]
	v_mfma_f32_16x16x32_bf16 v[58:61], v[156:159], v[174:177], v[58:61]
	v_mfma_f32_16x16x32_bf16 v[54:57], v[148:151], v[182:185], v[54:57]
	v_mfma_f32_16x16x32_bf16 v[50:53], v[156:159], v[182:185], v[50:53]
	v_mfma_f32_16x16x32_bf16 v[38:41], v[148:151], v[190:193], v[38:41]
	v_mfma_f32_16x16x32_bf16 v[34:37], v[156:159], v[190:193], v[34:37]
	v_mfma_f32_16x16x32_bf16 v[22:25], v[148:151], v[198:201], v[22:25]
	v_mfma_f32_16x16x32_bf16 v[18:21], v[156:159], v[198:201], v[18:21]
	s_setprio 0
	s_barrier
	s_add_u32 s84, s10, 0x40000
	s_addc_u32 s85, s11, 0
	s_add_i32 s86, s86, s70
	v_lshl_add_u64 v[144:145], s[84:85], 0, v[0:1]
	s_mov_b32 m0, s86
	s_nop 0
	global_load_lds_dwordx4 v[144:145], off
	v_lshl_add_u64 v[144:145], s[84:85], 0, v[130:131]
	s_add_i32 m0, s86, 0x2000
	s_nop 0
	global_load_lds_dwordx4 v[144:145], off
	s_waitcnt vmcnt(6)
	s_setprio 1
	s_barrier
	v_mfma_f32_16x16x32_bf16 v[46:49], v[216:219], v[160:163], v[46:49]
	v_mfma_f32_16x16x32_bf16 v[42:45], v[224:227], v[160:163], v[42:45]
	v_mfma_f32_16x16x32_bf16 v[30:33], v[216:219], v[178:181], v[30:33]
	v_mfma_f32_16x16x32_bf16 v[26:29], v[224:227], v[178:181], v[26:29]
	v_mfma_f32_16x16x32_bf16 v[14:17], v[216:219], v[186:189], v[14:17]
	v_mfma_f32_16x16x32_bf16 v[10:13], v[224:227], v[186:189], v[10:13]
	v_mfma_f32_16x16x32_bf16 v[6:9], v[216:219], v[194:197], v[6:9]
	v_mfma_f32_16x16x32_bf16 v[2:5], v[224:227], v[194:197], v[2:5]
	v_mfma_f32_16x16x32_bf16 v[46:49], v[220:223], v[174:177], v[46:49]
	v_mfma_f32_16x16x32_bf16 v[42:45], v[228:231], v[174:177], v[42:45]
	v_mfma_f32_16x16x32_bf16 v[30:33], v[220:223], v[182:185], v[30:33]
	v_mfma_f32_16x16x32_bf16 v[26:29], v[228:231], v[182:185], v[26:29]
	v_mfma_f32_16x16x32_bf16 v[14:17], v[220:223], v[190:193], v[14:17]
	v_mfma_f32_16x16x32_bf16 v[10:13], v[228:231], v[190:193], v[10:13]
	v_mfma_f32_16x16x32_bf16 v[6:9], v[220:223], v[198:201], v[6:9]
	v_mfma_f32_16x16x32_bf16 v[2:5], v[228:231], v[198:201], v[2:5]
	s_setprio 0
	s_barrier
	s_add_i32 s84, 0, 0x18000
	v_add_u32_e32 v156, s84, v141
	ds_read_b128 v[144:147], v156
	ds_read_b128 v[148:151], v156 offset:1024
	ds_read_b128 v[152:155], v156 offset:2048
	ds_read_b128 v[156:159], v156 offset:3072
	s_add_u32 s50, s50, 0x40000
	s_addc_u32 s51, s51, 0
	s_mov_b32 m0, s73
	v_lshl_add_u64 v[216:217], s[50:51], 0, v[134:135]
	ds_read_b128 v[160:163], v143 offset:32768
	ds_read_b128 v[174:177], v143 offset:33792
	ds_read_b128 v[178:181], v143 offset:34816
	ds_read_b128 v[182:185], v143 offset:35840
	ds_read_b128 v[186:189], v143 offset:36864
	ds_read_b128 v[190:193], v143 offset:37888
	ds_read_b128 v[194:197], v143 offset:38912
	ds_read_b128 v[198:201], v143 offset:39936
	global_load_lds_dwordx4 v[216:217], off
	v_lshl_add_u64 v[216:217], s[50:51], 0, v[132:133]
	s_mov_b32 m0, s74
	s_nop 0
	global_load_lds_dwordx4 v[216:217], off
	s_waitcnt lgkmcnt(8)
	s_setprio 1
	s_barrier
; #define PG8_STAGE(bufoff, gbase, voff) do { _Pragma("unroll") for (int _i = 0; _i < 2; ++_i) \
;         __builtin_amdgcn_global_load_lds((const unsigned*)((const char*)(gbase) + (voff)[_i]), (PG8_LAS unsigned*)(lds + (bufoff) + ldsw + _i * 8192), 16, 0, 0); } while (0)
; #define PG8_LDA(dst, b, h) do { _Pragma("unroll") for (int m = 0; m < 4; ++m) _Pragma("unroll") for (int k = 0; k < 2; ++k) dst[m][k] = *(const PG8_LAS bf16x8*)(lds + PG8_SA(b, h) + aoff + m * 2048 + k * 1024); } while (0)
; #define PG8_LDB(dst, b, h) do { _Pragma("unroll") for (int n = 0; n < 2; ++n) _Pragma("unroll") for (int k = 0; k < 2; ++k) dst[n][k] = *(const PG8_LAS bf16x8*)(lds + PG8_SB(b, h) + boff + n * 2048 + k * 1024); } while (0)
; #define PG8_MMA(ai, bj, At, Bt) do { __builtin_amdgcn_s_setprio(1); _Pragma("unroll") for (int m = 0; m < 4; ++m) _Pragma("unroll") for (int n = 0; n < 2; ++n) _Pragma("unroll") for (int k = 0; k < 2; ++k) \
;         acc[ai][bj][m][n] = __builtin_amdgcn_mfma_f32_16x16x32_bf16(Bt[n][k], At[m][k], acc[ai][bj][m][n], 0, 0, 0); __builtin_amdgcn_s_setprio(0); } while (0)
; #define PG8_WAIT_V(n) asm volatile("s_waitcnt vmcnt(" #n ")" ::: "memory")
; #define PG8_WAIT_L(n) asm volatile("s_waitcnt lgkmcnt(" #n ")" ::: "memory")
; #define PG8_BAR __builtin_amdgcn_s_barrier()
; #define PG8_SCHED __builtin_amdgcn_sched_barrier(0)
; template <class Epi, class Sched>
; __device__ __forceinline__ void gemm_phase(PG8_LAS unsigned char* lds, const Gemm g, const Sched& S, const Epi& E) {
;     ...
;             PG8_WAIT_L(8); PG8_BAR; PG8_WAIT_L(0); PG8_MMA(0, 0, At, B0); PG8_BAR; PG8_SCHED;
;             PG8_LDB(B1, 1, 1); PG8_STAGE(PG8_SB(1, 0), b3, voffB);
;             PG8_BAR; PG8_WAIT_L(0); PG8_MMA(0, 1, At, B1); PG8_BAR;
;             PG8_LDA(At, 1, 1); PG8_STAGE(PG8_SA(1, 0), a3, voffA);
;             PG8_BAR; PG8_WAIT_L(0); PG8_MMA(1, 0, At, B0); PG8_BAR; PG8_SCHED;
;             PG8_STAGE(PG8_SB(1, 1), b3 + hstep, voffB);
;             PG8_WAIT_V(6); PG8_BAR; PG8_MMA(1, 1, At, B1); PG8_BAR;
; __device__ __forceinline__ void seg_of(int ct, int& c0, int& w) {
;     if (ct < OFF_LQ) { c0 = ct & ~1023; w = 1024; }
;     else if (ct < OFF_LG) { const int k = (ct - OFF_LQ) / 1536; c0 = OFF_LQ + k * 1536; w = 1536; }
;     else if (ct < OFF_GATE) { c0 = OFF_LG + ((ct - OFF_LG) & ~511); w = 512; }
;     else { c0 = OFF_GATE; w = 3072; }
	s_waitcnt lgkmcnt(0)
	v_mfma_f32_16x16x32_bf16 v[126:129], v[144:147], v[160:163], v[126:129]
	v_mfma_f32_16x16x32_bf16 v[122:125], v[152:155], v[160:163], v[122:125]
	v_mfma_f32_16x16x32_bf16 v[118:121], v[144:147], v[178:181], v[118:121]
	v_mfma_f32_16x16x32_bf16 v[114:117], v[152:155], v[178:181], v[114:117]
	v_mfma_f32_16x16x32_bf16 v[102:105], v[144:147], v[186:189], v[102:105]
	v_mfma_f32_16x16x32_bf16 v[98:101], v[152:155], v[186:189], v[98:101]
	v_mfma_f32_16x16x32_bf16 v[86:89], v[144:147], v[194:197], v[86:89]
	v_mfma_f32_16x16x32_bf16 v[82:85], v[152:155], v[194:197], v[82:85]
	v_mfma_f32_16x16x32_bf16 v[126:129], v[148:151], v[174:177], v[126:129]
	v_mfma_f32_16x16x32_bf16 v[122:125], v[156:159], v[174:177], v[122:125]
	v_mfma_f32_16x16x32_bf16 v[118:121], v[148:151], v[182:185], v[118:121]
	v_mfma_f32_16x16x32_bf16 v[114:117], v[156:159], v[182:185], v[114:117]
	v_mfma_f32_16x16x32_bf16 v[102:105], v[148:151], v[190:193], v[102:105]
	v_mfma_f32_16x16x32_bf16 v[98:101], v[156:159], v[190:193], v[98:101]
	v_mfma_f32_16x16x32_bf16 v[86:89], v[148:151], v[198:201], v[86:89]
	v_mfma_f32_16x16x32_bf16 v[82:85], v[156:159], v[198:201], v[82:85]
	s_setprio 0
	s_barrier
	s_add_i32 s50, 0, 0x1c000
	s_add_i32 s51, s84, s70
	v_add_u32_e32 v173, s50, v141
	v_lshl_add_u64 v[202:203], v[202:203], 0, s[8:9]
	s_mov_b32 m0, s51
	ds_read_b128 v[216:219], v173
	ds_read_b128 v[220:223], v173 offset:1024
	ds_read_b128 v[224:227], v173 offset:2048
	ds_read_b128 v[228:231], v173 offset:3072
	global_load_lds_dwordx4 v[202:203], off
	v_lshl_add_u64 v[202:203], v[232:233], 0, s[8:9]
	s_add_i32 m0, s51, 0x2000
	s_nop 0
	global_load_lds_dwordx4 v[202:203], off
	s_setprio 1
	s_barrier
	s_waitcnt lgkmcnt(0)
	v_mfma_f32_16x16x32_bf16 v[110:113], v[216:219], v[160:163], v[110:113]
	v_mfma_f32_16x16x32_bf16 v[106:109], v[224:227], v[160:163], v[106:109]
	v_mfma_f32_16x16x32_bf16 v[94:97], v[216:219], v[178:181], v[94:97]
	v_mfma_f32_16x16x32_bf16 v[90:93], v[224:227], v[178:181], v[90:93]
	v_mfma_f32_16x16x32_bf16 v[78:81], v[216:219], v[186:189], v[78:81]
	v_mfma_f32_16x16x32_bf16 v[74:77], v[224:227], v[186:189], v[74:77]
	v_mfma_f32_16x16x32_bf16 v[70:73], v[216:219], v[194:197], v[70:73]
	v_mfma_f32_16x16x32_bf16 v[66:69], v[224:227], v[194:197], v[66:69]
	v_mfma_f32_16x16x32_bf16 v[110:113], v[220:223], v[174:177], v[110:113]
	v_mfma_f32_16x16x32_bf16 v[106:109], v[228:231], v[174:177], v[106:109]
	v_mfma_f32_16x16x32_bf16 v[94:97], v[220:223], v[182:185], v[94:97]
	v_mfma_f32_16x16x32_bf16 v[90:93], v[228:231], v[182:185], v[90:93]
	v_mfma_f32_16x16x32_bf16 v[78:81], v[220:223], v[190:193], v[78:81]
	v_mfma_f32_16x16x32_bf16 v[74:77], v[228:231], v[190:193], v[74:77]
	v_mfma_f32_16x16x32_bf16 v[70:73], v[220:223], v[198:201], v[70:73]
	v_mfma_f32_16x16x32_bf16 v[66:69], v[228:231], v[198:201], v[66:69]
	s_setprio 0
	s_barrier
	s_mov_b32 m0, s75
	v_lshl_add_u64 v[202:203], v[234:235], 0, s[8:9]
	ds_read_b128 v[160:163], v143 offset:49152
	ds_read_b128 v[174:177], v143 offset:50176
	ds_read_b128 v[178:181], v143 offset:51200
	ds_read_b128 v[182:185], v143 offset:52224
	ds_read_b128 v[186:189], v143 offset:53248
	ds_read_b128 v[190:193], v143 offset:54272
	ds_read_b128 v[194:197], v143 offset:55296
	ds_read_b128 v[198:201], v143 offset:56320
	global_load_lds_dwordx4 v[202:203], off
	v_lshl_add_u64 v[202:203], v[236:237], 0, s[8:9]
	s_mov_b32 m0, s76
	s_nop 0
	global_load_lds_dwordx4 v[202:203], off
	s_setprio 1
	s_barrier
	s_waitcnt lgkmcnt(0)
	v_mfma_f32_16x16x32_bf16 v[62:65], v[144:147], v[160:163], v[62:65]
	v_mfma_f32_16x16x32_bf16 v[58:61], v[152:155], v[160:163], v[58:61]
	v_mfma_f32_16x16x32_bf16 v[54:57], v[144:147], v[178:181], v[54:57]
	v_mfma_f32_16x16x32_bf16 v[50:53], v[152:155], v[178:181], v[50:53]
	v_mfma_f32_16x16x32_bf16 v[38:41], v[144:147], v[186:189], v[38:41]
	v_mfma_f32_16x16x32_bf16 v[34:37], v[152:155], v[186:189], v[34:37]
	v_mfma_f32_16x16x32_bf16 v[22:25], v[144:147], v[194:197], v[22:25]
	v_mfma_f32_16x16x32_bf16 v[18:21], v[152:155], v[194:197], v[18:21]
	v_mfma_f32_16x16x32_bf16 v[62:65], v[148:151], v[174:177], v[62:65]
	v_mfma_f32_16x16x32_bf16 v[58:61], v[156:159], v[174:177], v[58:61]
	v_mfma_f32_16x16x32_bf16 v[54:57], v[148:151], v[182:185], v[54:57]
	v_mfma_f32_16x16x32_bf16 v[50:53], v[156:159], v[182:185], v[50:53]
	v_mfma_f32_16x16x32_bf16 v[38:41], v[148:151], v[190:193], v[38:41]
	v_mfma_f32_16x16x32_bf16 v[34:37], v[156:159], v[190:193], v[34:37]
	v_mfma_f32_16x16x32_bf16 v[22:25], v[148:151], v[198:201], v[22:25]
	v_mfma_f32_16x16x32_bf16 v[18:21], v[156:159], v[198:201], v[18:21]
	s_setprio 0
	s_barrier
	s_add_u32 s10, s10, 0x40080
	s_addc_u32 s11, s11, 0
	s_add_i32 s50, s50, s70
	v_lshl_add_u64 v[144:145], s[10:11], 0, v[0:1]
	s_mov_b32 m0, s50
	s_nop 0
	global_load_lds_dwordx4 v[144:145], off
	v_lshl_add_u64 v[144:145], s[10:11], 0, v[130:131]
	s_add_i32 m0, s50, 0x2000
	s_nop 0
	global_load_lds_dwordx4 v[144:145], off
	s_waitcnt vmcnt(6)
	s_setprio 1
	s_barrier
	v_mfma_f32_16x16x32_bf16 v[46:49], v[216:219], v[160:163], v[46:49]
	v_mfma_f32_16x16x32_bf16 v[42:45], v[224:227], v[160:163], v[42:45]
	v_mfma_f32_16x16x32_bf16 v[30:33], v[216:219], v[178:181], v[30:33]
	v_mfma_f32_16x16x32_bf16 v[26:29], v[224:227], v[178:181], v[26:29]
	v_mfma_f32_16x16x32_bf16 v[14:17], v[216:219], v[186:189], v[14:17]
	v_mfma_f32_16x16x32_bf16 v[10:13], v[224:227], v[186:189], v[10:13]
	v_mfma_f32_16x16x32_bf16 v[6:9], v[216:219], v[194:197], v[6:9]
	v_mfma_f32_16x16x32_bf16 v[2:5], v[224:227], v[194:197], v[2:5]
	v_mfma_f32_16x16x32_bf16 v[46:49], v[220:223], v[174:177], v[46:49]
	v_mfma_f32_16x16x32_bf16 v[42:45], v[228:231], v[174:177], v[42:45]
	v_mfma_f32_16x16x32_bf16 v[30:33], v[220:223], v[182:185], v[30:33]
	v_mfma_f32_16x16x32_bf16 v[26:29], v[228:231], v[182:185], v[26:29]
	v_mfma_f32_16x16x32_bf16 v[14:17], v[220:223], v[190:193], v[14:17]
	v_mfma_f32_16x16x32_bf16 v[10:13], v[228:231], v[190:193], v[10:13]
	v_mfma_f32_16x16x32_bf16 v[6:9], v[220:223], v[198:201], v[6:9]
	v_mfma_f32_16x16x32_bf16 v[2:5], v[228:231], v[198:201], v[2:5]
	s_setprio 0
	s_add_i32 s83, s83, 2
	s_cmp_gt_u32 s83, 13
	s_barrier
	s_cbranch_scc0 .LBB0_88
	s_lshl_b32 s7, s28, 8
	s_cmp_gt_i32 s28, 15
	s_mov_b64 s[50:51], -1
	s_cbranch_scc0 .LBB0_95
	s_cmpk_gt_u32 s7, 0x21ff
	s_cbranch_scc0 .LBB0_92
	s_min_u32 s10, s7, 0x2800
	s_and_b32 s40, s10, 0x3e00
	s_cmpk_lt_u32 s7, 0x2800
	s_movk_i32 s10, 0x200
	s_cselect_b32 s28, s10, 0xc00
	s_mov_b64 s[50:51], 0
	s_mov_b64 s[10:11], s[28:29]

; #define PG8_STAGE(bufoff, gbase, voff) do { _Pragma("unroll") for (int _i = 0; _i < 2; ++_i) \
;         __builtin_amdgcn_global_load_lds((const unsigned*)((const char*)(gbase) + (voff)[_i]), (PG8_LAS unsigned*)(lds + (bufoff) + ldsw + _i * 8192), 16, 0, 0); } while (0)
; #define PG8_LDA(dst, b, h) do { _Pragma("unroll") for (int m = 0; m < 4; ++m) _Pragma("unroll") for (int k = 0; k < 2; ++k) dst[m][k] = *(const PG8_LAS bf16x8*)(lds + PG8_SA(b, h) + aoff + m * 2048 + k * 1024); } while (0)
; #define PG8_LDB(dst, b, h) do { _Pragma("unroll") for (int n = 0; n < 2; ++n) _Pragma("unroll") for (int k = 0; k < 2; ++k) dst[n][k] = *(const PG8_LAS bf16x8*)(lds + PG8_SB(b, h) + boff + n * 2048 + k * 1024); } while (0)
; #define PG8_MMA(ai, bj, At, Bt) do { __builtin_amdgcn_s_setprio(1); _Pragma("unroll") for (int m = 0; m < 4; ++m) _Pragma("unroll") for (int n = 0; n < 2; ++n) _Pragma("unroll") for (int k = 0; k < 2; ++k) \
;         acc[ai][bj][m][n] = __builtin_amdgcn_mfma_f32_16x16x32_bf16(Bt[n][k], At[m][k], acc[ai][bj][m][n], 0, 0, 0); __builtin_amdgcn_s_setprio(0); } while (0)
; #define PG8_WAIT_V(n) asm volatile("s_waitcnt vmcnt(" #n ")" ::: "memory")
; #define PG8_WAIT_L(n) asm volatile("s_waitcnt lgkmcnt(" #n ")" ::: "memory")
; #define PG8_BAR __builtin_amdgcn_s_barrier()
; #define PG8_SCHED __builtin_amdgcn_sched_barrier(0)
; template <class Epi, class Sched>
; __device__ __forceinline__ void gemm_phase(PG8_LAS unsigned char* lds, const Gemm g, const Sched& S, const Epi& E) {
;     ...
;             PG8_LDB(B0, 0, 0); PG8_SCHED; PG8_LDA(At, 0, 0); PG8_STAGE(PG8_SA(1, 1), a1 + hstep, voffA);
;             PG8_WAIT_L(8); PG8_BAR; PG8_WAIT_L(0); PG8_MMA(0, 0, At, B0); PG8_BAR; PG8_SCHED;
;             PG8_LDB(B1, 0, 1); PG8_STAGE(PG8_SB(0, 0), b2, voffB);
;             PG8_BAR; PG8_WAIT_L(0); PG8_MMA(0, 1, At, B1); PG8_BAR;
;             PG8_LDA(At, 0, 1); PG8_STAGE(PG8_SA(0, 0), a2, voffA);
;             PG8_BAR; PG8_WAIT_L(0); PG8_MMA(1, 0, At, B0); PG8_BAR; PG8_SCHED;
;             PG8_STAGE(PG8_SB(0, 1), b2 + hstep, voffB);
;             PG8_WAIT_V(6); PG8_BAR; PG8_MMA(1, 1, At, B1); PG8_BAR;
.LBB0_472:
	s_add_u32 s6, s50, 0xfff80080
	s_addc_u32 s7, s51, -1
	s_add_i32 s85, 0, 0x10000
	v_add_u32_e32 v0, s85, v222
	ds_read_b128 v[132:135], v0
	ds_read_b128 v[136:139], v0 offset:1024
	ds_read_b128 v[140:143], v0 offset:2048
	ds_read_b128 v[144:147], v0 offset:3072
	s_cmp_eq_u32 s84, 4
	s_cselect_b32 s53, s19, s7
	s_cselect_b32 s52, s41, s6
	s_cselect_b32 s7, s39, s83
	s_cselect_b32 s6, s81, s82
	v_lshl_add_u64 v[2:3], s[50:51], 0, v[182:183]
	s_add_i32 m0, s71, 0xc000
	ds_read_b128 v[148:151], v224
	ds_read_b128 v[152:155], v224 offset:1024
	ds_read_b128 v[156:159], v224 offset:2048
	ds_read_b128 v[160:163], v224 offset:3072
	ds_read_b128 v[186:189], v224 offset:4096
	ds_read_b128 v[190:193], v224 offset:5120
	ds_read_b128 v[194:197], v224 offset:6144
	ds_read_b128 v[198:201], v224 offset:7168
	global_load_lds_dwordx4 v[2:3], off
	v_lshl_add_u64 v[2:3], s[50:51], 0, v[184:185]
	s_add_i32 m0, s71, 0xe000
	s_nop 0
	global_load_lds_dwordx4 v[2:3], off
	s_waitcnt lgkmcnt(8)
	s_setprio 1
	s_barrier
	s_waitcnt lgkmcnt(0)
	v_mfma_f32_16x16x32_bf16 v[2:5], v[132:135], v[148:151], v[4:7]
	v_mfma_f32_16x16x32_bf16 v[6:9], v[140:143], v[148:151], v[8:11]
	v_mfma_f32_16x16x32_bf16 v[12:15], v[132:135], v[156:159], v[12:15]
	v_mfma_f32_16x16x32_bf16 v[16:19], v[140:143], v[156:159], v[16:19]
	v_mfma_f32_16x16x32_bf16 v[20:23], v[132:135], v[186:189], v[20:23]
	v_mfma_f32_16x16x32_bf16 v[24:27], v[140:143], v[186:189], v[24:27]
	v_mfma_f32_16x16x32_bf16 v[28:31], v[132:135], v[194:197], v[28:31]
	v_mfma_f32_16x16x32_bf16 v[32:35], v[140:143], v[194:197], v[32:35]
	v_mfma_f32_16x16x32_bf16 v[2:5], v[136:139], v[152:155], v[2:5]
	v_mfma_f32_16x16x32_bf16 v[8:11], v[144:147], v[152:155], v[6:9]
	v_mfma_f32_16x16x32_bf16 v[12:15], v[136:139], v[160:163], v[12:15]
	v_mfma_f32_16x16x32_bf16 v[16:19], v[144:147], v[160:163], v[16:19]
	v_mfma_f32_16x16x32_bf16 v[20:23], v[136:139], v[190:193], v[20:23]
	v_mfma_f32_16x16x32_bf16 v[24:27], v[144:147], v[190:193], v[24:27]
	v_mfma_f32_16x16x32_bf16 v[28:31], v[136:139], v[198:201], v[28:31]
	v_mfma_f32_16x16x32_bf16 v[32:35], v[144:147], v[198:201], v[32:35]
	s_setprio 0
	s_barrier
	s_add_i32 s88, 0, 0x14000
	s_add_i32 s85, s85, s70
	v_add_u32_e32 v0, s88, v222
	v_lshl_add_u64 v[202:203], s[6:7], 0, v[178:179]
	s_mov_b32 m0, s85
	ds_read_b128 v[226:229], v0
	ds_read_b128 v[230:233], v0 offset:1024
	ds_read_b128 v[234:237], v0 offset:2048
	ds_read_b128 v[238:241], v0 offset:3072
	global_load_lds_dwordx4 v[202:203], off
	v_lshl_add_u64 v[242:243], s[6:7], 0, v[174:175]
	s_add_i32 m0, s85, 0x2000
	s_nop 0
	global_load_lds_dwordx4 v[242:243], off
	s_setprio 1
	s_barrier
	s_waitcnt lgkmcnt(0)
	v_mfma_f32_16x16x32_bf16 v[36:39], v[226:229], v[148:151], v[36:39]
	v_mfma_f32_16x16x32_bf16 v[40:43], v[234:237], v[148:151], v[40:43]
	v_mfma_f32_16x16x32_bf16 v[44:47], v[226:229], v[156:159], v[44:47]
	v_mfma_f32_16x16x32_bf16 v[48:51], v[234:237], v[156:159], v[48:51]
	v_mfma_f32_16x16x32_bf16 v[52:55], v[226:229], v[186:189], v[52:55]
	v_mfma_f32_16x16x32_bf16 v[56:59], v[234:237], v[186:189], v[56:59]
	v_mfma_f32_16x16x32_bf16 v[60:63], v[226:229], v[194:197], v[60:63]
	v_mfma_f32_16x16x32_bf16 v[64:67], v[234:237], v[194:197], v[64:67]
	v_mfma_f32_16x16x32_bf16 v[36:39], v[230:233], v[152:155], v[36:39]
	v_mfma_f32_16x16x32_bf16 v[40:43], v[238:241], v[152:155], v[40:43]
	v_mfma_f32_16x16x32_bf16 v[44:47], v[230:233], v[160:163], v[44:47]
	v_mfma_f32_16x16x32_bf16 v[48:51], v[238:241], v[160:163], v[48:51]
	v_mfma_f32_16x16x32_bf16 v[52:55], v[230:233], v[190:193], v[52:55]
	v_mfma_f32_16x16x32_bf16 v[56:59], v[238:241], v[190:193], v[56:59]
	v_mfma_f32_16x16x32_bf16 v[60:63], v[230:233], v[198:201], v[60:63]
	v_mfma_f32_16x16x32_bf16 v[64:67], v[238:241], v[198:201], v[64:67]
	s_setprio 0
	s_barrier
	s_mov_b32 m0, s71
	v_lshl_add_u64 v[244:245], s[52:53], 0, v[180:181]
	ds_read_b128 v[148:151], v224 offset:16384
	ds_read_b128 v[152:155], v224 offset:17408
	ds_read_b128 v[156:159], v224 offset:18432
	ds_read_b128 v[160:163], v224 offset:19456
	ds_read_b128 v[186:189], v224 offset:20480
	ds_read_b128 v[190:193], v224 offset:21504
	ds_read_b128 v[194:197], v224 offset:22528
	ds_read_b128 v[198:201], v224 offset:23552
	global_load_lds_dwordx4 v[244:245], off
	v_lshl_add_u64 v[246:247], s[52:53], 0, v[176:177]
	s_mov_b32 m0, s72
	s_nop 0
	global_load_lds_dwordx4 v[246:247], off
	s_setprio 1
	s_barrier
	s_waitcnt lgkmcnt(0)
	v_mfma_f32_16x16x32_bf16 v[68:71], v[132:135], v[148:151], v[68:71]
	v_mfma_f32_16x16x32_bf16 v[72:75], v[140:143], v[148:151], v[72:75]
	v_mfma_f32_16x16x32_bf16 v[76:79], v[132:135], v[156:159], v[76:79]
	v_mfma_f32_16x16x32_bf16 v[80:83], v[140:143], v[156:159], v[80:83]
	v_mfma_f32_16x16x32_bf16 v[84:87], v[132:135], v[186:189], v[84:87]
	v_mfma_f32_16x16x32_bf16 v[88:91], v[140:143], v[186:189], v[88:91]
	v_mfma_f32_16x16x32_bf16 v[92:95], v[132:135], v[194:197], v[92:95]
	v_mfma_f32_16x16x32_bf16 v[96:99], v[140:143], v[194:197], v[96:99]
	v_mfma_f32_16x16x32_bf16 v[68:71], v[136:139], v[152:155], v[68:71]
	v_mfma_f32_16x16x32_bf16 v[72:75], v[144:147], v[152:155], v[72:75]
	v_mfma_f32_16x16x32_bf16 v[76:79], v[136:139], v[160:163], v[76:79]
	v_mfma_f32_16x16x32_bf16 v[80:83], v[144:147], v[160:163], v[80:83]
	v_mfma_f32_16x16x32_bf16 v[84:87], v[136:139], v[190:193], v[84:87]
	v_mfma_f32_16x16x32_bf16 v[88:91], v[144:147], v[190:193], v[88:91]
	v_mfma_f32_16x16x32_bf16 v[92:95], v[136:139], v[198:201], v[92:95]
	v_mfma_f32_16x16x32_bf16 v[96:99], v[144:147], v[198:201], v[96:99]
	s_setprio 0
	s_barrier
; #define PG8_STAGE(bufoff, gbase, voff) do { _Pragma("unroll") for (int _i = 0; _i < 2; ++_i) \
;         __builtin_amdgcn_global_load_lds((const unsigned*)((const char*)(gbase) + (voff)[_i]), (PG8_LAS unsigned*)(lds + (bufoff) + ldsw + _i * 8192), 16, 0, 0); } while (0)
; #define PG8_LDA(dst, b, h) do { _Pragma("unroll") for (int m = 0; m < 4; ++m) _Pragma("unroll") for (int k = 0; k < 2; ++k) dst[m][k] = *(const PG8_LAS bf16x8*)(lds + PG8_SA(b, h) + aoff + m * 2048 + k * 1024); } while (0)
; #define PG8_LDB(dst, b, h) do { _Pragma("unroll") for (int n = 0; n < 2; ++n) _Pragma("unroll") for (int k = 0; k < 2; ++k) dst[n][k] = *(const PG8_LAS bf16x8*)(lds + PG8_SB(b, h) + boff + n * 2048 + k * 1024); } while (0)
; #define PG8_MMA(ai, bj, At, Bt) do { __builtin_amdgcn_s_setprio(1); _Pragma("unroll") for (int m = 0; m < 4; ++m) _Pragma("unroll") for (int n = 0; n < 2; ++n) _Pragma("unroll") for (int k = 0; k < 2; ++k) \
;         acc[ai][bj][m][n] = __builtin_amdgcn_mfma_f32_16x16x32_bf16(Bt[n][k], At[m][k], acc[ai][bj][m][n], 0, 0, 0); __builtin_amdgcn_s_setprio(0); } while (0)
; #define PG8_WAIT_V(n) asm volatile("s_waitcnt vmcnt(" #n ")" ::: "memory")
; #define PG8_WAIT_L(n) asm volatile("s_waitcnt lgkmcnt(" #n ")" ::: "memory")
; #define PG8_BAR __builtin_amdgcn_s_barrier()
; #define PG8_SCHED __builtin_amdgcn_sched_barrier(0)
; template <class Epi, class Sched>
; __device__ __forceinline__ void gemm_phase(PG8_LAS unsigned char* lds, const Gemm g, const Sched& S, const Epi& E) {
;     ...
;             PG8_STAGE(PG8_SB(0, 1), b2 + hstep, voffB);
;             PG8_WAIT_V(6); PG8_BAR; PG8_MMA(1, 1, At, B1); PG8_BAR;
;             PG8_LDB(B0, 1, 0); PG8_SCHED; PG8_LDA(At, 1, 0); PG8_STAGE(PG8_SA(0, 1), a2 + hstep, voffA);
;             PG8_WAIT_L(8); PG8_BAR; PG8_WAIT_L(0); PG8_MMA(0, 0, At, B0); PG8_BAR; PG8_SCHED;
;             PG8_LDB(B1, 1, 1); PG8_STAGE(PG8_SB(1, 0), b3, voffB);
;             PG8_BAR; PG8_WAIT_L(0); PG8_MMA(0, 1, At, B1); PG8_BAR;
;             PG8_LDA(At, 1, 1); PG8_STAGE(PG8_SA(1, 0), a3, voffA);
;             PG8_BAR; PG8_WAIT_L(0); PG8_MMA(1, 0, At, B0); PG8_BAR; PG8_SCHED;
	s_add_u32 s86, s6, 0x80000
	s_addc_u32 s87, s7, 0
	s_add_i32 s85, s88, s70
	v_lshl_add_u64 v[6:7], s[86:87], 0, v[178:179]
	s_mov_b32 m0, s85
	s_nop 0
	global_load_lds_dwordx4 v[6:7], off
	v_lshl_add_u64 v[6:7], s[86:87], 0, v[174:175]
	s_add_i32 m0, s85, 0x2000
	s_nop 0
	global_load_lds_dwordx4 v[6:7], off
	s_waitcnt vmcnt(6)
	s_setprio 1
	s_barrier
	v_mfma_f32_16x16x32_bf16 v[100:103], v[226:229], v[148:151], v[100:103]
	v_mfma_f32_16x16x32_bf16 v[104:107], v[234:237], v[148:151], v[104:107]
	v_mfma_f32_16x16x32_bf16 v[108:111], v[226:229], v[156:159], v[108:111]
	v_mfma_f32_16x16x32_bf16 v[112:115], v[234:237], v[156:159], v[112:115]
	v_mfma_f32_16x16x32_bf16 v[116:119], v[226:229], v[186:189], v[116:119]
	v_mfma_f32_16x16x32_bf16 v[120:123], v[234:237], v[186:189], v[120:123]
	v_mfma_f32_16x16x32_bf16 v[124:127], v[226:229], v[194:197], v[124:127]
	v_mfma_f32_16x16x32_bf16 v[128:131], v[234:237], v[194:197], v[128:131]
	v_mfma_f32_16x16x32_bf16 v[100:103], v[230:233], v[152:155], v[100:103]
	v_mfma_f32_16x16x32_bf16 v[104:107], v[238:241], v[152:155], v[104:107]
	v_mfma_f32_16x16x32_bf16 v[108:111], v[230:233], v[160:163], v[108:111]
	v_mfma_f32_16x16x32_bf16 v[112:115], v[238:241], v[160:163], v[112:115]
	v_mfma_f32_16x16x32_bf16 v[116:119], v[230:233], v[190:193], v[116:119]
	v_mfma_f32_16x16x32_bf16 v[120:123], v[238:241], v[190:193], v[120:123]
	v_mfma_f32_16x16x32_bf16 v[124:127], v[230:233], v[198:201], v[124:127]
	v_mfma_f32_16x16x32_bf16 v[128:131], v[238:241], v[198:201], v[128:131]
	s_setprio 0
	s_barrier
	s_add_i32 s85, 0, 0x18000
	v_add_u32_e32 v0, s85, v222
	ds_read_b128 v[132:135], v0
	ds_read_b128 v[136:139], v0 offset:1024
	ds_read_b128 v[140:143], v0 offset:2048
	ds_read_b128 v[144:147], v0 offset:3072
	s_add_u32 s52, s52, 0x80000
	s_addc_u32 s53, s53, 0
	s_mov_b32 m0, s73
	v_lshl_add_u64 v[6:7], s[52:53], 0, v[180:181]
	ds_read_b128 v[148:151], v224 offset:32768
	ds_read_b128 v[152:155], v224 offset:33792
	ds_read_b128 v[156:159], v224 offset:34816
	ds_read_b128 v[160:163], v224 offset:35840
	ds_read_b128 v[186:189], v224 offset:36864
	ds_read_b128 v[190:193], v224 offset:37888
	ds_read_b128 v[194:197], v224 offset:38912
	ds_read_b128 v[198:201], v224 offset:39936
	global_load_lds_dwordx4 v[6:7], off
	v_lshl_add_u64 v[6:7], s[52:53], 0, v[176:177]
	s_mov_b32 m0, s74
	s_nop 0
	global_load_lds_dwordx4 v[6:7], off
	s_waitcnt lgkmcnt(8)
	s_setprio 1
	s_barrier
	s_waitcnt lgkmcnt(0)
	v_mfma_f32_16x16x32_bf16 v[2:5], v[132:135], v[148:151], v[2:5]
	v_mfma_f32_16x16x32_bf16 v[8:11], v[140:143], v[148:151], v[8:11]
	v_mfma_f32_16x16x32_bf16 v[12:15], v[132:135], v[156:159], v[12:15]
	v_mfma_f32_16x16x32_bf16 v[16:19], v[140:143], v[156:159], v[16:19]
	v_mfma_f32_16x16x32_bf16 v[20:23], v[132:135], v[186:189], v[20:23]
	v_mfma_f32_16x16x32_bf16 v[24:27], v[140:143], v[186:189], v[24:27]
	v_mfma_f32_16x16x32_bf16 v[28:31], v[132:135], v[194:197], v[28:31]
	v_mfma_f32_16x16x32_bf16 v[32:35], v[140:143], v[194:197], v[32:35]
	v_mfma_f32_16x16x32_bf16 v[4:7], v[136:139], v[152:155], v[2:5]
	v_mfma_f32_16x16x32_bf16 v[8:11], v[144:147], v[152:155], v[8:11]
	v_mfma_f32_16x16x32_bf16 v[12:15], v[136:139], v[160:163], v[12:15]
	v_mfma_f32_16x16x32_bf16 v[16:19], v[144:147], v[160:163], v[16:19]
	v_mfma_f32_16x16x32_bf16 v[20:23], v[136:139], v[190:193], v[20:23]
	v_mfma_f32_16x16x32_bf16 v[24:27], v[144:147], v[190:193], v[24:27]
	v_mfma_f32_16x16x32_bf16 v[28:31], v[136:139], v[198:201], v[28:31]
	v_mfma_f32_16x16x32_bf16 v[32:35], v[144:147], v[198:201], v[32:35]
	s_setprio 0
	s_barrier
	s_add_i32 s52, 0, 0x1c000
	s_add_i32 s53, s85, s70
	v_add_u32_e32 v0, s52, v222
	v_lshl_add_u64 v[2:3], v[202:203], 0, s[8:9]
	s_mov_b32 m0, s53
	ds_read_b128 v[226:229], v0
	ds_read_b128 v[230:233], v0 offset:1024
	ds_read_b128 v[234:237], v0 offset:2048
	ds_read_b128 v[238:241], v0 offset:3072
	global_load_lds_dwordx4 v[2:3], off
	v_lshl_add_u64 v[2:3], v[242:243], 0, s[8:9]
	s_add_i32 m0, s53, 0x2000
	s_nop 0
	global_load_lds_dwordx4 v[2:3], off
	s_setprio 1
	s_barrier
	s_waitcnt lgkmcnt(0)
	v_mfma_f32_16x16x32_bf16 v[36:39], v[226:229], v[148:151], v[36:39]
	v_mfma_f32_16x16x32_bf16 v[40:43], v[234:237], v[148:151], v[40:43]
	v_mfma_f32_16x16x32_bf16 v[44:47], v[226:229], v[156:159], v[44:47]
	v_mfma_f32_16x16x32_bf16 v[48:51], v[234:237], v[156:159], v[48:51]
	v_mfma_f32_16x16x32_bf16 v[52:55], v[226:229], v[186:189], v[52:55]
	v_mfma_f32_16x16x32_bf16 v[56:59], v[234:237], v[186:189], v[56:59]
	v_mfma_f32_16x16x32_bf16 v[60:63], v[226:229], v[194:197], v[60:63]
	v_mfma_f32_16x16x32_bf16 v[64:67], v[234:237], v[194:197], v[64:67]
	v_mfma_f32_16x16x32_bf16 v[36:39], v[230:233], v[152:155], v[36:39]
	v_mfma_f32_16x16x32_bf16 v[40:43], v[238:241], v[152:155], v[40:43]
	v_mfma_f32_16x16x32_bf16 v[44:47], v[230:233], v[160:163], v[44:47]
	v_mfma_f32_16x16x32_bf16 v[48:51], v[238:241], v[160:163], v[48:51]
	v_mfma_f32_16x16x32_bf16 v[52:55], v[230:233], v[190:193], v[52:55]
	v_mfma_f32_16x16x32_bf16 v[56:59], v[238:241], v[190:193], v[56:59]
	v_mfma_f32_16x16x32_bf16 v[60:63], v[230:233], v[198:201], v[60:63]
	v_mfma_f32_16x16x32_bf16 v[64:67], v[238:241], v[198:201], v[64:67]
	s_setprio 0
	s_barrier
	s_mov_b32 m0, s75
	v_lshl_add_u64 v[2:3], v[244:245], 0, s[8:9]
	ds_read_b128 v[148:151], v224 offset:49152
	ds_read_b128 v[152:155], v224 offset:50176
	ds_read_b128 v[156:159], v224 offset:51200
	ds_read_b128 v[160:163], v224 offset:52224
	ds_read_b128 v[186:189], v224 offset:53248
	ds_read_b128 v[190:193], v224 offset:54272
	ds_read_b128 v[194:197], v224 offset:55296
	ds_read_b128 v[198:201], v224 offset:56320
	global_load_lds_dwordx4 v[2:3], off
	v_lshl_add_u64 v[2:3], v[246:247], 0, s[8:9]
	s_mov_b32 m0, s76
	s_nop 0
	global_load_lds_dwordx4 v[2:3], off
	s_setprio 1
	s_barrier
; #define PG8_STAGE(bufoff, gbase, voff) do { _Pragma("unroll") for (int _i = 0; _i < 2; ++_i) \
;         __builtin_amdgcn_global_load_lds((const unsigned*)((const char*)(gbase) + (voff)[_i]), (PG8_LAS unsigned*)(lds + (bufoff) + ldsw + _i * 8192), 16, 0, 0); } while (0)
; #define PG8_BAR __builtin_amdgcn_s_barrier()
; template <class Epi, class Sched>
; __device__ __forceinline__ void gemm_phase(PG8_LAS unsigned char* lds, const Gemm g, const Sched& S, const Epi& E) {
;     ...
;             PG8_BAR; PG8_WAIT_L(0); PG8_MMA(0, 1, At, B1); PG8_BAR;
;             PG8_LDA(At, 1, 1); PG8_STAGE(PG8_SA(1, 0), a3, voffA);
;             PG8_BAR; PG8_WAIT_L(0); PG8_MMA(1, 0, At, B0); PG8_BAR; PG8_SCHED;
;             PG8_STAGE(PG8_SB(1, 1), b3 + hstep, voffB);
;             PG8_WAIT_V(6); PG8_BAR; PG8_MMA(1, 1, At, B1); PG8_BAR;
;     __device__ __forceinline__ void operator()(f32x4 (&acc)[2][2][4][2], const Unit& u, int wr, int wc, int fr, int fq) const {
;         const int row0 = u.pm * 256 + wr * 64 + fr, col0 = u.pn * 256 + wc * 32 + 8 * fq;
;         if (u.seg == 0) return;
;         if (u.seg < 3) {
;             const int br = u.seg - 1;
; #pragma unroll
;             for (int ai = 0; ai < 2; ++ai)
; #pragma unroll
;                 for (int m = 0; m < 4; ++m) { const bf16* zp = Z + (size_t)T * OFF_GATE + (size_t)(row0 + ai * 128 + m * 16) * 3072 + br * 1024 + col0;
; #pragma unroll
;                     for (int bj = 0; bj < 2; ++bj) { const v4u gc = *(const v4u*)(zp + bj * 128), gn = *(const v4u*)(zp + 1024 + bj * 128);
;                         f32x4 r0, r1;
;     ...
;                         r0[0] = RAT(bflo(gn.x), bflo(gc.x)); r0[1] = RAT(bfhi(gn.x), bfhi(gc.x)); r0[2] = RAT(bflo(gn.y), bflo(gc.y)); r0[3] = RAT(bfhi(gn.y), bfhi(gc.y));
;                         r1[0] = RAT(bflo(gn.z), bflo(gc.z)); r1[1] = RAT(bfhi(gn.z), bfhi(gc.z)); r1[2] = RAT(bflo(gn.w), bflo(gc.w)); r1[3] = RAT(bfhi(gn.w), bfhi(gc.w));
;     ...
;                         acc[ai][bj][m][0] *= r0; acc[ai][bj][m][1] *= r1; } }
;             return;
;         }
; #pragma unroll
;         for (int ai = 0; ai < 2; ++ai) {
;             v4u gq[4][2];
; #pragma unroll
;             for (int m = 0; m < 4; ++m)
; #pragma unroll
;                 for (int bj = 0; bj < 2; ++bj) gq[m][bj] = *(const v4u*)(Z + (size_t)T * OFF_GATE + (size_t)(row0 + ai * 128 + m * 16) * 3072 + 2048 + col0 + bj * 128);
	s_waitcnt lgkmcnt(0)
	v_mfma_f32_16x16x32_bf16 v[68:71], v[132:135], v[148:151], v[68:71]
	v_mfma_f32_16x16x32_bf16 v[72:75], v[140:143], v[148:151], v[72:75]
	v_mfma_f32_16x16x32_bf16 v[76:79], v[132:135], v[156:159], v[76:79]
	v_mfma_f32_16x16x32_bf16 v[80:83], v[140:143], v[156:159], v[80:83]
	v_mfma_f32_16x16x32_bf16 v[84:87], v[132:135], v[186:189], v[84:87]
	v_mfma_f32_16x16x32_bf16 v[88:91], v[140:143], v[186:189], v[88:91]
	v_mfma_f32_16x16x32_bf16 v[92:95], v[132:135], v[194:197], v[92:95]
	v_mfma_f32_16x16x32_bf16 v[96:99], v[140:143], v[194:197], v[96:99]
	v_mfma_f32_16x16x32_bf16 v[68:71], v[136:139], v[152:155], v[68:71]
	v_mfma_f32_16x16x32_bf16 v[72:75], v[144:147], v[152:155], v[72:75]
	v_mfma_f32_16x16x32_bf16 v[76:79], v[136:139], v[160:163], v[76:79]
	v_mfma_f32_16x16x32_bf16 v[80:83], v[144:147], v[160:163], v[80:83]
	v_mfma_f32_16x16x32_bf16 v[84:87], v[136:139], v[190:193], v[84:87]
	v_mfma_f32_16x16x32_bf16 v[88:91], v[144:147], v[190:193], v[88:91]
	v_mfma_f32_16x16x32_bf16 v[92:95], v[136:139], v[198:201], v[92:95]
	v_mfma_f32_16x16x32_bf16 v[96:99], v[144:147], v[198:201], v[96:99]
	s_setprio 0
	s_barrier
	s_add_u32 s6, s6, 0x80080
	s_addc_u32 s7, s7, 0
	s_add_i32 s52, s52, s70
	v_lshl_add_u64 v[2:3], s[6:7], 0, v[178:179]
	s_mov_b32 m0, s52
	s_nop 0
	global_load_lds_dwordx4 v[2:3], off
	v_lshl_add_u64 v[2:3], s[6:7], 0, v[174:175]
	s_add_i32 m0, s52, 0x2000
	s_nop 0
	global_load_lds_dwordx4 v[2:3], off
	s_waitcnt vmcnt(6)
	s_setprio 1
	s_barrier
	v_mfma_f32_16x16x32_bf16 v[100:103], v[226:229], v[148:151], v[100:103]
	v_mfma_f32_16x16x32_bf16 v[104:107], v[234:237], v[148:151], v[104:107]
	v_mfma_f32_16x16x32_bf16 v[108:111], v[226:229], v[156:159], v[108:111]
	v_mfma_f32_16x16x32_bf16 v[112:115], v[234:237], v[156:159], v[112:115]
	v_mfma_f32_16x16x32_bf16 v[116:119], v[226:229], v[186:189], v[116:119]
	v_mfma_f32_16x16x32_bf16 v[120:123], v[234:237], v[186:189], v[120:123]
	v_mfma_f32_16x16x32_bf16 v[124:127], v[226:229], v[194:197], v[124:127]
	v_mfma_f32_16x16x32_bf16 v[128:131], v[234:237], v[194:197], v[128:131]
	v_mfma_f32_16x16x32_bf16 v[100:103], v[230:233], v[152:155], v[100:103]
	v_mfma_f32_16x16x32_bf16 v[104:107], v[238:241], v[152:155], v[104:107]
	v_mfma_f32_16x16x32_bf16 v[108:111], v[230:233], v[160:163], v[108:111]
	v_mfma_f32_16x16x32_bf16 v[112:115], v[238:241], v[160:163], v[112:115]
	v_mfma_f32_16x16x32_bf16 v[116:119], v[230:233], v[190:193], v[116:119]
	v_mfma_f32_16x16x32_bf16 v[120:123], v[238:241], v[190:193], v[120:123]
	v_mfma_f32_16x16x32_bf16 v[124:127], v[230:233], v[198:201], v[124:127]
	v_mfma_f32_16x16x32_bf16 v[128:131], v[238:241], v[198:201], v[128:131]
	s_setprio 0
	s_add_i32 s84, s84, 2
	s_add_u32 s50, s50, 0x100
	s_addc_u32 s51, s51, 0
	s_add_u32 s82, s82, 0x100
	s_addc_u32 s83, s83, 0
	s_cmp_gt_u32 s84, 5
	s_barrier
	s_cbranch_scc0 .LBB0_472
	s_cmp_eq_u32 s78, 0
	s_cbranch_scc1 .LBB0_478
	v_lshl_add_u32 v2, s80, 8, v221
	v_lshl_or_b32 v192, s79, 8, v223
	s_mov_b64 s[6:7], -1
	s_cmp_lt_i32 s78, 3
	v_ashrrev_i32_e32 v193, 31, v192
	v_or_b32_e32 v190, 16, v2
	v_or_b32_e32 v188, 32, v2
	v_or_b32_e32 v186, 48, v2
	s_cbranch_scc1 .LBB0_476
	v_mov_b64_e32 v[196:197], s[46:47]
	v_mad_i64_i32 v[132:133], s[6:7], v2, s68, v[196:197]
	v_lshlrev_b64 v[194:195], 1, v[192:193]
	v_lshl_add_u64 v[132:133], v[132:133], 0, v[194:195]
	s_mov_b64 s[50:51], 0x14001000
	v_lshl_add_u64 v[134:135], v[132:133], 0, s[50:51]
	v_add_co_u32_e32 v132, vcc, 0x14001000, v132
	v_ashrrev_i32_e32 v3, 31, v2
	s_nop 0
	v_addc_co_u32_e32 v133, vcc, 0, v133, vcc
	global_load_dwordx4 v[160:163], v[132:133], off
	global_load_dwordx4 v[156:159], v[134:135], off offset:256
	v_mad_i64_i32 v[132:133], s[6:7], v190, s68, v[196:197]
	v_lshl_add_u64 v[132:133], v[132:133], 0, v[194:195]
	v_lshl_add_u64 v[134:135], v[132:133], 0, s[50:51]
	v_add_co_u32_e32 v132, vcc, 0x14001000, v132
	v_lshlrev_b64 v[198:199], 11, v[2:3]
	s_nop 0
	v_addc_co_u32_e32 v133, vcc, 0, v133, vcc
	global_load_dwordx4 v[152:155], v[132:133], off
	global_load_dwordx4 v[148:151], v[134:135], off offset:256
	v_mad_i64_i32 v[132:133], s[6:7], v188, s68, v[196:197]
	v_lshl_add_u64 v[132:133], v[132:133], 0, v[194:195]
	v_lshl_add_u64 v[134:135], v[132:133], 0, s[50:51]
	v_add_co_u32_e32 v132, vcc, 0x14001000, v132
	v_lshl_add_u64 v[198:199], s[56:57], 0, v[198:199]
	s_nop 0
	v_addc_co_u32_e32 v133, vcc, 0, v133, vcc
	global_load_dwordx4 v[144:147], v[132:133], off
	global_load_dwordx4 v[140:143], v[134:135], off offset:256
	v_mad_i64_i32 v[132:133], s[6:7], v186, s68, v[196:197]
	v_lshl_add_u64 v[132:133], v[132:133], 0, v[194:195]
	v_lshl_add_u64 v[134:135], v[132:133], 0, s[50:51]
	v_add_co_u32_e32 v132, vcc, 0x14001000, v132
	v_lshl_add_u64 v[198:199], v[198:199], 0, v[194:195]
	s_nop 0
	v_addc_co_u32_e32 v133, vcc, 0, v133, vcc
	global_load_dwordx4 v[136:139], v[132:133], off
	s_nop 0
	global_load_dwordx4 v[132:135], v[134:135], off offset:256
	v_ashrrev_i32_e32 v191, 31, v190
	v_ashrrev_i32_e32 v189, 31, v188
	v_ashrrev_i32_e32 v187, 31, v186
	v_add_u32_e32 v226, 0x80, v2
	s_mov_b32 s19, 0x14001000
	v_add_u32_e32 v202, 0x90, v2
	v_ashrrev_i32_e32 v227, 31, v226
	v_ashrrev_i32_e32 v203, 31, v202
	s_waitcnt vmcnt(0)
; __device__ __forceinline__ unsigned pk2(float lo, float hi) { v2f v = {lo, hi}; return __builtin_bit_cast(unsigned, __builtin_convertvector(v, v2bf)); }
; __device__ __forceinline__ float bflo(unsigned u) { return __uint_as_float(u << 16); }
; __device__ __forceinline__ float bfhi(unsigned u) { return __uint_as_float(u & 0xffff0000u); }
; #define SG(a_, g_) ((a_) * __builtin_amdgcn_rcpf(einv(g_)))
;     __device__ __forceinline__ void operator()(f32x4 (&acc)[2][2][4][2], const Unit& u, int wr, int wc, int fr, int fq) const {
;     ...
;             for (int m = 0; m < 4; ++m) { const int row = row0 + ai * 128 + m * 16;
; #pragma unroll
;                 for (int bj = 0; bj < 2; ++bj) { const int col = col0 + bj * 128;
;                     const v4u gw = gq[m][bj];
;                     const f32x4 a0 = acc[ai][bj][m][0], a1 = acc[ai][bj][m][1];
;     ...
;                     v4u w; w.x = pk2(SG(a0[0], bflo(gw.x)), SG(a0[1], bfhi(gw.x))); w.y = pk2(SG(a0[2], bflo(gw.y)), SG(a0[3], bfhi(gw.y)));
;                     w.z = pk2(SG(a1[0], bflo(gw.z)), SG(a1[1], bfhi(gw.z))); w.w = pk2(SG(a1[2], bflo(gw.w)), SG(a1[3], bfhi(gw.w)));
;     ...
;                     *(v4u*)(MB + (size_t)row * 1024 + col) = w; } }
	v_lshlrev_b32_e32 v0, 16, v160
	v_max_f32_e64 v0, -v0, -v0
	v_min_f32_e32 v0, 0x41f00000, v0
	v_mul_f32_e32 v0, 0x3fb8aa3b, v0
	v_exp_f32_e32 v0, v0
	s_nop 0
	v_add_f32_e32 v0, 1.0, v0
	v_rcp_f32_e32 v200, v0
	v_and_b32_e32 v0, 0xffff0000, v160
	v_max_f32_e64 v0, -v0, -v0
	v_min_f32_e32 v0, 0x41f00000, v0
	v_mul_f32_e32 v0, 0x3fb8aa3b, v0
	v_exp_f32_e32 v0, v0
	s_nop 0
	v_add_f32_e32 v0, 1.0, v0
	v_rcp_f32_e32 v201, v0
	v_lshlrev_b32_e32 v0, 16, v161
	v_max_f32_e64 v0, -v0, -v0
	v_min_f32_e32 v0, 0x41f00000, v0
	v_mul_f32_e32 v0, 0x3fb8aa3b, v0
	v_exp_f32_e32 v0, v0
	v_pk_mul_f32 v[200:201], v[4:5], v[200:201]
	v_add_f32_e32 v0, 1.0, v0
	v_cvt_pk_bf16_f32 v160, v200, v201
	v_rcp_f32_e32 v200, v0
	v_and_b32_e32 v0, 0xffff0000, v161
	v_max_f32_e64 v0, -v0, -v0
	v_min_f32_e32 v0, 0x41f00000, v0
	v_mul_f32_e32 v0, 0x3fb8aa3b, v0
	v_exp_f32_e32 v0, v0
	s_nop 0
	v_add_f32_e32 v0, 1.0, v0
	v_rcp_f32_e32 v201, v0
	v_lshlrev_b32_e32 v0, 16, v162
	v_max_f32_e64 v0, -v0, -v0
	v_min_f32_e32 v0, 0x41f00000, v0
	v_mul_f32_e32 v0, 0x3fb8aa3b, v0
	v_exp_f32_e32 v0, v0
	v_pk_mul_f32 v[200:201], v[6:7], v[200:201]
	v_add_f32_e32 v0, 1.0, v0
	v_cvt_pk_bf16_f32 v161, v200, v201
	v_rcp_f32_e32 v200, v0
	v_and_b32_e32 v0, 0xffff0000, v162
	v_max_f32_e64 v0, -v0, -v0
	v_min_f32_e32 v0, 0x41f00000, v0
	v_mul_f32_e32 v0, 0x3fb8aa3b, v0
	v_exp_f32_e32 v0, v0
	s_nop 0
	v_add_f32_e32 v0, 1.0, v0
	v_rcp_f32_e32 v201, v0
	v_lshlrev_b32_e32 v0, 16, v163
	v_max_f32_e64 v0, -v0, -v0
	v_min_f32_e32 v0, 0x41f00000, v0
	v_mul_f32_e32 v0, 0x3fb8aa3b, v0
	v_exp_f32_e32 v0, v0
	v_pk_mul_f32 v[200:201], v[8:9], v[200:201]
	v_add_f32_e32 v0, 1.0, v0
	v_cvt_pk_bf16_f32 v162, v200, v201
	v_rcp_f32_e32 v200, v0
	v_and_b32_e32 v0, 0xffff0000, v163
	v_max_f32_e64 v0, -v0, -v0
	v_min_f32_e32 v0, 0x41f00000, v0
	v_mul_f32_e32 v0, 0x3fb8aa3b, v0
	v_exp_f32_e32 v0, v0
	s_nop 0
	v_add_f32_e32 v0, 1.0, v0
	v_rcp_f32_e32 v201, v0
	v_lshlrev_b32_e32 v0, 16, v156
	v_max_f32_e64 v0, -v0, -v0
	v_min_f32_e32 v0, 0x41f00000, v0
	v_mul_f32_e32 v0, 0x3fb8aa3b, v0
	v_exp_f32_e32 v0, v0
	v_pk_mul_f32 v[200:201], v[10:11], v[200:201]
	v_add_f32_e32 v0, 1.0, v0
	v_cvt_pk_bf16_f32 v163, v200, v201
	global_store_dwordx4 v[198:199], v[160:163], off
	v_add_u32_e32 v200, 0xa0, v2
	v_ashrrev_i32_e32 v201, 31, v200
	v_rcp_f32_e32 v160, v0
	v_and_b32_e32 v0, 0xffff0000, v156
	v_max_f32_e64 v0, -v0, -v0
	v_min_f32_e32 v0, 0x41f00000, v0
	v_mul_f32_e32 v0, 0x3fb8aa3b, v0
	v_exp_f32_e32 v0, v0
	s_nop 0
	v_add_f32_e32 v0, 1.0, v0
	v_rcp_f32_e32 v161, v0
	v_lshlrev_b32_e32 v0, 16, v157
	v_max_f32_e64 v0, -v0, -v0
	v_min_f32_e32 v0, 0x41f00000, v0
	v_mul_f32_e32 v0, 0x3fb8aa3b, v0
	v_exp_f32_e32 v0, v0
	v_pk_mul_f32 v[160:161], v[36:37], v[160:161]
	v_add_f32_e32 v0, 1.0, v0
	v_cvt_pk_bf16_f32 v156, v160, v161
	v_rcp_f32_e32 v160, v0
	v_and_b32_e32 v0, 0xffff0000, v157
	v_max_f32_e64 v0, -v0, -v0
	v_min_f32_e32 v0, 0x41f00000, v0
	v_mul_f32_e32 v0, 0x3fb8aa3b, v0
	v_exp_f32_e32 v0, v0
	s_nop 0
	v_add_f32_e32 v0, 1.0, v0
	v_rcp_f32_e32 v161, v0
	v_lshlrev_b32_e32 v0, 16, v158
	v_max_f32_e64 v0, -v0, -v0
	v_min_f32_e32 v0, 0x41f00000, v0
	v_mul_f32_e32 v0, 0x3fb8aa3b, v0
	v_exp_f32_e32 v0, v0
	v_pk_mul_f32 v[160:161], v[38:39], v[160:161]
	v_add_f32_e32 v0, 1.0, v0
	v_cvt_pk_bf16_f32 v157, v160, v161
	v_rcp_f32_e32 v160, v0
	v_and_b32_e32 v0, 0xffff0000, v158
	v_max_f32_e64 v0, -v0, -v0
	v_min_f32_e32 v0, 0x41f00000, v0
	v_mul_f32_e32 v0, 0x3fb8aa3b, v0
	v_exp_f32_e32 v0, v0
	s_nop 0
	v_add_f32_e32 v0, 1.0, v0
	v_rcp_f32_e32 v161, v0
	v_lshlrev_b32_e32 v0, 16, v159
	v_max_f32_e64 v0, -v0, -v0
	v_min_f32_e32 v0, 0x41f00000, v0
	v_mul_f32_e32 v0, 0x3fb8aa3b, v0
	v_exp_f32_e32 v0, v0
	v_pk_mul_f32 v[160:161], v[40:41], v[160:161]
	v_add_f32_e32 v0, 1.0, v0
	v_cvt_pk_bf16_f32 v158, v160, v161
	v_rcp_f32_e32 v160, v0
	v_and_b32_e32 v0, 0xffff0000, v159
	v_max_f32_e64 v0, -v0, -v0
	v_min_f32_e32 v0, 0x41f00000, v0
	v_mul_f32_e32 v0, 0x3fb8aa3b, v0
	v_exp_f32_e32 v0, v0
	s_nop 0
	v_add_f32_e32 v0, 1.0, v0
	v_rcp_f32_e32 v161, v0
	v_lshlrev_b32_e32 v0, 16, v152
	v_max_f32_e64 v0, -v0, -v0
	v_min_f32_e32 v0, 0x41f00000, v0
	v_mul_f32_e32 v0, 0x3fb8aa3b, v0
	v_exp_f32_e32 v0, v0
	v_pk_mul_f32 v[160:161], v[42:43], v[160:161]
	v_add_f32_e32 v0, 1.0, v0
	v_cvt_pk_bf16_f32 v159, v160, v161
	global_store_dwordx4 v[198:199], v[156:159], off offset:256
	v_add_u32_e32 v198, 0xb0, v2
	v_ashrrev_i32_e32 v199, 31, v198
	v_rcp_f32_e32 v158, v0
	v_and_b32_e32 v0, 0xffff0000, v152
	v_max_f32_e64 v0, -v0, -v0
	v_min_f32_e32 v0, 0x41f00000, v0
	v_mul_f32_e32 v0, 0x3fb8aa3b, v0
	v_exp_f32_e32 v0, v0
	v_lshlrev_b64 v[156:157], 11, v[190:191]
	v_lshl_add_u64 v[156:157], s[56:57], 0, v[156:157]
	v_lshl_add_u64 v[156:157], v[156:157], 0, v[194:195]
	v_add_f32_e32 v0, 1.0, v0
	v_rcp_f32_e32 v159, v0
	v_lshlrev_b32_e32 v0, 16, v153
	v_max_f32_e64 v0, -v0, -v0
	v_min_f32_e32 v0, 0x41f00000, v0
	v_mul_f32_e32 v0, 0x3fb8aa3b, v0
	v_exp_f32_e32 v0, v0
	v_pk_mul_f32 v[158:159], v[12:13], v[158:159]
	v_add_f32_e32 v0, 1.0, v0
	v_cvt_pk_bf16_f32 v152, v158, v159
	v_rcp_f32_e32 v158, v0
	v_and_b32_e32 v0, 0xffff0000, v153
	v_max_f32_e64 v0, -v0, -v0
	v_min_f32_e32 v0, 0x41f00000, v0
	v_mul_f32_e32 v0, 0x3fb8aa3b, v0
	v_exp_f32_e32 v0, v0
	s_nop 0
	v_add_f32_e32 v0, 1.0, v0
	v_rcp_f32_e32 v159, v0
	v_lshlrev_b32_e32 v0, 16, v154
	v_max_f32_e64 v0, -v0, -v0
	v_min_f32_e32 v0, 0x41f00000, v0
	v_mul_f32_e32 v0, 0x3fb8aa3b, v0
	v_exp_f32_e32 v0, v0
	v_pk_mul_f32 v[158:159], v[14:15], v[158:159]
	v_add_f32_e32 v0, 1.0, v0
	v_cvt_pk_bf16_f32 v153, v158, v159
	v_rcp_f32_e32 v158, v0
	v_and_b32_e32 v0, 0xffff0000, v154
	v_max_f32_e64 v0, -v0, -v0
; __device__ __forceinline__ unsigned pk2(float lo, float hi) { v2f v = {lo, hi}; return __builtin_bit_cast(unsigned, __builtin_convertvector(v, v2bf)); }
; __device__ __forceinline__ float bflo(unsigned u) { return __uint_as_float(u << 16); }
; __device__ __forceinline__ float bfhi(unsigned u) { return __uint_as_float(u & 0xffff0000u); }
; #define SG(a_, g_) ((a_) * __builtin_amdgcn_rcpf(einv(g_)))
;     static __device__ __forceinline__ float einv(float g) { return 1.f + __expf(fminf(-g, 30.f)); }
;     __device__ __forceinline__ void operator()(f32x4 (&acc)[2][2][4][2], const Unit& u, int wr, int wc, int fr, int fq) const {
;     ...
; #pragma unroll
;         for (int ai = 0; ai < 2; ++ai) {
;             v4u gq[4][2];
; #pragma unroll
;             for (int m = 0; m < 4; ++m)
; #pragma unroll
;                 for (int bj = 0; bj < 2; ++bj) gq[m][bj] = *(const v4u*)(Z + (size_t)T * OFF_GATE + (size_t)(row0 + ai * 128 + m * 16) * 3072 + 2048 + col0 + bj * 128);
; #pragma unroll
;             for (int m = 0; m < 4; ++m) { const int row = row0 + ai * 128 + m * 16;
; #pragma unroll
;                 for (int bj = 0; bj < 2; ++bj) { const int col = col0 + bj * 128;
;                     const v4u gw = gq[m][bj];
;                     const f32x4 a0 = acc[ai][bj][m][0], a1 = acc[ai][bj][m][1];
;     ...
;                     v4u w; w.x = pk2(SG(a0[0], bflo(gw.x)), SG(a0[1], bfhi(gw.x))); w.y = pk2(SG(a0[2], bflo(gw.y)), SG(a0[3], bfhi(gw.y)));
;                     w.z = pk2(SG(a1[0], bflo(gw.z)), SG(a1[1], bfhi(gw.z))); w.w = pk2(SG(a1[2], bflo(gw.w)), SG(a1[3], bfhi(gw.w)));
;     ...
;                     *(v4u*)(MB + (size_t)row * 1024 + col) = w; } }
;         }
	v_min_f32_e32 v0, 0x41f00000, v0
	v_mul_f32_e32 v0, 0x3fb8aa3b, v0
	v_exp_f32_e32 v0, v0
	s_nop 0
	v_add_f32_e32 v0, 1.0, v0
	v_rcp_f32_e32 v159, v0
	v_lshlrev_b32_e32 v0, 16, v155
	v_max_f32_e64 v0, -v0, -v0
	v_min_f32_e32 v0, 0x41f00000, v0
	v_mul_f32_e32 v0, 0x3fb8aa3b, v0
	v_exp_f32_e32 v0, v0
	v_pk_mul_f32 v[158:159], v[16:17], v[158:159]
	v_add_f32_e32 v0, 1.0, v0
	v_cvt_pk_bf16_f32 v154, v158, v159
	v_rcp_f32_e32 v158, v0
	v_and_b32_e32 v0, 0xffff0000, v155
	v_max_f32_e64 v0, -v0, -v0
	v_min_f32_e32 v0, 0x41f00000, v0
	v_mul_f32_e32 v0, 0x3fb8aa3b, v0
	v_exp_f32_e32 v0, v0
	s_nop 0
	v_add_f32_e32 v0, 1.0, v0
	v_rcp_f32_e32 v159, v0
	v_lshlrev_b32_e32 v0, 16, v148
	v_max_f32_e64 v0, -v0, -v0
	v_min_f32_e32 v0, 0x41f00000, v0
	v_mul_f32_e32 v0, 0x3fb8aa3b, v0
	v_exp_f32_e32 v0, v0
	v_pk_mul_f32 v[158:159], v[18:19], v[158:159]
	v_add_f32_e32 v0, 1.0, v0
	v_cvt_pk_bf16_f32 v155, v158, v159
	global_store_dwordx4 v[156:157], v[152:155], off
	s_nop 1
	v_rcp_f32_e32 v152, v0
	v_and_b32_e32 v0, 0xffff0000, v148
	v_max_f32_e64 v0, -v0, -v0
	v_min_f32_e32 v0, 0x41f00000, v0
	v_mul_f32_e32 v0, 0x3fb8aa3b, v0
	v_exp_f32_e32 v0, v0
	s_nop 0
	v_add_f32_e32 v0, 1.0, v0
	v_rcp_f32_e32 v153, v0
	v_lshlrev_b32_e32 v0, 16, v149
	v_max_f32_e64 v0, -v0, -v0
	v_min_f32_e32 v0, 0x41f00000, v0
	v_mul_f32_e32 v0, 0x3fb8aa3b, v0
	v_exp_f32_e32 v0, v0
	v_pk_mul_f32 v[152:153], v[44:45], v[152:153]
	v_add_f32_e32 v0, 1.0, v0
	v_cvt_pk_bf16_f32 v148, v152, v153
	v_rcp_f32_e32 v152, v0
	v_and_b32_e32 v0, 0xffff0000, v149
	v_max_f32_e64 v0, -v0, -v0
	v_min_f32_e32 v0, 0x41f00000, v0
	v_mul_f32_e32 v0, 0x3fb8aa3b, v0
	v_exp_f32_e32 v0, v0
	s_nop 0
	v_add_f32_e32 v0, 1.0, v0
	v_rcp_f32_e32 v153, v0
	v_lshlrev_b32_e32 v0, 16, v150
	v_max_f32_e64 v0, -v0, -v0
	v_min_f32_e32 v0, 0x41f00000, v0
	v_mul_f32_e32 v0, 0x3fb8aa3b, v0
	v_exp_f32_e32 v0, v0
	v_pk_mul_f32 v[152:153], v[46:47], v[152:153]
	v_add_f32_e32 v0, 1.0, v0
	v_cvt_pk_bf16_f32 v149, v152, v153
	v_rcp_f32_e32 v152, v0
	v_and_b32_e32 v0, 0xffff0000, v150
	v_max_f32_e64 v0, -v0, -v0
	v_min_f32_e32 v0, 0x41f00000, v0
	v_mul_f32_e32 v0, 0x3fb8aa3b, v0
	v_exp_f32_e32 v0, v0
	s_nop 0
	v_add_f32_e32 v0, 1.0, v0
	v_rcp_f32_e32 v153, v0
	v_lshlrev_b32_e32 v0, 16, v151
	v_max_f32_e64 v0, -v0, -v0
	v_min_f32_e32 v0, 0x41f00000, v0
	v_mul_f32_e32 v0, 0x3fb8aa3b, v0
	v_exp_f32_e32 v0, v0
	v_pk_mul_f32 v[152:153], v[48:49], v[152:153]
	v_add_f32_e32 v0, 1.0, v0
	v_cvt_pk_bf16_f32 v150, v152, v153
	v_rcp_f32_e32 v152, v0
	v_and_b32_e32 v0, 0xffff0000, v151
	v_max_f32_e64 v0, -v0, -v0
	v_min_f32_e32 v0, 0x41f00000, v0
	v_mul_f32_e32 v0, 0x3fb8aa3b, v0
	v_exp_f32_e32 v0, v0
	s_nop 0
	v_add_f32_e32 v0, 1.0, v0
	v_rcp_f32_e32 v153, v0
	v_lshlrev_b32_e32 v0, 16, v144
	v_max_f32_e64 v0, -v0, -v0
	v_min_f32_e32 v0, 0x41f00000, v0
	v_mul_f32_e32 v0, 0x3fb8aa3b, v0
	v_exp_f32_e32 v0, v0
	v_pk_mul_f32 v[152:153], v[50:51], v[152:153]
	v_add_f32_e32 v0, 1.0, v0
	v_cvt_pk_bf16_f32 v151, v152, v153
	global_store_dwordx4 v[156:157], v[148:151], off offset:256
	s_nop 1
	v_rcp_f32_e32 v150, v0
	v_and_b32_e32 v0, 0xffff0000, v144
	v_max_f32_e64 v0, -v0, -v0
	v_min_f32_e32 v0, 0x41f00000, v0
	v_mul_f32_e32 v0, 0x3fb8aa3b, v0
	v_exp_f32_e32 v0, v0
	v_lshlrev_b64 v[148:149], 11, v[188:189]
	v_lshl_add_u64 v[148:149], s[56:57], 0, v[148:149]
	v_lshl_add_u64 v[148:149], v[148:149], 0, v[194:195]
	v_add_f32_e32 v0, 1.0, v0
	v_rcp_f32_e32 v151, v0
	v_lshlrev_b32_e32 v0, 16, v145
	v_max_f32_e64 v0, -v0, -v0
	v_min_f32_e32 v0, 0x41f00000, v0
	v_mul_f32_e32 v0, 0x3fb8aa3b, v0
	v_exp_f32_e32 v0, v0
	v_pk_mul_f32 v[150:151], v[20:21], v[150:151]
	v_add_f32_e32 v0, 1.0, v0
	v_cvt_pk_bf16_f32 v144, v150, v151
	v_rcp_f32_e32 v150, v0
	v_and_b32_e32 v0, 0xffff0000, v145
	v_max_f32_e64 v0, -v0, -v0
	v_min_f32_e32 v0, 0x41f00000, v0
	v_mul_f32_e32 v0, 0x3fb8aa3b, v0
	v_exp_f32_e32 v0, v0
	s_nop 0
	v_add_f32_e32 v0, 1.0, v0
	v_rcp_f32_e32 v151, v0
	v_lshlrev_b32_e32 v0, 16, v146
	v_max_f32_e64 v0, -v0, -v0
	v_min_f32_e32 v0, 0x41f00000, v0
	v_mul_f32_e32 v0, 0x3fb8aa3b, v0
	v_exp_f32_e32 v0, v0
	v_pk_mul_f32 v[150:151], v[22:23], v[150:151]
	v_add_f32_e32 v0, 1.0, v0
	v_cvt_pk_bf16_f32 v145, v150, v151
	v_rcp_f32_e32 v150, v0
	v_and_b32_e32 v0, 0xffff0000, v146
	v_max_f32_e64 v0, -v0, -v0
	v_min_f32_e32 v0, 0x41f00000, v0
	v_mul_f32_e32 v0, 0x3fb8aa3b, v0
	v_exp_f32_e32 v0, v0
	s_nop 0
	v_add_f32_e32 v0, 1.0, v0
	v_rcp_f32_e32 v151, v0
	v_lshlrev_b32_e32 v0, 16, v147
	v_max_f32_e64 v0, -v0, -v0
	v_min_f32_e32 v0, 0x41f00000, v0
	v_mul_f32_e32 v0, 0x3fb8aa3b, v0
	v_exp_f32_e32 v0, v0
	v_pk_mul_f32 v[150:151], v[24:25], v[150:151]
	v_add_f32_e32 v0, 1.0, v0
	v_cvt_pk_bf16_f32 v146, v150, v151
	v_rcp_f32_e32 v150, v0
	v_and_b32_e32 v0, 0xffff0000, v147
	v_max_f32_e64 v0, -v0, -v0
	v_min_f32_e32 v0, 0x41f00000, v0
	v_mul_f32_e32 v0, 0x3fb8aa3b, v0
	v_exp_f32_e32 v0, v0
	s_nop 0
	v_add_f32_e32 v0, 1.0, v0
	v_rcp_f32_e32 v151, v0
	v_lshlrev_b32_e32 v0, 16, v140
	v_max_f32_e64 v0, -v0, -v0
	v_min_f32_e32 v0, 0x41f00000, v0
	v_mul_f32_e32 v0, 0x3fb8aa3b, v0
	v_exp_f32_e32 v0, v0
	v_pk_mul_f32 v[150:151], v[26:27], v[150:151]
	v_add_f32_e32 v0, 1.0, v0
	v_cvt_pk_bf16_f32 v147, v150, v151
	global_store_dwordx4 v[148:149], v[144:147], off
	s_nop 1
	v_rcp_f32_e32 v144, v0
	v_and_b32_e32 v0, 0xffff0000, v140
	v_max_f32_e64 v0, -v0, -v0
	v_min_f32_e32 v0, 0x41f00000, v0
	v_mul_f32_e32 v0, 0x3fb8aa3b, v0
	v_exp_f32_e32 v0, v0
	s_nop 0
	v_add_f32_e32 v0, 1.0, v0
	v_rcp_f32_e32 v145, v0
	v_lshlrev_b32_e32 v0, 16, v141
	v_max_f32_e64 v0, -v0, -v0
	v_min_f32_e32 v0, 0x41f00000, v0
	v_mul_f32_e32 v0, 0x3fb8aa3b, v0
	v_exp_f32_e32 v0, v0
	v_pk_mul_f32 v[144:145], v[52:53], v[144:145]
; __device__ __forceinline__ unsigned pk2(float lo, float hi) { v2f v = {lo, hi}; return __builtin_bit_cast(unsigned, __builtin_convertvector(v, v2bf)); }
; __device__ __forceinline__ float bflo(unsigned u) { return __uint_as_float(u << 16); }
; __device__ __forceinline__ float bfhi(unsigned u) { return __uint_as_float(u & 0xffff0000u); }
; #define SG(a_, g_) ((a_) * __builtin_amdgcn_rcpf(einv(g_)))
;     static __device__ __forceinline__ float einv(float g) { return 1.f + __expf(fminf(-g, 30.f)); }
;     __device__ __forceinline__ void operator()(f32x4 (&acc)[2][2][4][2], const Unit& u, int wr, int wc, int fr, int fq) const {
;     ...
; #pragma unroll
;         for (int ai = 0; ai < 2; ++ai) {
;             v4u gq[4][2];
; #pragma unroll
;             for (int m = 0; m < 4; ++m)
; #pragma unroll
;                 for (int bj = 0; bj < 2; ++bj) gq[m][bj] = *(const v4u*)(Z + (size_t)T * OFF_GATE + (size_t)(row0 + ai * 128 + m * 16) * 3072 + 2048 + col0 + bj * 128);
; #pragma unroll
;             for (int m = 0; m < 4; ++m) { const int row = row0 + ai * 128 + m * 16;
; #pragma unroll
;                 for (int bj = 0; bj < 2; ++bj) { const int col = col0 + bj * 128;
;                     const v4u gw = gq[m][bj];
;                     const f32x4 a0 = acc[ai][bj][m][0], a1 = acc[ai][bj][m][1];
;     ...
;                     v4u w; w.x = pk2(SG(a0[0], bflo(gw.x)), SG(a0[1], bfhi(gw.x))); w.y = pk2(SG(a0[2], bflo(gw.y)), SG(a0[3], bfhi(gw.y)));
;                     w.z = pk2(SG(a1[0], bflo(gw.z)), SG(a1[1], bfhi(gw.z))); w.w = pk2(SG(a1[2], bflo(gw.w)), SG(a1[3], bfhi(gw.w)));
;     ...
;                     *(v4u*)(MB + (size_t)row * 1024 + col) = w; } }
;         }
	v_add_f32_e32 v0, 1.0, v0
	v_cvt_pk_bf16_f32 v140, v144, v145
	v_rcp_f32_e32 v144, v0
	v_and_b32_e32 v0, 0xffff0000, v141
	v_max_f32_e64 v0, -v0, -v0
	v_min_f32_e32 v0, 0x41f00000, v0
	v_mul_f32_e32 v0, 0x3fb8aa3b, v0
	v_exp_f32_e32 v0, v0
	s_nop 0
	v_add_f32_e32 v0, 1.0, v0
	v_rcp_f32_e32 v145, v0
	v_lshlrev_b32_e32 v0, 16, v142
	v_max_f32_e64 v0, -v0, -v0
	v_min_f32_e32 v0, 0x41f00000, v0
	v_mul_f32_e32 v0, 0x3fb8aa3b, v0
	v_exp_f32_e32 v0, v0
	v_pk_mul_f32 v[144:145], v[54:55], v[144:145]
	v_add_f32_e32 v0, 1.0, v0
	v_cvt_pk_bf16_f32 v141, v144, v145
	v_rcp_f32_e32 v144, v0
	v_and_b32_e32 v0, 0xffff0000, v142
	v_max_f32_e64 v0, -v0, -v0
	v_min_f32_e32 v0, 0x41f00000, v0
	v_mul_f32_e32 v0, 0x3fb8aa3b, v0
	v_exp_f32_e32 v0, v0
	s_nop 0
	v_add_f32_e32 v0, 1.0, v0
	v_rcp_f32_e32 v145, v0
	v_lshlrev_b32_e32 v0, 16, v143
	v_max_f32_e64 v0, -v0, -v0
	v_min_f32_e32 v0, 0x41f00000, v0
	v_mul_f32_e32 v0, 0x3fb8aa3b, v0
	v_exp_f32_e32 v0, v0
	v_pk_mul_f32 v[144:145], v[56:57], v[144:145]
	v_add_f32_e32 v0, 1.0, v0
	v_cvt_pk_bf16_f32 v142, v144, v145
	v_rcp_f32_e32 v144, v0
	v_and_b32_e32 v0, 0xffff0000, v143
	v_max_f32_e64 v0, -v0, -v0
	v_min_f32_e32 v0, 0x41f00000, v0
	v_mul_f32_e32 v0, 0x3fb8aa3b, v0
	v_exp_f32_e32 v0, v0
	s_nop 0
	v_add_f32_e32 v0, 1.0, v0
	v_rcp_f32_e32 v145, v0
	v_lshlrev_b32_e32 v0, 16, v136
	v_max_f32_e64 v0, -v0, -v0
	v_min_f32_e32 v0, 0x41f00000, v0
	v_mul_f32_e32 v0, 0x3fb8aa3b, v0
	v_exp_f32_e32 v0, v0
	v_pk_mul_f32 v[144:145], v[58:59], v[144:145]
	v_add_f32_e32 v0, 1.0, v0
	v_cvt_pk_bf16_f32 v143, v144, v145
	global_store_dwordx4 v[148:149], v[140:143], off offset:256
	s_nop 1
	v_rcp_f32_e32 v142, v0
	v_and_b32_e32 v0, 0xffff0000, v136
	v_max_f32_e64 v0, -v0, -v0
	v_min_f32_e32 v0, 0x41f00000, v0
	v_mul_f32_e32 v0, 0x3fb8aa3b, v0
	v_exp_f32_e32 v0, v0
	v_lshlrev_b64 v[140:141], 11, v[186:187]
	v_lshl_add_u64 v[140:141], s[56:57], 0, v[140:141]
	v_lshl_add_u64 v[140:141], v[140:141], 0, v[194:195]
	v_add_f32_e32 v0, 1.0, v0
	v_rcp_f32_e32 v143, v0
	v_lshlrev_b32_e32 v0, 16, v137
	v_max_f32_e64 v0, -v0, -v0
	v_min_f32_e32 v0, 0x41f00000, v0
	v_mul_f32_e32 v0, 0x3fb8aa3b, v0
	v_exp_f32_e32 v0, v0
	v_pk_mul_f32 v[142:143], v[28:29], v[142:143]
	v_add_f32_e32 v0, 1.0, v0
	v_cvt_pk_bf16_f32 v136, v142, v143
	v_rcp_f32_e32 v142, v0
	v_and_b32_e32 v0, 0xffff0000, v137
	v_max_f32_e64 v0, -v0, -v0
	v_min_f32_e32 v0, 0x41f00000, v0
	v_mul_f32_e32 v0, 0x3fb8aa3b, v0
	v_exp_f32_e32 v0, v0
	s_nop 0
	v_add_f32_e32 v0, 1.0, v0
	v_rcp_f32_e32 v143, v0
	v_lshlrev_b32_e32 v0, 16, v138
	v_max_f32_e64 v0, -v0, -v0
	v_min_f32_e32 v0, 0x41f00000, v0
	v_mul_f32_e32 v0, 0x3fb8aa3b, v0
	v_exp_f32_e32 v0, v0
	v_pk_mul_f32 v[142:143], v[30:31], v[142:143]
	v_add_f32_e32 v0, 1.0, v0
	v_cvt_pk_bf16_f32 v137, v142, v143
	v_rcp_f32_e32 v142, v0
	v_and_b32_e32 v0, 0xffff0000, v138
	v_max_f32_e64 v0, -v0, -v0
	v_min_f32_e32 v0, 0x41f00000, v0
	v_mul_f32_e32 v0, 0x3fb8aa3b, v0
	v_exp_f32_e32 v0, v0
	s_nop 0
	v_add_f32_e32 v0, 1.0, v0
	v_rcp_f32_e32 v143, v0
	v_lshlrev_b32_e32 v0, 16, v139
	v_max_f32_e64 v0, -v0, -v0
	v_min_f32_e32 v0, 0x41f00000, v0
	v_mul_f32_e32 v0, 0x3fb8aa3b, v0
	v_exp_f32_e32 v0, v0
	v_pk_mul_f32 v[142:143], v[32:33], v[142:143]
	v_add_f32_e32 v0, 1.0, v0
	v_cvt_pk_bf16_f32 v138, v142, v143
	v_rcp_f32_e32 v142, v0
	v_and_b32_e32 v0, 0xffff0000, v139
	v_max_f32_e64 v0, -v0, -v0
	v_min_f32_e32 v0, 0x41f00000, v0
	v_mul_f32_e32 v0, 0x3fb8aa3b, v0
	v_exp_f32_e32 v0, v0
	s_nop 0
	v_add_f32_e32 v0, 1.0, v0
	v_rcp_f32_e32 v143, v0
	v_lshlrev_b32_e32 v0, 16, v132
	v_max_f32_e64 v0, -v0, -v0
	v_min_f32_e32 v0, 0x41f00000, v0
	v_mul_f32_e32 v0, 0x3fb8aa3b, v0
	v_exp_f32_e32 v0, v0
	v_pk_mul_f32 v[142:143], v[34:35], v[142:143]
	v_add_f32_e32 v0, 1.0, v0
	v_cvt_pk_bf16_f32 v139, v142, v143
	global_store_dwordx4 v[140:141], v[136:139], off
	s_nop 1
	v_rcp_f32_e32 v136, v0
	v_and_b32_e32 v0, 0xffff0000, v132
	v_max_f32_e64 v0, -v0, -v0
	v_min_f32_e32 v0, 0x41f00000, v0
	v_mul_f32_e32 v0, 0x3fb8aa3b, v0
	v_exp_f32_e32 v0, v0
	s_nop 0
	v_add_f32_e32 v0, 1.0, v0
	v_rcp_f32_e32 v137, v0
	v_lshlrev_b32_e32 v0, 16, v133
	v_max_f32_e64 v0, -v0, -v0
	v_min_f32_e32 v0, 0x41f00000, v0
	v_mul_f32_e32 v0, 0x3fb8aa3b, v0
	v_exp_f32_e32 v0, v0
	v_pk_mul_f32 v[136:137], v[60:61], v[136:137]
	v_add_f32_e32 v0, 1.0, v0
	v_cvt_pk_bf16_f32 v132, v136, v137
	v_rcp_f32_e32 v136, v0
	v_and_b32_e32 v0, 0xffff0000, v133
	v_max_f32_e64 v0, -v0, -v0
	v_min_f32_e32 v0, 0x41f00000, v0
	v_mul_f32_e32 v0, 0x3fb8aa3b, v0
	v_exp_f32_e32 v0, v0
	s_nop 0
	v_add_f32_e32 v0, 1.0, v0
	v_rcp_f32_e32 v137, v0
	v_lshlrev_b32_e32 v0, 16, v134
	v_max_f32_e64 v0, -v0, -v0
	v_min_f32_e32 v0, 0x41f00000, v0
	v_mul_f32_e32 v0, 0x3fb8aa3b, v0
	v_exp_f32_e32 v0, v0
	v_pk_mul_f32 v[136:137], v[62:63], v[136:137]
	v_add_f32_e32 v0, 1.0, v0
	v_cvt_pk_bf16_f32 v133, v136, v137
	v_rcp_f32_e32 v136, v0
	v_and_b32_e32 v0, 0xffff0000, v134
	v_max_f32_e64 v0, -v0, -v0
	v_min_f32_e32 v0, 0x41f00000, v0
	v_mul_f32_e32 v0, 0x3fb8aa3b, v0
	v_exp_f32_e32 v0, v0
	s_nop 0
	v_add_f32_e32 v0, 1.0, v0
	v_rcp_f32_e32 v137, v0
	v_lshlrev_b32_e32 v0, 16, v135
	v_max_f32_e64 v0, -v0, -v0
	v_min_f32_e32 v0, 0x41f00000, v0
	v_mul_f32_e32 v0, 0x3fb8aa3b, v0
	v_exp_f32_e32 v0, v0
	v_pk_mul_f32 v[136:137], v[64:65], v[136:137]
	v_add_f32_e32 v0, 1.0, v0
	v_cvt_pk_bf16_f32 v134, v136, v137
	v_rcp_f32_e32 v136, v0
	v_and_b32_e32 v0, 0xffff0000, v135
	v_max_f32_e64 v0, -v0, -v0
	v_min_f32_e32 v0, 0x41f00000, v0
	v_mul_f32_e32 v0, 0x3fb8aa3b, v0
	v_exp_f32_e32 v0, v0
	s_nop 0
	v_add_f32_e32 v0, 1.0, v0
	v_rcp_f32_e32 v137, v0
	s_nop 0
	v_pk_mul_f32 v[136:137], v[66:67], v[136:137]
	s_nop 0
	v_cvt_pk_bf16_f32 v135, v136, v137
	global_store_dwordx4 v[140:141], v[132:135], off offset:256
	s_nop 1
	v_mad_i64_i32 v[132:133], s[6:7], v226, s68, v[196:197]
	v_lshl_add_u64 v[132:133], v[132:133], 0, v[194:195]
	v_lshl_add_u64 v[134:135], v[132:133], 0, s[50:51]
	v_add_co_u32_e32 v132, vcc, s19, v132
	s_nop 1
	v_addc_co_u32_e32 v133, vcc, 0, v133, vcc
	global_load_dwordx4 v[160:163], v[132:133], off
	global_load_dwordx4 v[156:159], v[134:135], off offset:256
	v_mad_i64_i32 v[132:133], s[6:7], v202, s68, v[196:197]
	v_lshl_add_u64 v[132:133], v[132:133], 0, v[194:195]
	v_lshl_add_u64 v[134:135], v[132:133], 0, s[50:51]
	v_add_co_u32_e32 v132, vcc, s19, v132
	s_waitcnt vmcnt(0)
; __device__ __forceinline__ unsigned pk2(float lo, float hi) { v2f v = {lo, hi}; return __builtin_bit_cast(unsigned, __builtin_convertvector(v, v2bf)); }
; __device__ __forceinline__ float bflo(unsigned u) { return __uint_as_float(u << 16); }
; __device__ __forceinline__ float bfhi(unsigned u) { return __uint_as_float(u & 0xffff0000u); }
; #define SG(a_, g_) ((a_) * __builtin_amdgcn_rcpf(einv(g_)))
;     static __device__ __forceinline__ float einv(float g) { return 1.f + __expf(fminf(-g, 30.f)); }
;     __device__ __forceinline__ void operator()(f32x4 (&acc)[2][2][4][2], const Unit& u, int wr, int wc, int fr, int fq) const {
;     ...
;             for (int m = 0; m < 4; ++m)
; #pragma unroll
;                 for (int bj = 0; bj < 2; ++bj) gq[m][bj] = *(const v4u*)(Z + (size_t)T * OFF_GATE + (size_t)(row0 + ai * 128 + m * 16) * 3072 + 2048 + col0 + bj * 128);
; #pragma unroll
;             for (int m = 0; m < 4; ++m) { const int row = row0 + ai * 128 + m * 16;
; #pragma unroll
;                 for (int bj = 0; bj < 2; ++bj) { const int col = col0 + bj * 128;
;                     const v4u gw = gq[m][bj];
;                     const f32x4 a0 = acc[ai][bj][m][0], a1 = acc[ai][bj][m][1];
;     ...
;                     v4u w; w.x = pk2(SG(a0[0], bflo(gw.x)), SG(a0[1], bfhi(gw.x))); w.y = pk2(SG(a0[2], bflo(gw.y)), SG(a0[3], bfhi(gw.y)));
;                     w.z = pk2(SG(a1[0], bflo(gw.z)), SG(a1[1], bfhi(gw.z))); w.w = pk2(SG(a1[2], bflo(gw.w)), SG(a1[3], bfhi(gw.w)));
;     ...
;                     *(v4u*)(MB + (size_t)row * 1024 + col) = w; } }
;         }
	v_lshlrev_b32_e32 v0, 16, v160
	v_max_f32_e64 v0, -v0, -v0
	v_min_f32_e32 v0, 0x41f00000, v0
	v_mul_f32_e32 v0, 0x3fb8aa3b, v0
	v_addc_co_u32_e32 v133, vcc, 0, v133, vcc
	v_exp_f32_e32 v0, v0
	global_load_dwordx4 v[152:155], v[132:133], off
	global_load_dwordx4 v[148:151], v[134:135], off offset:256
	v_mad_i64_i32 v[132:133], s[6:7], v200, s68, v[196:197]
	v_lshl_add_u64 v[132:133], v[132:133], 0, v[194:195]
	v_lshl_add_u64 v[134:135], v[132:133], 0, s[50:51]
	v_add_co_u32_e32 v132, vcc, s19, v132
	v_add_f32_e32 v0, 1.0, v0
	s_nop 0
	v_addc_co_u32_e32 v133, vcc, 0, v133, vcc
	global_load_dwordx4 v[144:147], v[132:133], off
	global_load_dwordx4 v[140:143], v[134:135], off offset:256
	v_mad_i64_i32 v[132:133], s[6:7], v198, s68, v[196:197]
	v_lshlrev_b64 v[196:197], 11, v[226:227]
	v_rcp_f32_e32 v226, v0
	v_and_b32_e32 v0, 0xffff0000, v160
	v_max_f32_e64 v0, -v0, -v0
	v_min_f32_e32 v0, 0x41f00000, v0
	v_mul_f32_e32 v0, 0x3fb8aa3b, v0
	v_exp_f32_e32 v0, v0
	v_lshl_add_u64 v[132:133], v[132:133], 0, v[194:195]
	v_lshl_add_u64 v[134:135], v[132:133], 0, s[50:51]
	v_add_co_u32_e32 v132, vcc, s19, v132
	v_add_f32_e32 v0, 1.0, v0
	v_rcp_f32_e32 v227, v0
	v_lshlrev_b32_e32 v0, 16, v161
	v_max_f32_e64 v0, -v0, -v0
	v_min_f32_e32 v0, 0x41f00000, v0
	v_mul_f32_e32 v0, 0x3fb8aa3b, v0
	v_exp_f32_e32 v0, v0
	v_pk_mul_f32 v[226:227], v[68:69], v[226:227]
	v_lshl_add_u64 v[196:197], s[56:57], 0, v[196:197]
	v_cvt_pk_bf16_f32 v160, v226, v227
	v_add_f32_e32 v0, 1.0, v0
	v_rcp_f32_e32 v226, v0
	v_and_b32_e32 v0, 0xffff0000, v161
	v_max_f32_e64 v0, -v0, -v0
	v_min_f32_e32 v0, 0x41f00000, v0
	v_mul_f32_e32 v0, 0x3fb8aa3b, v0
	v_exp_f32_e32 v0, v0
	v_addc_co_u32_e32 v133, vcc, 0, v133, vcc
	v_lshl_add_u64 v[196:197], v[196:197], 0, v[194:195]
	v_add_f32_e32 v0, 1.0, v0
	v_rcp_f32_e32 v227, v0
	v_lshlrev_b32_e32 v0, 16, v162
	v_max_f32_e64 v0, -v0, -v0
	v_min_f32_e32 v0, 0x41f00000, v0
	v_mul_f32_e32 v0, 0x3fb8aa3b, v0
	v_exp_f32_e32 v0, v0
	v_pk_mul_f32 v[226:227], v[70:71], v[226:227]
	global_load_dwordx4 v[136:139], v[132:133], off
	s_nop 0
	global_load_dwordx4 v[132:135], v[134:135], off offset:256
	v_cvt_pk_bf16_f32 v161, v226, v227
	v_add_f32_e32 v0, 1.0, v0
	v_rcp_f32_e32 v226, v0
	v_and_b32_e32 v0, 0xffff0000, v162
	v_max_f32_e64 v0, -v0, -v0
	v_min_f32_e32 v0, 0x41f00000, v0
	v_mul_f32_e32 v0, 0x3fb8aa3b, v0
	v_exp_f32_e32 v0, v0
	s_mov_b64 s[6:7], 0
	v_add_f32_e32 v0, 1.0, v0
	v_rcp_f32_e32 v227, v0
	v_lshlrev_b32_e32 v0, 16, v163
	v_max_f32_e64 v0, -v0, -v0
	v_min_f32_e32 v0, 0x41f00000, v0
	v_mul_f32_e32 v0, 0x3fb8aa3b, v0
	v_exp_f32_e32 v0, v0
	v_pk_mul_f32 v[226:227], v[72:73], v[226:227]
	v_add_f32_e32 v0, 1.0, v0
	v_cvt_pk_bf16_f32 v162, v226, v227
	v_rcp_f32_e32 v226, v0
	v_and_b32_e32 v0, 0xffff0000, v163
	v_max_f32_e64 v0, -v0, -v0
	v_min_f32_e32 v0, 0x41f00000, v0
	v_mul_f32_e32 v0, 0x3fb8aa3b, v0
	v_exp_f32_e32 v0, v0
	s_nop 0
	v_add_f32_e32 v0, 1.0, v0
	v_rcp_f32_e32 v227, v0
	v_lshlrev_b32_e32 v0, 16, v156
	v_max_f32_e64 v0, -v0, -v0
	v_min_f32_e32 v0, 0x41f00000, v0
	v_mul_f32_e32 v0, 0x3fb8aa3b, v0
	v_exp_f32_e32 v0, v0
	v_pk_mul_f32 v[226:227], v[74:75], v[226:227]
	v_add_f32_e32 v0, 1.0, v0
	v_cvt_pk_bf16_f32 v163, v226, v227
	global_store_dwordx4 v[196:197], v[160:163], off
	s_nop 1
	v_rcp_f32_e32 v160, v0
	v_and_b32_e32 v0, 0xffff0000, v156
	v_max_f32_e64 v0, -v0, -v0
	v_min_f32_e32 v0, 0x41f00000, v0
	v_mul_f32_e32 v0, 0x3fb8aa3b, v0
	v_exp_f32_e32 v0, v0
	s_nop 0
	v_add_f32_e32 v0, 1.0, v0
	v_rcp_f32_e32 v161, v0
	v_lshlrev_b32_e32 v0, 16, v157
	v_max_f32_e64 v0, -v0, -v0
	v_min_f32_e32 v0, 0x41f00000, v0
	v_mul_f32_e32 v0, 0x3fb8aa3b, v0
	v_exp_f32_e32 v0, v0
	v_pk_mul_f32 v[160:161], v[100:101], v[160:161]
	v_add_f32_e32 v0, 1.0, v0
	v_cvt_pk_bf16_f32 v156, v160, v161
	v_rcp_f32_e32 v160, v0
	v_and_b32_e32 v0, 0xffff0000, v157
	v_max_f32_e64 v0, -v0, -v0
	v_min_f32_e32 v0, 0x41f00000, v0
	v_mul_f32_e32 v0, 0x3fb8aa3b, v0
	v_exp_f32_e32 v0, v0
	s_nop 0
	v_add_f32_e32 v0, 1.0, v0
	v_rcp_f32_e32 v161, v0
	v_lshlrev_b32_e32 v0, 16, v158
	v_max_f32_e64 v0, -v0, -v0
	v_min_f32_e32 v0, 0x41f00000, v0
	v_mul_f32_e32 v0, 0x3fb8aa3b, v0
	v_exp_f32_e32 v0, v0
	v_pk_mul_f32 v[160:161], v[102:103], v[160:161]
	v_add_f32_e32 v0, 1.0, v0
	v_cvt_pk_bf16_f32 v157, v160, v161
	v_rcp_f32_e32 v160, v0
	v_and_b32_e32 v0, 0xffff0000, v158
	v_max_f32_e64 v0, -v0, -v0
	v_min_f32_e32 v0, 0x41f00000, v0
	v_mul_f32_e32 v0, 0x3fb8aa3b, v0
	v_exp_f32_e32 v0, v0
	s_nop 0
	v_add_f32_e32 v0, 1.0, v0
	v_rcp_f32_e32 v161, v0
	v_lshlrev_b32_e32 v0, 16, v159
	v_max_f32_e64 v0, -v0, -v0
	v_min_f32_e32 v0, 0x41f00000, v0
	v_mul_f32_e32 v0, 0x3fb8aa3b, v0
	v_exp_f32_e32 v0, v0
	v_pk_mul_f32 v[160:161], v[104:105], v[160:161]
	v_add_f32_e32 v0, 1.0, v0
	v_cvt_pk_bf16_f32 v158, v160, v161
	v_rcp_f32_e32 v160, v0
	v_and_b32_e32 v0, 0xffff0000, v159
	v_max_f32_e64 v0, -v0, -v0
	v_min_f32_e32 v0, 0x41f00000, v0
	v_mul_f32_e32 v0, 0x3fb8aa3b, v0
	v_exp_f32_e32 v0, v0
	s_nop 0
	v_add_f32_e32 v0, 1.0, v0
	v_rcp_f32_e32 v161, v0
	s_waitcnt vmcnt(0)
; __device__ __forceinline__ unsigned pk2(float lo, float hi) { v2f v = {lo, hi}; return __builtin_bit_cast(unsigned, __builtin_convertvector(v, v2bf)); }
; __device__ __forceinline__ float bflo(unsigned u) { return __uint_as_float(u << 16); }
; __device__ __forceinline__ float bfhi(unsigned u) { return __uint_as_float(u & 0xffff0000u); }
; #define SG(a_, g_) ((a_) * __builtin_amdgcn_rcpf(einv(g_)))
;     static __device__ __forceinline__ float einv(float g) { return 1.f + __expf(fminf(-g, 30.f)); }
;     __device__ __forceinline__ void operator()(f32x4 (&acc)[2][2][4][2], const Unit& u, int wr, int wc, int fr, int fq) const {
;     ...
;             for (int m = 0; m < 4; ++m) { const int row = row0 + ai * 128 + m * 16;
; #pragma unroll
;                 for (int bj = 0; bj < 2; ++bj) { const int col = col0 + bj * 128;
;                     const v4u gw = gq[m][bj];
;                     const f32x4 a0 = acc[ai][bj][m][0], a1 = acc[ai][bj][m][1];
;     ...
;                     v4u w; w.x = pk2(SG(a0[0], bflo(gw.x)), SG(a0[1], bfhi(gw.x))); w.y = pk2(SG(a0[2], bflo(gw.y)), SG(a0[3], bfhi(gw.y)));
;                     w.z = pk2(SG(a1[0], bflo(gw.z)), SG(a1[1], bfhi(gw.z))); w.w = pk2(SG(a1[2], bflo(gw.w)), SG(a1[3], bfhi(gw.w)));
;     ...
;                     *(v4u*)(MB + (size_t)row * 1024 + col) = w; } }
;         }
	v_lshlrev_b32_e32 v0, 16, v152
	v_max_f32_e64 v0, -v0, -v0
	v_min_f32_e32 v0, 0x41f00000, v0
	v_mul_f32_e32 v0, 0x3fb8aa3b, v0
	v_exp_f32_e32 v0, v0
	v_pk_mul_f32 v[160:161], v[106:107], v[160:161]
	v_add_f32_e32 v0, 1.0, v0
	v_cvt_pk_bf16_f32 v159, v160, v161
	global_store_dwordx4 v[196:197], v[156:159], off offset:256
	s_nop 1
	v_rcp_f32_e32 v158, v0
	v_and_b32_e32 v0, 0xffff0000, v152
	v_max_f32_e64 v0, -v0, -v0
	v_min_f32_e32 v0, 0x41f00000, v0
	v_mul_f32_e32 v0, 0x3fb8aa3b, v0
	v_exp_f32_e32 v0, v0
	v_lshlrev_b64 v[156:157], 11, v[202:203]
	v_lshl_add_u64 v[156:157], s[56:57], 0, v[156:157]
	v_lshl_add_u64 v[156:157], v[156:157], 0, v[194:195]
	v_add_f32_e32 v0, 1.0, v0
	v_rcp_f32_e32 v159, v0
	v_lshlrev_b32_e32 v0, 16, v153
	v_max_f32_e64 v0, -v0, -v0
	v_min_f32_e32 v0, 0x41f00000, v0
	v_mul_f32_e32 v0, 0x3fb8aa3b, v0
	v_exp_f32_e32 v0, v0
	v_pk_mul_f32 v[158:159], v[76:77], v[158:159]
	v_add_f32_e32 v0, 1.0, v0
	v_cvt_pk_bf16_f32 v152, v158, v159
	v_rcp_f32_e32 v158, v0
	v_and_b32_e32 v0, 0xffff0000, v153
	v_max_f32_e64 v0, -v0, -v0
	v_min_f32_e32 v0, 0x41f00000, v0
	v_mul_f32_e32 v0, 0x3fb8aa3b, v0
	v_exp_f32_e32 v0, v0
	s_nop 0
	v_add_f32_e32 v0, 1.0, v0
	v_rcp_f32_e32 v159, v0
	v_lshlrev_b32_e32 v0, 16, v154
	v_max_f32_e64 v0, -v0, -v0
	v_min_f32_e32 v0, 0x41f00000, v0
	v_mul_f32_e32 v0, 0x3fb8aa3b, v0
	v_exp_f32_e32 v0, v0
	v_pk_mul_f32 v[158:159], v[78:79], v[158:159]
	v_add_f32_e32 v0, 1.0, v0
	v_cvt_pk_bf16_f32 v153, v158, v159
	v_rcp_f32_e32 v158, v0
	v_and_b32_e32 v0, 0xffff0000, v154
	v_max_f32_e64 v0, -v0, -v0
	v_min_f32_e32 v0, 0x41f00000, v0
	v_mul_f32_e32 v0, 0x3fb8aa3b, v0
	v_exp_f32_e32 v0, v0
	s_nop 0
	v_add_f32_e32 v0, 1.0, v0
	v_rcp_f32_e32 v159, v0
	v_lshlrev_b32_e32 v0, 16, v155
	v_max_f32_e64 v0, -v0, -v0
	v_min_f32_e32 v0, 0x41f00000, v0
	v_mul_f32_e32 v0, 0x3fb8aa3b, v0
	v_exp_f32_e32 v0, v0
	v_pk_mul_f32 v[158:159], v[80:81], v[158:159]
	v_add_f32_e32 v0, 1.0, v0
	v_cvt_pk_bf16_f32 v154, v158, v159
	v_rcp_f32_e32 v158, v0
	v_and_b32_e32 v0, 0xffff0000, v155
	v_max_f32_e64 v0, -v0, -v0
	v_min_f32_e32 v0, 0x41f00000, v0
	v_mul_f32_e32 v0, 0x3fb8aa3b, v0
	v_exp_f32_e32 v0, v0
	s_nop 0
	v_add_f32_e32 v0, 1.0, v0
	v_rcp_f32_e32 v159, v0
	v_lshlrev_b32_e32 v0, 16, v148
	v_max_f32_e64 v0, -v0, -v0
	v_min_f32_e32 v0, 0x41f00000, v0
	v_mul_f32_e32 v0, 0x3fb8aa3b, v0
	v_exp_f32_e32 v0, v0
	v_pk_mul_f32 v[158:159], v[82:83], v[158:159]
	v_add_f32_e32 v0, 1.0, v0
	v_cvt_pk_bf16_f32 v155, v158, v159
	global_store_dwordx4 v[156:157], v[152:155], off
	s_nop 1
	v_rcp_f32_e32 v152, v0
	v_and_b32_e32 v0, 0xffff0000, v148
	v_max_f32_e64 v0, -v0, -v0
	v_min_f32_e32 v0, 0x41f00000, v0
	v_mul_f32_e32 v0, 0x3fb8aa3b, v0
	v_exp_f32_e32 v0, v0
	s_nop 0
	v_add_f32_e32 v0, 1.0, v0
	v_rcp_f32_e32 v153, v0
	v_lshlrev_b32_e32 v0, 16, v149
	v_max_f32_e64 v0, -v0, -v0
	v_min_f32_e32 v0, 0x41f00000, v0
	v_mul_f32_e32 v0, 0x3fb8aa3b, v0
	v_exp_f32_e32 v0, v0
	v_pk_mul_f32 v[152:153], v[108:109], v[152:153]
	v_add_f32_e32 v0, 1.0, v0
	v_cvt_pk_bf16_f32 v148, v152, v153
	v_rcp_f32_e32 v152, v0
	v_and_b32_e32 v0, 0xffff0000, v149
	v_max_f32_e64 v0, -v0, -v0
	v_min_f32_e32 v0, 0x41f00000, v0
	v_mul_f32_e32 v0, 0x3fb8aa3b, v0
	v_exp_f32_e32 v0, v0
	s_nop 0
	v_add_f32_e32 v0, 1.0, v0
	v_rcp_f32_e32 v153, v0
	v_lshlrev_b32_e32 v0, 16, v150
	v_max_f32_e64 v0, -v0, -v0
	v_min_f32_e32 v0, 0x41f00000, v0
	v_mul_f32_e32 v0, 0x3fb8aa3b, v0
	v_exp_f32_e32 v0, v0
	v_pk_mul_f32 v[152:153], v[110:111], v[152:153]
	v_add_f32_e32 v0, 1.0, v0
	v_cvt_pk_bf16_f32 v149, v152, v153
	v_rcp_f32_e32 v152, v0
	v_and_b32_e32 v0, 0xffff0000, v150
	v_max_f32_e64 v0, -v0, -v0
	v_min_f32_e32 v0, 0x41f00000, v0
	v_mul_f32_e32 v0, 0x3fb8aa3b, v0
	v_exp_f32_e32 v0, v0
	s_nop 0
	v_add_f32_e32 v0, 1.0, v0
	v_rcp_f32_e32 v153, v0
	v_lshlrev_b32_e32 v0, 16, v151
	v_max_f32_e64 v0, -v0, -v0
	v_min_f32_e32 v0, 0x41f00000, v0
	v_mul_f32_e32 v0, 0x3fb8aa3b, v0
	v_exp_f32_e32 v0, v0
	v_pk_mul_f32 v[152:153], v[112:113], v[152:153]
	v_add_f32_e32 v0, 1.0, v0
	v_cvt_pk_bf16_f32 v150, v152, v153
	v_rcp_f32_e32 v152, v0
	v_and_b32_e32 v0, 0xffff0000, v151
	v_max_f32_e64 v0, -v0, -v0
	v_min_f32_e32 v0, 0x41f00000, v0
	v_mul_f32_e32 v0, 0x3fb8aa3b, v0
	v_exp_f32_e32 v0, v0
	s_nop 0
	v_add_f32_e32 v0, 1.0, v0
	v_rcp_f32_e32 v153, v0
	v_lshlrev_b32_e32 v0, 16, v144
	v_max_f32_e64 v0, -v0, -v0
	v_min_f32_e32 v0, 0x41f00000, v0
	v_mul_f32_e32 v0, 0x3fb8aa3b, v0
	v_exp_f32_e32 v0, v0
	v_pk_mul_f32 v[152:153], v[114:115], v[152:153]
	v_add_f32_e32 v0, 1.0, v0
	v_cvt_pk_bf16_f32 v151, v152, v153
	global_store_dwordx4 v[156:157], v[148:151], off offset:256
	s_nop 1
	v_rcp_f32_e32 v150, v0
	v_and_b32_e32 v0, 0xffff0000, v144
	v_max_f32_e64 v0, -v0, -v0
	v_min_f32_e32 v0, 0x41f00000, v0
	v_mul_f32_e32 v0, 0x3fb8aa3b, v0
	v_exp_f32_e32 v0, v0
	v_lshlrev_b64 v[148:149], 11, v[200:201]
	v_lshl_add_u64 v[148:149], s[56:57], 0, v[148:149]
	v_lshl_add_u64 v[148:149], v[148:149], 0, v[194:195]
	v_add_f32_e32 v0, 1.0, v0
	v_rcp_f32_e32 v151, v0
	v_lshlrev_b32_e32 v0, 16, v145
	v_max_f32_e64 v0, -v0, -v0
	v_min_f32_e32 v0, 0x41f00000, v0
	v_mul_f32_e32 v0, 0x3fb8aa3b, v0
	v_exp_f32_e32 v0, v0
	v_pk_mul_f32 v[150:151], v[84:85], v[150:151]
	v_add_f32_e32 v0, 1.0, v0
	v_cvt_pk_bf16_f32 v144, v150, v151
	v_rcp_f32_e32 v150, v0
	v_and_b32_e32 v0, 0xffff0000, v145
	v_max_f32_e64 v0, -v0, -v0
	v_min_f32_e32 v0, 0x41f00000, v0
	v_mul_f32_e32 v0, 0x3fb8aa3b, v0
	v_exp_f32_e32 v0, v0
	s_nop 0
	v_add_f32_e32 v0, 1.0, v0
	v_rcp_f32_e32 v151, v0
	v_lshlrev_b32_e32 v0, 16, v146
	v_max_f32_e64 v0, -v0, -v0
	v_min_f32_e32 v0, 0x41f00000, v0
	v_mul_f32_e32 v0, 0x3fb8aa3b, v0
	v_exp_f32_e32 v0, v0
; __device__ __forceinline__ unsigned pk2(float lo, float hi) { v2f v = {lo, hi}; return __builtin_bit_cast(unsigned, __builtin_convertvector(v, v2bf)); }
; __device__ __forceinline__ float bflo(unsigned u) { return __uint_as_float(u << 16); }
; __device__ __forceinline__ float bfhi(unsigned u) { return __uint_as_float(u & 0xffff0000u); }
; #define SG(a_, g_) ((a_) * __builtin_amdgcn_rcpf(einv(g_)))
;     static __device__ __forceinline__ float einv(float g) { return 1.f + __expf(fminf(-g, 30.f)); }
;     __device__ __forceinline__ void operator()(f32x4 (&acc)[2][2][4][2], const Unit& u, int wr, int wc, int fr, int fq) const {
;     ...
;             for (int m = 0; m < 4; ++m) { const int row = row0 + ai * 128 + m * 16;
; #pragma unroll
;                 for (int bj = 0; bj < 2; ++bj) { const int col = col0 + bj * 128;
;                     const v4u gw = gq[m][bj];
;                     const f32x4 a0 = acc[ai][bj][m][0], a1 = acc[ai][bj][m][1];
;     ...
;                     v4u w; w.x = pk2(SG(a0[0], bflo(gw.x)), SG(a0[1], bfhi(gw.x))); w.y = pk2(SG(a0[2], bflo(gw.y)), SG(a0[3], bfhi(gw.y)));
;                     w.z = pk2(SG(a1[0], bflo(gw.z)), SG(a1[1], bfhi(gw.z))); w.w = pk2(SG(a1[2], bflo(gw.w)), SG(a1[3], bfhi(gw.w)));
;     ...
;                     *(v4u*)(MB + (size_t)row * 1024 + col) = w; } }
;         }
	v_pk_mul_f32 v[150:151], v[86:87], v[150:151]
	v_add_f32_e32 v0, 1.0, v0
	v_cvt_pk_bf16_f32 v145, v150, v151
	v_rcp_f32_e32 v150, v0
	v_and_b32_e32 v0, 0xffff0000, v146
	v_max_f32_e64 v0, -v0, -v0
	v_min_f32_e32 v0, 0x41f00000, v0
	v_mul_f32_e32 v0, 0x3fb8aa3b, v0
	v_exp_f32_e32 v0, v0
	s_nop 0
	v_add_f32_e32 v0, 1.0, v0
	v_rcp_f32_e32 v151, v0
	v_lshlrev_b32_e32 v0, 16, v147
	v_max_f32_e64 v0, -v0, -v0
	v_min_f32_e32 v0, 0x41f00000, v0
	v_mul_f32_e32 v0, 0x3fb8aa3b, v0
	v_exp_f32_e32 v0, v0
	v_pk_mul_f32 v[150:151], v[88:89], v[150:151]
	v_add_f32_e32 v0, 1.0, v0
	v_cvt_pk_bf16_f32 v146, v150, v151
	v_rcp_f32_e32 v150, v0
	v_and_b32_e32 v0, 0xffff0000, v147
	v_max_f32_e64 v0, -v0, -v0
	v_min_f32_e32 v0, 0x41f00000, v0
	v_mul_f32_e32 v0, 0x3fb8aa3b, v0
	v_exp_f32_e32 v0, v0
	s_nop 0
	v_add_f32_e32 v0, 1.0, v0
	v_rcp_f32_e32 v151, v0
	v_lshlrev_b32_e32 v0, 16, v140
	v_max_f32_e64 v0, -v0, -v0
	v_min_f32_e32 v0, 0x41f00000, v0
	v_mul_f32_e32 v0, 0x3fb8aa3b, v0
	v_exp_f32_e32 v0, v0
	v_pk_mul_f32 v[150:151], v[90:91], v[150:151]
	v_add_f32_e32 v0, 1.0, v0
	v_cvt_pk_bf16_f32 v147, v150, v151
	global_store_dwordx4 v[148:149], v[144:147], off
	s_nop 1
	v_rcp_f32_e32 v144, v0
	v_and_b32_e32 v0, 0xffff0000, v140
	v_max_f32_e64 v0, -v0, -v0
	v_min_f32_e32 v0, 0x41f00000, v0
	v_mul_f32_e32 v0, 0x3fb8aa3b, v0
	v_exp_f32_e32 v0, v0
	s_nop 0
	v_add_f32_e32 v0, 1.0, v0
	v_rcp_f32_e32 v145, v0
	v_lshlrev_b32_e32 v0, 16, v141
	v_max_f32_e64 v0, -v0, -v0
	v_min_f32_e32 v0, 0x41f00000, v0
	v_mul_f32_e32 v0, 0x3fb8aa3b, v0
	v_exp_f32_e32 v0, v0
	v_pk_mul_f32 v[144:145], v[116:117], v[144:145]
	v_add_f32_e32 v0, 1.0, v0
	v_cvt_pk_bf16_f32 v140, v144, v145
	v_rcp_f32_e32 v144, v0
	v_and_b32_e32 v0, 0xffff0000, v141
	v_max_f32_e64 v0, -v0, -v0
	v_min_f32_e32 v0, 0x41f00000, v0
	v_mul_f32_e32 v0, 0x3fb8aa3b, v0
	v_exp_f32_e32 v0, v0
	s_nop 0
	v_add_f32_e32 v0, 1.0, v0
	v_rcp_f32_e32 v145, v0
	v_lshlrev_b32_e32 v0, 16, v142
	v_max_f32_e64 v0, -v0, -v0
	v_min_f32_e32 v0, 0x41f00000, v0
	v_mul_f32_e32 v0, 0x3fb8aa3b, v0
	v_exp_f32_e32 v0, v0
	v_pk_mul_f32 v[144:145], v[118:119], v[144:145]
	v_add_f32_e32 v0, 1.0, v0
	v_cvt_pk_bf16_f32 v141, v144, v145
	v_rcp_f32_e32 v144, v0
	v_and_b32_e32 v0, 0xffff0000, v142
	v_max_f32_e64 v0, -v0, -v0
	v_min_f32_e32 v0, 0x41f00000, v0
	v_mul_f32_e32 v0, 0x3fb8aa3b, v0
	v_exp_f32_e32 v0, v0
	s_nop 0
	v_add_f32_e32 v0, 1.0, v0
	v_rcp_f32_e32 v145, v0
	v_lshlrev_b32_e32 v0, 16, v143
	v_max_f32_e64 v0, -v0, -v0
	v_min_f32_e32 v0, 0x41f00000, v0
	v_mul_f32_e32 v0, 0x3fb8aa3b, v0
	v_exp_f32_e32 v0, v0
	v_pk_mul_f32 v[144:145], v[120:121], v[144:145]
	v_add_f32_e32 v0, 1.0, v0
	v_cvt_pk_bf16_f32 v142, v144, v145
	v_rcp_f32_e32 v144, v0
	v_and_b32_e32 v0, 0xffff0000, v143
	v_max_f32_e64 v0, -v0, -v0
	v_min_f32_e32 v0, 0x41f00000, v0
	v_mul_f32_e32 v0, 0x3fb8aa3b, v0
	v_exp_f32_e32 v0, v0
	s_nop 0
	v_add_f32_e32 v0, 1.0, v0
	v_rcp_f32_e32 v145, v0
	v_lshlrev_b32_e32 v0, 16, v136
	v_max_f32_e64 v0, -v0, -v0
	v_min_f32_e32 v0, 0x41f00000, v0
	v_mul_f32_e32 v0, 0x3fb8aa3b, v0
	v_exp_f32_e32 v0, v0
	v_pk_mul_f32 v[144:145], v[122:123], v[144:145]
	v_add_f32_e32 v0, 1.0, v0
	v_cvt_pk_bf16_f32 v143, v144, v145
	global_store_dwordx4 v[148:149], v[140:143], off offset:256
	s_nop 1
	v_rcp_f32_e32 v142, v0
	v_and_b32_e32 v0, 0xffff0000, v136
	v_max_f32_e64 v0, -v0, -v0
	v_min_f32_e32 v0, 0x41f00000, v0
	v_mul_f32_e32 v0, 0x3fb8aa3b, v0
	v_exp_f32_e32 v0, v0
	v_lshlrev_b64 v[140:141], 11, v[198:199]
	v_lshl_add_u64 v[140:141], s[56:57], 0, v[140:141]
	v_lshl_add_u64 v[140:141], v[140:141], 0, v[194:195]
	v_add_f32_e32 v0, 1.0, v0
	v_rcp_f32_e32 v143, v0
	v_lshlrev_b32_e32 v0, 16, v137
	v_max_f32_e64 v0, -v0, -v0
; __device__ __forceinline__ unsigned pk2(float lo, float hi) { v2f v = {lo, hi}; return __builtin_bit_cast(unsigned, __builtin_convertvector(v, v2bf)); }
; __device__ __forceinline__ float bflo(unsigned u) { return __uint_as_float(u << 16); }
; __device__ __forceinline__ float bfhi(unsigned u) { return __uint_as_float(u & 0xffff0000u); }
; #define SG(a_, g_) ((a_) * __builtin_amdgcn_rcpf(einv(g_)))
;     static __device__ __forceinline__ float einv(float g) { return 1.f + __expf(fminf(-g, 30.f)); }
;     __device__ __forceinline__ void operator()(f32x4 (&acc)[2][2][4][2], const Unit& u, int wr, int wc, int fr, int fq) const {
;     ...
;             for (int m = 0; m < 4; ++m) { const int row = row0 + ai * 128 + m * 16;
; #pragma unroll
;                 for (int bj = 0; bj < 2; ++bj) { const int col = col0 + bj * 128;
;                     const v4u gw = gq[m][bj];
;                     const f32x4 a0 = acc[ai][bj][m][0], a1 = acc[ai][bj][m][1];
;     ...
;                     v4u w; w.x = pk2(SG(a0[0], bflo(gw.x)), SG(a0[1], bfhi(gw.x))); w.y = pk2(SG(a0[2], bflo(gw.y)), SG(a0[3], bfhi(gw.y)));
;                     w.z = pk2(SG(a1[0], bflo(gw.z)), SG(a1[1], bfhi(gw.z))); w.w = pk2(SG(a1[2], bflo(gw.w)), SG(a1[3], bfhi(gw.w)));
;     ...
;                     *(v4u*)(MB + (size_t)row * 1024 + col) = w; } }
;         }
	v_min_f32_e32 v0, 0x41f00000, v0
	v_mul_f32_e32 v0, 0x3fb8aa3b, v0
	v_exp_f32_e32 v0, v0
	v_pk_mul_f32 v[142:143], v[92:93], v[142:143]
	v_add_f32_e32 v0, 1.0, v0
	v_cvt_pk_bf16_f32 v136, v142, v143
	v_rcp_f32_e32 v142, v0
	v_and_b32_e32 v0, 0xffff0000, v137
	v_max_f32_e64 v0, -v0, -v0
	v_min_f32_e32 v0, 0x41f00000, v0
	v_mul_f32_e32 v0, 0x3fb8aa3b, v0
	v_exp_f32_e32 v0, v0
	s_nop 0
	v_add_f32_e32 v0, 1.0, v0
	v_rcp_f32_e32 v143, v0
	v_lshlrev_b32_e32 v0, 16, v138
	v_max_f32_e64 v0, -v0, -v0
	v_min_f32_e32 v0, 0x41f00000, v0
	v_mul_f32_e32 v0, 0x3fb8aa3b, v0
	v_exp_f32_e32 v0, v0
	v_pk_mul_f32 v[142:143], v[94:95], v[142:143]
	v_add_f32_e32 v0, 1.0, v0
	v_cvt_pk_bf16_f32 v137, v142, v143
	v_rcp_f32_e32 v142, v0
	v_and_b32_e32 v0, 0xffff0000, v138
	v_max_f32_e64 v0, -v0, -v0
	v_min_f32_e32 v0, 0x41f00000, v0
	v_mul_f32_e32 v0, 0x3fb8aa3b, v0
	v_exp_f32_e32 v0, v0
	s_nop 0
	v_add_f32_e32 v0, 1.0, v0
	v_rcp_f32_e32 v143, v0
	v_lshlrev_b32_e32 v0, 16, v139
	v_max_f32_e64 v0, -v0, -v0
	v_min_f32_e32 v0, 0x41f00000, v0
	v_mul_f32_e32 v0, 0x3fb8aa3b, v0
	v_exp_f32_e32 v0, v0
	v_pk_mul_f32 v[142:143], v[96:97], v[142:143]
	v_add_f32_e32 v0, 1.0, v0
	v_cvt_pk_bf16_f32 v138, v142, v143
	v_rcp_f32_e32 v142, v0
	v_and_b32_e32 v0, 0xffff0000, v139
	v_max_f32_e64 v0, -v0, -v0
	v_min_f32_e32 v0, 0x41f00000, v0
	v_mul_f32_e32 v0, 0x3fb8aa3b, v0
	v_exp_f32_e32 v0, v0
	s_nop 0
	v_add_f32_e32 v0, 1.0, v0
	v_rcp_f32_e32 v143, v0
	v_lshlrev_b32_e32 v0, 16, v132
	v_max_f32_e64 v0, -v0, -v0
	v_min_f32_e32 v0, 0x41f00000, v0
	v_mul_f32_e32 v0, 0x3fb8aa3b, v0
	v_exp_f32_e32 v0, v0
	v_pk_mul_f32 v[142:143], v[98:99], v[142:143]
	v_add_f32_e32 v0, 1.0, v0
	v_cvt_pk_bf16_f32 v139, v142, v143
	global_store_dwordx4 v[140:141], v[136:139], off
	s_nop 1
	v_rcp_f32_e32 v136, v0
	v_and_b32_e32 v0, 0xffff0000, v132
	v_max_f32_e64 v0, -v0, -v0
	v_min_f32_e32 v0, 0x41f00000, v0
	v_mul_f32_e32 v0, 0x3fb8aa3b, v0
	v_exp_f32_e32 v0, v0
	s_nop 0
	v_add_f32_e32 v0, 1.0, v0
	v_rcp_f32_e32 v137, v0
	v_lshlrev_b32_e32 v0, 16, v133
	v_max_f32_e64 v0, -v0, -v0
	v_min_f32_e32 v0, 0x41f00000, v0
	v_mul_f32_e32 v0, 0x3fb8aa3b, v0
	v_exp_f32_e32 v0, v0
	v_pk_mul_f32 v[136:137], v[124:125], v[136:137]
	v_add_f32_e32 v0, 1.0, v0
	v_cvt_pk_bf16_f32 v132, v136, v137
	v_rcp_f32_e32 v136, v0
	v_and_b32_e32 v0, 0xffff0000, v133
	v_max_f32_e64 v0, -v0, -v0
	v_min_f32_e32 v0, 0x41f00000, v0
	v_mul_f32_e32 v0, 0x3fb8aa3b, v0
	v_exp_f32_e32 v0, v0
	s_nop 0
	v_add_f32_e32 v0, 1.0, v0
	v_rcp_f32_e32 v137, v0
	v_lshlrev_b32_e32 v0, 16, v134
	v_max_f32_e64 v0, -v0, -v0
	v_min_f32_e32 v0, 0x41f00000, v0
	v_mul_f32_e32 v0, 0x3fb8aa3b, v0
	v_exp_f32_e32 v0, v0
	v_pk_mul_f32 v[136:137], v[126:127], v[136:137]
	v_add_f32_e32 v0, 1.0, v0
	v_cvt_pk_bf16_f32 v133, v136, v137
	v_rcp_f32_e32 v136, v0
	v_and_b32_e32 v0, 0xffff0000, v134
	v_max_f32_e64 v0, -v0, -v0
	v_min_f32_e32 v0, 0x41f00000, v0
	v_mul_f32_e32 v0, 0x3fb8aa3b, v0
	v_exp_f32_e32 v0, v0
	s_nop 0
	v_add_f32_e32 v0, 1.0, v0
	v_rcp_f32_e32 v137, v0
	v_lshlrev_b32_e32 v0, 16, v135
	v_max_f32_e64 v0, -v0, -v0
	v_min_f32_e32 v0, 0x41f00000, v0
	v_mul_f32_e32 v0, 0x3fb8aa3b, v0
	v_exp_f32_e32 v0, v0
	v_pk_mul_f32 v[136:137], v[128:129], v[136:137]
	v_add_f32_e32 v0, 1.0, v0
	v_cvt_pk_bf16_f32 v134, v136, v137
	v_rcp_f32_e32 v136, v0
	v_and_b32_e32 v0, 0xffff0000, v135
	v_max_f32_e64 v0, -v0, -v0
	v_min_f32_e32 v0, 0x41f00000, v0
	v_mul_f32_e32 v0, 0x3fb8aa3b, v0
	v_exp_f32_e32 v0, v0
	s_nop 0
	v_add_f32_e32 v0, 1.0, v0
	v_rcp_f32_e32 v137, v0
	s_nop 0
	v_pk_mul_f32 v[136:137], v[130:131], v[136:137]
	s_nop 0
	v_cvt_pk_bf16_f32 v135, v136, v137
	global_store_dwordx4 v[140:141], v[132:135], off offset:256

; #define PG8_STAGE(bufoff, gbase, voff) do { _Pragma("unroll") for (int _i = 0; _i < 2; ++_i) \
;         __builtin_amdgcn_global_load_lds((const unsigned*)((const char*)(gbase) + (voff)[_i]), (PG8_LAS unsigned*)(lds + (bufoff) + ldsw + _i * 8192), 16, 0, 0); } while (0)
; #define PG8_LDA(dst, b, h) do { _Pragma("unroll") for (int m = 0; m < 4; ++m) _Pragma("unroll") for (int k = 0; k < 2; ++k) dst[m][k] = *(const PG8_LAS bf16x8*)(lds + PG8_SA(b, h) + aoff + m * 2048 + k * 1024); } while (0)
; #define PG8_LDB(dst, b, h) do { _Pragma("unroll") for (int n = 0; n < 2; ++n) _Pragma("unroll") for (int k = 0; k < 2; ++k) dst[n][k] = *(const PG8_LAS bf16x8*)(lds + PG8_SB(b, h) + boff + n * 2048 + k * 1024); } while (0)
; #define PG8_MMA(ai, bj, At, Bt) do { __builtin_amdgcn_s_setprio(1); _Pragma("unroll") for (int m = 0; m < 4; ++m) _Pragma("unroll") for (int n = 0; n < 2; ++n) _Pragma("unroll") for (int k = 0; k < 2; ++k) \
;         acc[ai][bj][m][n] = __builtin_amdgcn_mfma_f32_16x16x32_bf16(Bt[n][k], At[m][k], acc[ai][bj][m][n], 0, 0, 0); __builtin_amdgcn_s_setprio(0); } while (0)
; #define PG8_WAIT_L(n) asm volatile("s_waitcnt lgkmcnt(" #n ")" ::: "memory")
; #define PG8_BAR __builtin_amdgcn_s_barrier()
; #define PG8_SCHED __builtin_amdgcn_sched_barrier(0)
; template <class Epi, class Sched>
; __device__ __forceinline__ void gemm_phase(PG8_LAS unsigned char* lds, const Gemm g, const Sched& S, const Epi& E) {
;     ...
;             PG8_LDB(B0, 0, 0); PG8_SCHED; PG8_LDA(At, 0, 0); PG8_STAGE(PG8_SA(1, 1), a1 + hstep, voffA);
;             PG8_WAIT_L(8); PG8_BAR; PG8_WAIT_L(0); PG8_MMA(0, 0, At, B0); PG8_BAR; PG8_SCHED;
;             PG8_LDB(B1, 0, 1); PG8_STAGE(PG8_SB(0, 0), b2, voffB);
;             PG8_BAR; PG8_WAIT_L(0); PG8_MMA(0, 1, At, B1); PG8_BAR;
;             PG8_LDA(At, 0, 1); PG8_STAGE(PG8_SA(0, 0), a2, voffA);
;             PG8_BAR; PG8_WAIT_L(0); PG8_MMA(1, 0, At, B0); PG8_BAR; PG8_SCHED;
.LBB0_548:
	s_add_u32 s10, vcc_lo, 0xfffc0080
	s_addc_u32 s11, vcc_hi, -1
	s_add_i32 s84, 0, 0x10000
	v_add_u32_e32 v156, s84, v141
	ds_read_b128 v[144:147], v156
	ds_read_b128 v[148:151], v156 offset:1024
	ds_read_b128 v[152:155], v156 offset:2048
	ds_read_b128 v[156:159], v156 offset:3072
	s_cmp_eq_u32 s83, 12
	s_cselect_b32 s51, s21, s11
	s_cselect_b32 s50, s79, s10
	s_cselect_b32 s11, s19, s82
	s_cselect_b32 s10, s80, s81
	v_lshl_add_u64 v[202:203], vcc, 0, v[136:137]
	s_add_i32 m0, s70, 0xc000
	ds_read_b128 v[160:163], v143
	ds_read_b128 v[174:177], v143 offset:1024
	ds_read_b128 v[178:181], v143 offset:2048
	ds_read_b128 v[182:185], v143 offset:3072
	ds_read_b128 v[186:189], v143 offset:4096
	ds_read_b128 v[190:193], v143 offset:5120
	ds_read_b128 v[194:197], v143 offset:6144
	ds_read_b128 v[198:201], v143 offset:7168
	global_load_lds_dwordx4 v[202:203], off
	v_lshl_add_u64 v[202:203], vcc, 0, v[138:139]
	s_add_i32 m0, s70, 0xe000
	s_nop 0
	global_load_lds_dwordx4 v[202:203], off
	s_waitcnt lgkmcnt(8)
	s_setprio 1
	s_barrier
	s_waitcnt lgkmcnt(0)
	v_mfma_f32_16x16x32_bf16 v[6:9], v[144:147], v[160:163], v[6:9]
	v_mfma_f32_16x16x32_bf16 v[2:5], v[152:155], v[160:163], v[2:5]
	v_mfma_f32_16x16x32_bf16 v[22:25], v[144:147], v[178:181], v[22:25]
	v_mfma_f32_16x16x32_bf16 v[18:21], v[152:155], v[178:181], v[18:21]
	v_mfma_f32_16x16x32_bf16 v[38:41], v[144:147], v[186:189], v[38:41]
	v_mfma_f32_16x16x32_bf16 v[34:37], v[152:155], v[186:189], v[34:37]
	v_mfma_f32_16x16x32_bf16 v[54:57], v[144:147], v[194:197], v[54:57]
	v_mfma_f32_16x16x32_bf16 v[50:53], v[152:155], v[194:197], v[50:53]
	v_mfma_f32_16x16x32_bf16 v[6:9], v[148:151], v[174:177], v[6:9]
	v_mfma_f32_16x16x32_bf16 v[2:5], v[156:159], v[174:177], v[2:5]
	v_mfma_f32_16x16x32_bf16 v[22:25], v[148:151], v[182:185], v[22:25]
	v_mfma_f32_16x16x32_bf16 v[18:21], v[156:159], v[182:185], v[18:21]
	v_mfma_f32_16x16x32_bf16 v[38:41], v[148:151], v[190:193], v[38:41]
	v_mfma_f32_16x16x32_bf16 v[34:37], v[156:159], v[190:193], v[34:37]
	v_mfma_f32_16x16x32_bf16 v[54:57], v[148:151], v[198:201], v[54:57]
	v_mfma_f32_16x16x32_bf16 v[50:53], v[156:159], v[198:201], v[50:53]
	s_setprio 0
	s_barrier
	s_add_i32 s86, 0, 0x14000
	v_add_u32_e32 v202, s86, v141
	s_add_i32 s84, s84, s53
	ds_read_b128 v[222:225], v202
	ds_read_b128 v[226:229], v202 offset:1024
	ds_read_b128 v[230:233], v202 offset:2048
	ds_read_b128 v[234:237], v202 offset:3072
	v_lshl_add_u64 v[202:203], s[10:11], 0, v[0:1]
	s_mov_b32 m0, s84
	v_lshl_add_u64 v[238:239], s[10:11], 0, v[130:131]
	global_load_lds_dwordx4 v[202:203], off
	s_add_i32 m0, s84, 0x2000
	s_nop 0
	global_load_lds_dwordx4 v[238:239], off
	s_setprio 1
	s_barrier
	s_waitcnt lgkmcnt(0)
	v_mfma_f32_16x16x32_bf16 v[14:17], v[222:225], v[160:163], v[14:17]
	v_mfma_f32_16x16x32_bf16 v[10:13], v[230:233], v[160:163], v[10:13]
	v_mfma_f32_16x16x32_bf16 v[30:33], v[222:225], v[178:181], v[30:33]
	v_mfma_f32_16x16x32_bf16 v[26:29], v[230:233], v[178:181], v[26:29]
	v_mfma_f32_16x16x32_bf16 v[46:49], v[222:225], v[186:189], v[46:49]
	v_mfma_f32_16x16x32_bf16 v[42:45], v[230:233], v[186:189], v[42:45]
	v_mfma_f32_16x16x32_bf16 v[62:65], v[222:225], v[194:197], v[62:65]
	v_mfma_f32_16x16x32_bf16 v[58:61], v[230:233], v[194:197], v[58:61]
	v_mfma_f32_16x16x32_bf16 v[14:17], v[226:229], v[174:177], v[14:17]
	v_mfma_f32_16x16x32_bf16 v[10:13], v[234:237], v[174:177], v[10:13]
	v_mfma_f32_16x16x32_bf16 v[30:33], v[226:229], v[182:185], v[30:33]
	v_mfma_f32_16x16x32_bf16 v[26:29], v[234:237], v[182:185], v[26:29]
	v_mfma_f32_16x16x32_bf16 v[46:49], v[226:229], v[190:193], v[46:49]
	v_mfma_f32_16x16x32_bf16 v[42:45], v[234:237], v[190:193], v[42:45]
	v_mfma_f32_16x16x32_bf16 v[62:65], v[226:229], v[198:201], v[62:65]
	v_mfma_f32_16x16x32_bf16 v[58:61], v[234:237], v[198:201], v[58:61]
	s_setprio 0
	s_barrier
	s_mov_b32 m0, s70
	v_lshl_add_u64 v[240:241], s[50:51], 0, v[134:135]
	ds_read_b128 v[160:163], v143 offset:16384
	ds_read_b128 v[174:177], v143 offset:17408
	ds_read_b128 v[178:181], v143 offset:18432
	ds_read_b128 v[182:185], v143 offset:19456
	ds_read_b128 v[186:189], v143 offset:20480
	ds_read_b128 v[190:193], v143 offset:21504
	ds_read_b128 v[194:197], v143 offset:22528
	ds_read_b128 v[198:201], v143 offset:23552
	global_load_lds_dwordx4 v[240:241], off
	v_lshl_add_u64 v[242:243], s[50:51], 0, v[132:133]
	s_mov_b32 m0, s71
	s_nop 0
	global_load_lds_dwordx4 v[242:243], off
	s_setprio 1
	s_barrier
	s_waitcnt lgkmcnt(0)
	v_mfma_f32_16x16x32_bf16 v[66:69], v[144:147], v[160:163], v[66:69]
	v_mfma_f32_16x16x32_bf16 v[70:73], v[152:155], v[160:163], v[70:73]
	v_mfma_f32_16x16x32_bf16 v[82:85], v[144:147], v[178:181], v[82:85]
	v_mfma_f32_16x16x32_bf16 v[86:89], v[152:155], v[178:181], v[86:89]
	v_mfma_f32_16x16x32_bf16 v[98:101], v[144:147], v[186:189], v[98:101]
	v_mfma_f32_16x16x32_bf16 v[102:105], v[152:155], v[186:189], v[102:105]
	v_mfma_f32_16x16x32_bf16 v[114:117], v[144:147], v[194:197], v[114:117]
	v_mfma_f32_16x16x32_bf16 v[118:121], v[152:155], v[194:197], v[118:121]
	v_mfma_f32_16x16x32_bf16 v[66:69], v[148:151], v[174:177], v[66:69]
	v_mfma_f32_16x16x32_bf16 v[70:73], v[156:159], v[174:177], v[70:73]
	v_mfma_f32_16x16x32_bf16 v[82:85], v[148:151], v[182:185], v[82:85]
	v_mfma_f32_16x16x32_bf16 v[86:89], v[156:159], v[182:185], v[86:89]
	v_mfma_f32_16x16x32_bf16 v[98:101], v[148:151], v[190:193], v[98:101]
	v_mfma_f32_16x16x32_bf16 v[102:105], v[156:159], v[190:193], v[102:105]
	v_mfma_f32_16x16x32_bf16 v[114:117], v[148:151], v[198:201], v[114:117]
	v_mfma_f32_16x16x32_bf16 v[118:121], v[156:159], v[198:201], v[118:121]
	s_setprio 0
	s_barrier
; #define PG8_STAGE(bufoff, gbase, voff) do { _Pragma("unroll") for (int _i = 0; _i < 2; ++_i) \
;         __builtin_amdgcn_global_load_lds((const unsigned*)((const char*)(gbase) + (voff)[_i]), (PG8_LAS unsigned*)(lds + (bufoff) + ldsw + _i * 8192), 16, 0, 0); } while (0)
; #define PG8_LDA(dst, b, h) do { _Pragma("unroll") for (int m = 0; m < 4; ++m) _Pragma("unroll") for (int k = 0; k < 2; ++k) dst[m][k] = *(const PG8_LAS bf16x8*)(lds + PG8_SA(b, h) + aoff + m * 2048 + k * 1024); } while (0)
; #define PG8_LDB(dst, b, h) do { _Pragma("unroll") for (int n = 0; n < 2; ++n) _Pragma("unroll") for (int k = 0; k < 2; ++k) dst[n][k] = *(const PG8_LAS bf16x8*)(lds + PG8_SB(b, h) + boff + n * 2048 + k * 1024); } while (0)
; #define PG8_MMA(ai, bj, At, Bt) do { __builtin_amdgcn_s_setprio(1); _Pragma("unroll") for (int m = 0; m < 4; ++m) _Pragma("unroll") for (int n = 0; n < 2; ++n) _Pragma("unroll") for (int k = 0; k < 2; ++k) \
;         acc[ai][bj][m][n] = __builtin_amdgcn_mfma_f32_16x16x32_bf16(Bt[n][k], At[m][k], acc[ai][bj][m][n], 0, 0, 0); __builtin_amdgcn_s_setprio(0); } while (0)
; #define PG8_WAIT_V(n) asm volatile("s_waitcnt vmcnt(" #n ")" ::: "memory")
; #define PG8_WAIT_L(n) asm volatile("s_waitcnt lgkmcnt(" #n ")" ::: "memory")
; #define PG8_BAR __builtin_amdgcn_s_barrier()
; #define PG8_SCHED __builtin_amdgcn_sched_barrier(0)
; template <class Epi, class Sched>
; __device__ __forceinline__ void gemm_phase(PG8_LAS unsigned char* lds, const Gemm g, const Sched& S, const Epi& E) {
;     ...
;             PG8_STAGE(PG8_SB(0, 1), b2 + hstep, voffB);
;             PG8_WAIT_V(6); PG8_BAR; PG8_MMA(1, 1, At, B1); PG8_BAR;
;             PG8_LDB(B0, 1, 0); PG8_SCHED; PG8_LDA(At, 1, 0); PG8_STAGE(PG8_SA(0, 1), a2 + hstep, voffA);
;             PG8_WAIT_L(8); PG8_BAR; PG8_WAIT_L(0); PG8_MMA(0, 0, At, B0); PG8_BAR; PG8_SCHED;
;             PG8_LDB(B1, 1, 1); PG8_STAGE(PG8_SB(1, 0), b3, voffB);
;             PG8_BAR; PG8_WAIT_L(0); PG8_MMA(0, 1, At, B1); PG8_BAR;
;             PG8_LDA(At, 1, 1); PG8_STAGE(PG8_SA(1, 0), a3, voffA);
;             PG8_BAR; PG8_WAIT_L(0); PG8_MMA(1, 0, At, B0); PG8_BAR; PG8_SCHED;
	s_add_u32 s84, s10, 0x40000
	s_addc_u32 s85, s11, 0
	s_add_i32 s86, s86, s53
	v_lshl_add_u64 v[144:145], s[84:85], 0, v[0:1]
	s_mov_b32 m0, s86
	s_nop 0
	global_load_lds_dwordx4 v[144:145], off
	v_lshl_add_u64 v[144:145], s[84:85], 0, v[130:131]
	s_add_i32 m0, s86, 0x2000
	s_nop 0
	global_load_lds_dwordx4 v[144:145], off
	s_waitcnt vmcnt(6)
	s_setprio 1
	s_barrier
	v_mfma_f32_16x16x32_bf16 v[78:81], v[222:225], v[160:163], v[78:81]
	v_mfma_f32_16x16x32_bf16 v[74:77], v[230:233], v[160:163], v[74:77]
	v_mfma_f32_16x16x32_bf16 v[94:97], v[222:225], v[178:181], v[94:97]
	v_mfma_f32_16x16x32_bf16 v[90:93], v[230:233], v[178:181], v[90:93]
	v_mfma_f32_16x16x32_bf16 v[110:113], v[222:225], v[186:189], v[110:113]
	v_mfma_f32_16x16x32_bf16 v[106:109], v[230:233], v[186:189], v[106:109]
	v_mfma_f32_16x16x32_bf16 v[126:129], v[222:225], v[194:197], v[126:129]
	v_mfma_f32_16x16x32_bf16 v[122:125], v[230:233], v[194:197], v[122:125]
	v_mfma_f32_16x16x32_bf16 v[78:81], v[226:229], v[174:177], v[78:81]
	v_mfma_f32_16x16x32_bf16 v[74:77], v[234:237], v[174:177], v[74:77]
	v_mfma_f32_16x16x32_bf16 v[94:97], v[226:229], v[182:185], v[94:97]
	v_mfma_f32_16x16x32_bf16 v[90:93], v[234:237], v[182:185], v[90:93]
	v_mfma_f32_16x16x32_bf16 v[110:113], v[226:229], v[190:193], v[110:113]
	v_mfma_f32_16x16x32_bf16 v[106:109], v[234:237], v[190:193], v[106:109]
	v_mfma_f32_16x16x32_bf16 v[126:129], v[226:229], v[198:201], v[126:129]
	v_mfma_f32_16x16x32_bf16 v[122:125], v[234:237], v[198:201], v[122:125]
	s_setprio 0
	s_barrier
	s_add_i32 s84, 0, 0x18000
	v_add_u32_e32 v156, s84, v141
	ds_read_b128 v[144:147], v156
	ds_read_b128 v[148:151], v156 offset:1024
	ds_read_b128 v[152:155], v156 offset:2048
	ds_read_b128 v[156:159], v156 offset:3072
	s_add_u32 s50, s50, 0x40000
	s_addc_u32 s51, s51, 0
	s_mov_b32 m0, s72
	v_lshl_add_u64 v[222:223], s[50:51], 0, v[134:135]
	ds_read_b128 v[160:163], v143 offset:32768
	ds_read_b128 v[174:177], v143 offset:33792
	ds_read_b128 v[178:181], v143 offset:34816
	ds_read_b128 v[182:185], v143 offset:35840
	ds_read_b128 v[186:189], v143 offset:36864
	ds_read_b128 v[190:193], v143 offset:37888
	ds_read_b128 v[194:197], v143 offset:38912
	ds_read_b128 v[198:201], v143 offset:39936
	global_load_lds_dwordx4 v[222:223], off
	v_lshl_add_u64 v[222:223], s[50:51], 0, v[132:133]
	s_mov_b32 m0, s73
	s_nop 0
	global_load_lds_dwordx4 v[222:223], off
	s_waitcnt lgkmcnt(8)
	s_setprio 1
	s_barrier
	s_waitcnt lgkmcnt(0)
	v_mfma_f32_16x16x32_bf16 v[6:9], v[144:147], v[160:163], v[6:9]
	v_mfma_f32_16x16x32_bf16 v[2:5], v[152:155], v[160:163], v[2:5]
	v_mfma_f32_16x16x32_bf16 v[22:25], v[144:147], v[178:181], v[22:25]
	v_mfma_f32_16x16x32_bf16 v[18:21], v[152:155], v[178:181], v[18:21]
	v_mfma_f32_16x16x32_bf16 v[38:41], v[144:147], v[186:189], v[38:41]
	v_mfma_f32_16x16x32_bf16 v[34:37], v[152:155], v[186:189], v[34:37]
	v_mfma_f32_16x16x32_bf16 v[54:57], v[144:147], v[194:197], v[54:57]
	v_mfma_f32_16x16x32_bf16 v[50:53], v[152:155], v[194:197], v[50:53]
	v_mfma_f32_16x16x32_bf16 v[6:9], v[148:151], v[174:177], v[6:9]
	v_mfma_f32_16x16x32_bf16 v[2:5], v[156:159], v[174:177], v[2:5]
	v_mfma_f32_16x16x32_bf16 v[22:25], v[148:151], v[182:185], v[22:25]
	v_mfma_f32_16x16x32_bf16 v[18:21], v[156:159], v[182:185], v[18:21]
	v_mfma_f32_16x16x32_bf16 v[38:41], v[148:151], v[190:193], v[38:41]
	v_mfma_f32_16x16x32_bf16 v[34:37], v[156:159], v[190:193], v[34:37]
	v_mfma_f32_16x16x32_bf16 v[54:57], v[148:151], v[198:201], v[54:57]
	v_mfma_f32_16x16x32_bf16 v[50:53], v[156:159], v[198:201], v[50:53]
	s_setprio 0
	s_barrier
	s_add_i32 s50, 0, 0x1c000
	s_add_i32 s51, s84, s53
	v_add_u32_e32 v221, s50, v141
	v_lshl_add_u64 v[202:203], v[202:203], 0, s[8:9]
	s_mov_b32 m0, s51
	ds_read_b128 v[222:225], v221
	ds_read_b128 v[226:229], v221 offset:1024
	ds_read_b128 v[230:233], v221 offset:2048
	ds_read_b128 v[234:237], v221 offset:3072
	global_load_lds_dwordx4 v[202:203], off
	v_lshl_add_u64 v[202:203], v[238:239], 0, s[8:9]
	s_add_i32 m0, s51, 0x2000
	s_nop 0
	global_load_lds_dwordx4 v[202:203], off
	s_setprio 1
	s_barrier
	s_waitcnt lgkmcnt(0)
	v_mfma_f32_16x16x32_bf16 v[14:17], v[222:225], v[160:163], v[14:17]
	v_mfma_f32_16x16x32_bf16 v[10:13], v[230:233], v[160:163], v[10:13]
	v_mfma_f32_16x16x32_bf16 v[30:33], v[222:225], v[178:181], v[30:33]
	v_mfma_f32_16x16x32_bf16 v[26:29], v[230:233], v[178:181], v[26:29]
	v_mfma_f32_16x16x32_bf16 v[46:49], v[222:225], v[186:189], v[46:49]
	v_mfma_f32_16x16x32_bf16 v[42:45], v[230:233], v[186:189], v[42:45]
	v_mfma_f32_16x16x32_bf16 v[62:65], v[222:225], v[194:197], v[62:65]
	v_mfma_f32_16x16x32_bf16 v[58:61], v[230:233], v[194:197], v[58:61]
	v_mfma_f32_16x16x32_bf16 v[14:17], v[226:229], v[174:177], v[14:17]
	v_mfma_f32_16x16x32_bf16 v[10:13], v[234:237], v[174:177], v[10:13]
	v_mfma_f32_16x16x32_bf16 v[30:33], v[226:229], v[182:185], v[30:33]
	v_mfma_f32_16x16x32_bf16 v[26:29], v[234:237], v[182:185], v[26:29]
	v_mfma_f32_16x16x32_bf16 v[46:49], v[226:229], v[190:193], v[46:49]
	v_mfma_f32_16x16x32_bf16 v[42:45], v[234:237], v[190:193], v[42:45]
	v_mfma_f32_16x16x32_bf16 v[62:65], v[226:229], v[198:201], v[62:65]
	v_mfma_f32_16x16x32_bf16 v[58:61], v[234:237], v[198:201], v[58:61]
	s_setprio 0
	s_barrier
	s_mov_b32 m0, s74
	v_lshl_add_u64 v[202:203], v[240:241], 0, s[8:9]
	ds_read_b128 v[160:163], v143 offset:49152
	ds_read_b128 v[174:177], v143 offset:50176
	ds_read_b128 v[178:181], v143 offset:51200
	ds_read_b128 v[182:185], v143 offset:52224
	ds_read_b128 v[186:189], v143 offset:53248
	ds_read_b128 v[190:193], v143 offset:54272
	ds_read_b128 v[194:197], v143 offset:55296
	ds_read_b128 v[198:201], v143 offset:56320
	global_load_lds_dwordx4 v[202:203], off
	v_lshl_add_u64 v[202:203], v[242:243], 0, s[8:9]
	s_mov_b32 m0, s75
	s_nop 0
	global_load_lds_dwordx4 v[202:203], off
	s_setprio 1
	s_barrier
; #define PG8_STAGE(bufoff, gbase, voff) do { _Pragma("unroll") for (int _i = 0; _i < 2; ++_i) \
;         __builtin_amdgcn_global_load_lds((const unsigned*)((const char*)(gbase) + (voff)[_i]), (PG8_LAS unsigned*)(lds + (bufoff) + ldsw + _i * 8192), 16, 0, 0); } while (0)
; #define PG8_MMA(ai, bj, At, Bt) do { __builtin_amdgcn_s_setprio(1); _Pragma("unroll") for (int m = 0; m < 4; ++m) _Pragma("unroll") for (int n = 0; n < 2; ++n) _Pragma("unroll") for (int k = 0; k < 2; ++k) \
;         acc[ai][bj][m][n] = __builtin_amdgcn_mfma_f32_16x16x32_bf16(Bt[n][k], At[m][k], acc[ai][bj][m][n], 0, 0, 0); __builtin_amdgcn_s_setprio(0); } while (0)
; #define PG8_WAIT_V(n) asm volatile("s_waitcnt vmcnt(" #n ")" ::: "memory")
; #define PG8_WAIT_L(n) asm volatile("s_waitcnt lgkmcnt(" #n ")" ::: "memory")
; #define PG8_BAR __builtin_amdgcn_s_barrier()
; #define PG8_SCHED __builtin_amdgcn_sched_barrier(0)
; template <class Epi, class Sched>
; __device__ __forceinline__ void gemm_phase(PG8_LAS unsigned char* lds, const Gemm g, const Sched& S, const Epi& E) {
;     ...
;             PG8_BAR; PG8_WAIT_L(0); PG8_MMA(1, 0, At, B0); PG8_BAR; PG8_SCHED;
;             PG8_STAGE(PG8_SB(1, 1), b3 + hstep, voffB);
;             PG8_WAIT_V(6); PG8_BAR; PG8_MMA(1, 1, At, B1); PG8_BAR;
;     __device__ __forceinline__ void operator()(const f32x4 (&acc)[2][2][4][2], const Unit& u, int wr, int wc, int fr, int fq) const {
;         const int row0 = u.pm * 256 + wr * 64 + fr, col0 = u.pn * 256 + wc * 32 + 8 * fq;
; #pragma unroll
;         for (int ai = 0; ai < 2; ++ai)
; #pragma unroll
;             for (int m = 0; m < 4; ++m) { const size_t ro = (size_t)(row0 + ai * 128 + m * 16) * 1024 + col0;
; #pragma unroll
;                 for (int bj = 0; bj < 2; ++bj) { *(f32x4*)(XO + ro + bj * 128) = acc[ai][bj][m][0]; *(f32x4*)(XO + ro + bj * 128 + 4) = acc[ai][bj][m][1]; } }
;     }
	s_waitcnt lgkmcnt(0)
	v_mfma_f32_16x16x32_bf16 v[66:69], v[144:147], v[160:163], v[66:69]
	v_mfma_f32_16x16x32_bf16 v[70:73], v[152:155], v[160:163], v[70:73]
	v_mfma_f32_16x16x32_bf16 v[82:85], v[144:147], v[178:181], v[82:85]
	v_mfma_f32_16x16x32_bf16 v[86:89], v[152:155], v[178:181], v[86:89]
	v_mfma_f32_16x16x32_bf16 v[98:101], v[144:147], v[186:189], v[98:101]
	v_mfma_f32_16x16x32_bf16 v[102:105], v[152:155], v[186:189], v[102:105]
	v_mfma_f32_16x16x32_bf16 v[114:117], v[144:147], v[194:197], v[114:117]
	v_mfma_f32_16x16x32_bf16 v[118:121], v[152:155], v[194:197], v[118:121]
	v_mfma_f32_16x16x32_bf16 v[66:69], v[148:151], v[174:177], v[66:69]
	v_mfma_f32_16x16x32_bf16 v[70:73], v[156:159], v[174:177], v[70:73]
	v_mfma_f32_16x16x32_bf16 v[82:85], v[148:151], v[182:185], v[82:85]
	v_mfma_f32_16x16x32_bf16 v[86:89], v[156:159], v[182:185], v[86:89]
	v_mfma_f32_16x16x32_bf16 v[98:101], v[148:151], v[190:193], v[98:101]
	v_mfma_f32_16x16x32_bf16 v[102:105], v[156:159], v[190:193], v[102:105]
	v_mfma_f32_16x16x32_bf16 v[114:117], v[148:151], v[198:201], v[114:117]
	v_mfma_f32_16x16x32_bf16 v[118:121], v[156:159], v[198:201], v[118:121]
	s_setprio 0
	s_barrier
	s_add_u32 s10, s10, 0x40080
	s_addc_u32 s11, s11, 0
	s_add_i32 s50, s50, s53
	v_lshl_add_u64 v[144:145], s[10:11], 0, v[0:1]
	s_mov_b32 m0, s50
	s_nop 0
	global_load_lds_dwordx4 v[144:145], off
	v_lshl_add_u64 v[144:145], s[10:11], 0, v[130:131]
	s_add_i32 m0, s50, 0x2000
	s_nop 0
	global_load_lds_dwordx4 v[144:145], off
	s_waitcnt vmcnt(6)
	s_setprio 1
	s_barrier
	v_mfma_f32_16x16x32_bf16 v[78:81], v[222:225], v[160:163], v[78:81]
	v_mfma_f32_16x16x32_bf16 v[74:77], v[230:233], v[160:163], v[74:77]
	v_mfma_f32_16x16x32_bf16 v[94:97], v[222:225], v[178:181], v[94:97]
	v_mfma_f32_16x16x32_bf16 v[90:93], v[230:233], v[178:181], v[90:93]
	v_mfma_f32_16x16x32_bf16 v[110:113], v[222:225], v[186:189], v[110:113]
	v_mfma_f32_16x16x32_bf16 v[106:109], v[230:233], v[186:189], v[106:109]
	v_mfma_f32_16x16x32_bf16 v[126:129], v[222:225], v[194:197], v[126:129]
	v_mfma_f32_16x16x32_bf16 v[122:125], v[230:233], v[194:197], v[122:125]
	v_mfma_f32_16x16x32_bf16 v[78:81], v[226:229], v[174:177], v[78:81]
	v_mfma_f32_16x16x32_bf16 v[74:77], v[234:237], v[174:177], v[74:77]
	v_mfma_f32_16x16x32_bf16 v[94:97], v[226:229], v[182:185], v[94:97]
	v_mfma_f32_16x16x32_bf16 v[90:93], v[234:237], v[182:185], v[90:93]
	v_mfma_f32_16x16x32_bf16 v[110:113], v[226:229], v[190:193], v[110:113]
	v_mfma_f32_16x16x32_bf16 v[106:109], v[234:237], v[190:193], v[106:109]
	v_mfma_f32_16x16x32_bf16 v[126:129], v[226:229], v[198:201], v[126:129]
	v_mfma_f32_16x16x32_bf16 v[122:125], v[234:237], v[198:201], v[122:125]
	s_setprio 0
	s_add_i32 s83, s83, 2
	s_add_u32 vcc_lo, vcc_lo, 0x100
	s_addc_u32 vcc_hi, vcc_hi, 0
	s_add_u32 s81, s81, 0x100
	s_addc_u32 s82, s82, 0
	s_cmp_gt_u32 s83, 13
	s_barrier
	s_cbranch_scc0 .LBB0_548
	v_lshl_add_u32 v144, s78, 8, v140
	v_lshl_or_b32 v146, s77, 8, v142
	v_ashrrev_i32_e32 v145, 31, v144
	v_ashrrev_i32_e32 v147, 31, v146
	v_lshlrev_b64 v[148:149], 12, v[144:145]
	v_lshl_add_u64 v[148:149], s[62:63], 0, v[148:149]
	v_lshlrev_b64 v[146:147], 2, v[146:147]
	v_lshl_add_u64 v[148:149], v[148:149], 0, v[146:147]
	global_store_dwordx4 v[148:149], v[6:9], off
	global_store_dwordx4 v[148:149], v[2:5], off offset:16
	global_store_dwordx4 v[148:149], v[14:17], off offset:512
	global_store_dwordx4 v[148:149], v[10:13], off offset:528
	v_or_b32_e32 v2, 16, v144
	v_ashrrev_i32_e32 v3, 31, v2
	v_lshlrev_b64 v[2:3], 12, v[2:3]
	v_lshl_add_u64 v[2:3], s[62:63], 0, v[2:3]
	v_lshl_add_u64 v[2:3], v[2:3], 0, v[146:147]
	global_store_dwordx4 v[2:3], v[22:25], off
	global_store_dwordx4 v[2:3], v[18:21], off offset:16
	global_store_dwordx4 v[2:3], v[30:33], off offset:512
	global_store_dwordx4 v[2:3], v[26:29], off offset:528
	v_or_b32_e32 v2, 32, v144
	v_ashrrev_i32_e32 v3, 31, v2
	v_lshlrev_b64 v[2:3], 12, v[2:3]
	v_lshl_add_u64 v[2:3], s[62:63], 0, v[2:3]
	v_lshl_add_u64 v[2:3], v[2:3], 0, v[146:147]
	global_store_dwordx4 v[2:3], v[38:41], off
	global_store_dwordx4 v[2:3], v[34:37], off offset:16
	global_store_dwordx4 v[2:3], v[46:49], off offset:512
	global_store_dwordx4 v[2:3], v[42:45], off offset:528
	v_or_b32_e32 v2, 48, v144
	v_ashrrev_i32_e32 v3, 31, v2
	v_lshlrev_b64 v[2:3], 12, v[2:3]
	v_lshl_add_u64 v[2:3], s[62:63], 0, v[2:3]
	v_lshl_add_u64 v[2:3], v[2:3], 0, v[146:147]
	v_add_co_u32_e32 v4, vcc, s54, v148
	global_store_dwordx4 v[2:3], v[54:57], off
	global_store_dwordx4 v[2:3], v[50:53], off offset:16
	global_store_dwordx4 v[2:3], v[62:65], off offset:512
	global_store_dwordx4 v[2:3], v[58:61], off offset:528
	v_lshl_add_u64 v[2:3], v[148:149], 0, s[42:43]
	v_addc_co_u32_e32 v5, vcc, 0, v149, vcc
	s_mov_b64 s[10:11], 0x90000
	global_store_dwordx4 v[4:5], v[66:69], off
	global_store_dwordx4 v[2:3], v[70:73], off offset:16
	global_store_dwordx4 v[2:3], v[78:81], off offset:512
	global_store_dwordx4 v[2:3], v[74:77], off offset:528
	v_lshl_add_u64 v[2:3], v[148:149], 0, s[10:11]
	s_mov_b32 s10, 0x90000
	v_add_co_u32_e32 v4, vcc, s10, v148
	s_mov_b64 s[10:11], 0xa0000
	s_nop 0
	v_addc_co_u32_e32 v5, vcc, 0, v149, vcc
	global_store_dwordx4 v[4:5], v[82:85], off
	global_store_dwordx4 v[2:3], v[86:89], off offset:16
	global_store_dwordx4 v[2:3], v[94:97], off offset:512
	global_store_dwordx4 v[2:3], v[90:93], off offset:528
	v_lshl_add_u64 v[2:3], v[148:149], 0, s[10:11]
	s_mov_b32 s10, 0xa0000
	v_add_co_u32_e32 v4, vcc, s10, v148
	s_mov_b64 s[10:11], 0xb0000
	s_nop 0
	v_addc_co_u32_e32 v5, vcc, 0, v149, vcc
	global_store_dwordx4 v[4:5], v[98:101], off
	global_store_dwordx4 v[2:3], v[102:105], off offset:16
	global_store_dwordx4 v[2:3], v[110:113], off offset:512
	global_store_dwordx4 v[2:3], v[106:109], off offset:528
	v_add_co_u32_e32 v4, vcc, 0xb0000, v148
	v_lshl_add_u64 v[2:3], v[148:149], 0, s[10:11]
	s_nop 0
	v_addc_co_u32_e32 v5, vcc, 0, v149, vcc
	s_andn2_b64 vcc, exec, s[36:37]
	s_mov_b64 s[10:11], -1
	global_store_dwordx4 v[4:5], v[114:117], off
	global_store_dwordx4 v[2:3], v[118:121], off offset:16
	global_store_dwordx4 v[2:3], v[126:129], off offset:512
	global_store_dwordx4 v[2:3], v[122:125], off offset:528
	s_cbranch_vccnz .LBB0_540
;     __device__ __forceinline__ void init(f32x4 (&acc)[2][2][4][2], const Unit& u, int wr, int wc, int fr, int fq) const {
;         const int row0 = u.pm * 256 + wr * 64 + fr, col0 = u.pn * 256 + wc * 32 + 8 * fq;
; #pragma unroll
;         for (int ai = 0; ai < 2; ++ai)
; #pragma unroll
;             for (int m = 0; m < 4; ++m) { const size_t ro = (size_t)(row0 + ai * 128 + m * 16) * 1024 + col0;
; #pragma unroll
;                 for (int bj = 0; bj < 2; ++bj) { acc[ai][bj][m][0] = *(const f32x4*)(XI + ro + bj * 128); acc[ai][bj][m][1] = *(const f32x4*)(XI + ro + bj * 128 + 4); } }
;     }
	v_lshl_add_u32 v50, s20, 8, v140
	v_lshl_or_b32 v2, s18, 8, v142
	v_ashrrev_i32_e32 v51, 31, v50
	v_ashrrev_i32_e32 v3, 31, v2
	v_lshlrev_b64 v[4:5], 12, v[50:51]
	v_lshl_add_u64 v[4:5], s[6:7], 0, v[4:5]
	v_lshlrev_b64 v[52:53], 2, v[2:3]
	v_lshl_add_u64 v[114:115], v[4:5], 0, v[52:53]
	v_add_co_u32_e32 v66, vcc, s54, v114
	s_mov_b64 s[10:11], 0x90000
	s_nop 0
	v_addc_co_u32_e32 v67, vcc, 0, v115, vcc
	v_lshl_add_u64 v[94:95], v[114:115], 0, s[10:11]
	s_mov_b32 s10, 0x90000
	v_add_co_u32_e32 v82, vcc, s10, v114
	s_mov_b64 s[10:11], 0xa0000
	v_or_b32_e32 v18, 16, v50
	v_or_b32_e32 v34, 32, v50
	v_or_b32_e32 v50, 48, v50
	v_addc_co_u32_e32 v83, vcc, 0, v115, vcc
	v_lshl_add_u64 v[110:111], v[114:115], 0, s[10:11]
	s_mov_b32 s10, 0xa0000
	v_ashrrev_i32_e32 v19, 31, v18
	v_ashrrev_i32_e32 v35, 31, v34
	v_ashrrev_i32_e32 v51, 31, v50
	v_add_co_u32_e32 v98, vcc, s10, v114
	s_mov_b64 s[10:11], 0xb0000
	v_lshlrev_b64 v[18:19], 12, v[18:19]
	v_lshlrev_b64 v[34:35], 12, v[34:35]
	v_lshlrev_b64 v[50:51], 12, v[50:51]
	v_addc_co_u32_e32 v99, vcc, 0, v115, vcc
	v_lshl_add_u64 v[126:127], v[114:115], 0, s[10:11]
	s_mov_b32 s10, 0xb0000
	global_load_dwordx4 v[2:5], v[114:115], off offset:16
	global_load_dwordx4 v[6:9], v[114:115], off
	global_load_dwordx4 v[10:13], v[114:115], off offset:528
	global_load_dwordx4 v[14:17], v[114:115], off offset:512
	v_lshl_add_u64 v[18:19], s[6:7], 0, v[18:19]
	v_lshl_add_u64 v[34:35], s[6:7], 0, v[34:35]
	v_lshl_add_u64 v[50:51], s[6:7], 0, v[50:51]
	v_lshl_add_u64 v[78:79], v[114:115], 0, s[42:43]
	v_add_co_u32_e32 v114, vcc, s10, v114
	v_lshl_add_u64 v[30:31], v[18:19], 0, v[52:53]
	v_lshl_add_u64 v[46:47], v[34:35], 0, v[52:53]
	v_lshl_add_u64 v[62:63], v[50:51], 0, v[52:53]
	v_addc_co_u32_e32 v115, vcc, 0, v115, vcc
	global_load_dwordx4 v[18:21], v[30:31], off offset:16
	global_load_dwordx4 v[22:25], v[30:31], off
	global_load_dwordx4 v[26:29], v[30:31], off offset:528
	s_nop 0
	global_load_dwordx4 v[30:33], v[30:31], off offset:512
	s_nop 0
	global_load_dwordx4 v[34:37], v[46:47], off offset:16
	global_load_dwordx4 v[38:41], v[46:47], off
	global_load_dwordx4 v[42:45], v[46:47], off offset:528
	s_nop 0
	global_load_dwordx4 v[46:49], v[46:47], off offset:512
	s_nop 0
	global_load_dwordx4 v[50:53], v[62:63], off offset:16
	global_load_dwordx4 v[54:57], v[62:63], off
	global_load_dwordx4 v[58:61], v[62:63], off offset:528
	s_nop 0
	global_load_dwordx4 v[62:65], v[62:63], off offset:512
	s_nop 0
	global_load_dwordx4 v[66:69], v[66:67], off
	s_nop 0
	global_load_dwordx4 v[74:77], v[78:79], off offset:528
	global_load_dwordx4 v[70:73], v[78:79], off offset:16
	s_nop 0
	global_load_dwordx4 v[78:81], v[78:79], off offset:512
	s_nop 0
	global_load_dwordx4 v[82:85], v[82:83], off
	s_nop 0
	global_load_dwordx4 v[90:93], v[94:95], off offset:528
	global_load_dwordx4 v[86:89], v[94:95], off offset:16
	s_nop 0
	global_load_dwordx4 v[94:97], v[94:95], off offset:512
	s_nop 0
	global_load_dwordx4 v[98:101], v[98:99], off
	s_nop 0
	global_load_dwordx4 v[106:109], v[110:111], off offset:528
	global_load_dwordx4 v[102:105], v[110:111], off offset:16
	s_nop 0
	global_load_dwordx4 v[110:113], v[110:111], off offset:512
	s_nop 0
	global_load_dwordx4 v[114:117], v[114:115], off
	s_nop 0
	global_load_dwordx4 v[122:125], v[126:127], off offset:528
	global_load_dwordx4 v[118:121], v[126:127], off offset:16
	s_nop 0
	global_load_dwordx4 v[126:129], v[126:127], off offset:512
	s_mov_b64 s[10:11], 0
	s_branch .LBB0_540
